# compress: row loads issued only by lanes that own a valid block (exec mask = vcol); idle block slots and block-less waves no longer generate memory requests
# speedup vs baseline: 1.0105x; 1.0048x over previous
.LBB0_556:
	s_cmp_lg_u32 s79, 2
	s_cbranch_scc1 .LBB0_616
	v_readlane_b32 s0, v254, 7
	v_readlane_b32 s1, v254, 8
	v_readlane_b32 s1, v254, 32
	s_cmp_ge_i32 s1, s0
	s_cselect_b64 s[2:3], -1, 0
	s_and_b64 s[0:1], s[2:3], s[34:35]
	s_andn2_b64 vcc, exec, s[0:1]
	s_cbranch_vccnz .LBB0_570
	v_readlane_b32 s4, v254, 9
	v_readlane_b32 s5, v254, 10
	s_waitcnt vmcnt(0)
	v_mov_b32_e32 v4, v0
	v_readlane_b32 s0, v254, 6
	v_readlane_b32 s6, v254, 11
	v_readlane_b32 s7, v254, 12
	s_mov_b64 s[8:9], s[4:5]
	v_readlane_b32 s1, v254, 5
	v_readlane_b32 s10, v254, 17
	v_readlane_b32 s4, v254, 4
	s_abs_i32 s1, s4
	v_cvt_f32_u32_e32 v1, s1
	s_sub_i32 s11, 0, s1
	s_add_i32 s5, s4, 0x10ff
	s_xor_b32 s4, s5, s4
	v_rcp_iflag_f32_e32 v1, v1
	s_abs_i32 s5, s5
	s_ashr_i32 s4, s4, 31
	v_mul_f32_e32 v1, 0x4f7ffffe, v1
	v_cvt_u32_f32_e32 v1, v1
	s_nop 0
	v_readfirstlane_b32 s12, v1
	s_mul_i32 s11, s11, s12
	s_mul_hi_u32 s11, s12, s11
	s_add_i32 s12, s12, s11
	s_mul_hi_u32 s11, s5, s12
	s_mul_i32 s12, s11, s1
	s_sub_i32 s5, s5, s12
	s_add_i32 s12, s11, 1
	s_sub_i32 s13, s5, s1
	s_cmp_ge_u32 s5, s1
	s_cselect_b32 s11, s12, s11
	s_cselect_b32 s5, s13, s5
	s_add_i32 s12, s11, 1
	s_cmp_ge_u32 s5, s1
	s_cselect_b32 s1, s12, s11
	s_xor_b32 s1, s1, s4
	s_sub_i32 s1, s1, s4
	s_cmp_gt_i32 s1, 32
	s_cbranch_scc1 .LBB0_570
	v_mov_b32_e32 v1, s1
	v_mul_lo_u32 v1, s0, v1
	s_movk_i32 s0, 0x1101
	v_sub_u32_e32 v2, 0x1100, v1
	v_cmp_gt_i32_e32 vcc, s0, v1
	s_add_i32 s0, s1, 7
	v_min_i32_e32 v2, s1, v2
	s_ashr_i32 s1, s0, 31
	s_lshr_b32 s1, s1, 29
	s_add_i32 s0, s0, s1
	s_ashr_i32 s0, s0, 3
	v_mov_b32_e32 v5, s10
	v_cndmask_b32_e32 v2, 0, v2, vcc
	v_mul_lo_u32 v5, s0, v5
	v_sub_u32_e32 v2, v2, v5
	v_cmp_lt_i32_e32 vcc, -1, v2
	v_min_i32_e32 v2, s0, v2
	s_waitcnt vmcnt(0)
	v_bfe_u32 v6, v4, 2, 2
	v_cmp_gt_i32_e64 s[0:1], v2, v6
	s_and_b64 s[4:5], vcc, s[0:1]
	s_mov_b64 s[100:101], s[4:5]
	v_cndmask_b32_e64 v2, 0, v6, s[4:5]
	v_add3_u32 v1, v5, v1, v2
	v_min_i32_e32 v180, 0x10ff, v1
	v_ashrrev_i32_e32 v177, 7, v180
	v_and_b32_e32 v1, 0x7f, v180
	v_cmp_lt_i32_e32 vcc, 1, v177
	s_and_saveexec_b64 s[0:1], vcc
	s_xor_b64 s[0:1], exec, s[0:1]
	s_cbranch_execz .LBB0_561
	v_readlane_b32 s14, v254, 0
	v_readlane_b32 s15, v254, 1
	s_mov_b64 s[12:13], s[14:15]
	s_load_dwordx2 s[12:13], s[12:13], 0x10
	s_load_dwordx2 s[14:15], s[14:15], 0x28
	v_lshrrev_b32_e32 v2, 1, v1
	v_lshl_or_b32 v2, v177, 6, v2
	v_add_u32_e32 v2, 0xffffff80, v2
	s_waitcnt lgkmcnt(0)
	v_lshl_add_u64 v[6:7], v[2:3], 2, s[14:15]
	global_load_dword v6, v[6:7], off
	v_lshlrev_b32_e32 v2, 18, v180
	v_and_b32_e32 v2, 0x40000, v2
	s_waitcnt vmcnt(0)
	v_ashrrev_i32_e32 v7, 31, v6
	v_lshlrev_b64 v[6:7], 19, v[6:7]
	v_lshl_add_u64 v[6:7], s[12:13], 0, v[6:7]
	v_lshl_add_u64 v[68:69], v[6:7], 0, v[2:3]

.LBB0_564:
	s_mov_b32 s24, 0xffff4b70
	s_mov_b32 s25, -1
	v_lshl_add_u64 v[136:137], v[186:187], 0, s[24:25]
	s_mov_b32 s24, 0xffff5000
	s_add_i32 s23, 0, 0x10000
	v_add_co_u32_e32 v144, vcc, s24, v186
	s_mov_b32 s24, 0xffff4bf0
	v_lshl_add_u64 v[192:193], s[0:1], 0, v[188:189]
	s_add_i32 s21, s23, s12
	s_mov_b32 s25, -1
	s_waitcnt vmcnt(12)
	s_barrier
	v_lshl_add_u64 v[132:133], v[192:193], 0, s[84:85]
	s_mov_b32 m0, s21
	v_lshl_add_u64 v[194:195], s[0:1], 0, v[190:191]
	s_add_i32 s20, s21, 0x2000
	s_add_i32 s22, 0, 0x14000
	v_lshl_add_u64 v[146:147], v[186:187], 0, s[24:25]
	s_mov_b32 s24, 0xffff4f70
	global_load_lds_dwordx4 v[132:133], off
	v_lshl_add_u64 v[132:133], v[194:195], 0, s[84:85]
	s_mov_b32 m0, s20
	s_add_i32 s18, s22, s12
	s_mov_b32 s25, -1
	global_load_lds_dwordx4 v[132:133], off
	v_lshl_add_u64 v[132:133], v[192:193], 0, s[86:87]
	s_mov_b32 m0, s18
	s_add_i32 s19, s18, 0x2000
	v_lshl_add_u64 v[152:153], v[186:187], 0, s[24:25]
	s_mov_b32 s24, 0xffff4ff0
	global_load_lds_dwordx4 v[132:133], off
	v_lshl_add_u64 v[132:133], v[194:195], 0, s[86:87]
	s_mov_b32 m0, s19
	s_mov_b32 s25, -1
	global_load_lds_dwordx4 v[132:133], off
	v_addc_co_u32_e32 v145, vcc, -1, v187, vcc
	v_lshl_add_u64 v[154:155], v[186:187], 0, s[24:25]
	s_mov_b64 exec, s[100:101]
	global_load_dwordx4 v[132:135], v[144:145], off offset:-1168
	s_nop 0
	global_load_dwordx4 v[136:139], v[136:137], off offset:16
	s_nop 0
	global_load_dwordx4 v[148:151], v[144:145], off offset:-1040
	global_load_dwordx4 v[140:143], v[144:145], off offset:-144
	global_load_dwordx4 v[160:163], v[146:147], off offset:16
	s_nop 0
	global_load_dwordx4 v[144:147], v[144:145], off offset:-16
	s_nop 0
	global_load_dwordx4 v[156:159], v[152:153], off offset:16
	s_nop 0
	global_load_dwordx4 v[152:155], v[154:155], off offset:16
	s_mov_b64 exec, -1
	v_add_u32_e32 v179, 0, v181
	v_cvt_pk_bf16_f32 v60, v60, v61
	v_cvt_pk_bf16_f32 v61, v62, v63
	v_cvt_pk_bf16_f32 v62, v44, v45
	v_cvt_pk_bf16_f32 v63, v46, v47
	v_cvt_pk_bf16_f32 v44, v64, v65
	v_cvt_pk_bf16_f32 v45, v66, v67
	v_cvt_pk_bf16_f32 v46, v56, v57
	v_cvt_pk_bf16_f32 v47, v58, v59
	v_cvt_pk_bf16_f32 v48, v48, v49
	v_cvt_pk_bf16_f32 v49, v50, v51
	v_cvt_pk_bf16_f32 v50, v52, v53
	v_cvt_pk_bf16_f32 v51, v54, v55
	v_cvt_pk_bf16_f32 v40, v40, v41
	v_cvt_pk_bf16_f32 v41, v42, v43
	v_cvt_pk_bf16_f32 v42, v36, v37
	v_cvt_pk_bf16_f32 v43, v38, v39
	ds_read_b128 v[36:39], v179
	ds_read_b128 v[52:55], v179 offset:2048
	s_waitcnt lgkmcnt(0)
	v_mfma_f32_16x16x32_bf16 v[36:39], v[36:39], v[60:63], v[100:103]
	s_nop 2
	ds_read_b128 v[100:103], v179 offset:8192
	ds_read_b128 v[56:59], v179 offset:4096
	ds_read_b128 v[64:67], v179 offset:6144
	v_mfma_f32_16x16x32_bf16 v[52:55], v[52:55], v[60:63], v[104:107]
	s_nop 2
	ds_read_b128 v[104:107], v179 offset:10240
	s_waitcnt lgkmcnt(0)
	v_mfma_f32_16x16x32_bf16 v[116:119], v[100:103], v[60:63], v[116:119]
	ds_read_b128 v[100:103], v179 offset:12288
	v_mfma_f32_16x16x32_bf16 v[120:123], v[104:107], v[60:63], v[120:123]
	ds_read_b128 v[104:107], v179 offset:14336
	v_mfma_f32_16x16x32_bf16 v[56:59], v[56:59], v[60:63], v[108:111]
	v_mfma_f32_16x16x32_bf16 v[64:67], v[64:67], v[60:63], v[112:115]
	s_waitcnt lgkmcnt(0)
	v_mfma_f32_16x16x32_bf16 v[124:127], v[100:103], v[60:63], v[124:127]
	v_mfma_f32_16x16x32_bf16 v[60:63], v[104:107], v[60:63], v[128:131]
	ds_read_b128 v[100:103], v179 offset:1024
	s_waitcnt lgkmcnt(0)
	v_mfma_f32_16x16x32_bf16 v[100:103], v[100:103], v[44:47], v[36:39]
	s_nop 2
	ds_read_b128 v[36:39], v179 offset:3072
	s_waitcnt lgkmcnt(0)
	v_mfma_f32_16x16x32_bf16 v[104:107], v[36:39], v[44:47], v[52:55]
	ds_read_b128 v[36:39], v179 offset:5120
	s_waitcnt lgkmcnt(0)
	v_mfma_f32_16x16x32_bf16 v[108:111], v[36:39], v[44:47], v[56:59]
	ds_read_b128 v[36:39], v179 offset:7168
	s_waitcnt lgkmcnt(0)
	v_mfma_f32_16x16x32_bf16 v[112:115], v[36:39], v[44:47], v[64:67]
	ds_read_b128 v[36:39], v179 offset:9216
	s_waitcnt lgkmcnt(0)
	v_mfma_f32_16x16x32_bf16 v[116:119], v[36:39], v[44:47], v[116:119]
	ds_read_b128 v[36:39], v179 offset:11264
	s_waitcnt lgkmcnt(0)
	v_mfma_f32_16x16x32_bf16 v[120:123], v[36:39], v[44:47], v[120:123]
	ds_read_b128 v[36:39], v179 offset:13312
	s_waitcnt lgkmcnt(0)
	v_mfma_f32_16x16x32_bf16 v[124:127], v[36:39], v[44:47], v[124:127]
	ds_read_b128 v[36:39], v179 offset:15360
	s_waitcnt lgkmcnt(0)
	v_mfma_f32_16x16x32_bf16 v[128:131], v[36:39], v[44:47], v[60:63]
	s_nop 2
	ds_read_b128 v[60:63], v179 offset:24576
	ds_read_b128 v[64:67], v179 offset:26624
	ds_read_b128 v[36:39], v179 offset:16384
	ds_read_b128 v[44:47], v179 offset:18432
	ds_read_b128 v[52:55], v179 offset:20480
	ds_read_b128 v[56:59], v179 offset:22528
	s_waitcnt lgkmcnt(0)
	v_mfma_f32_16x16x32_bf16 v[64:67], v[64:67], v[48:51], v[76:79]
	s_nop 2
	ds_read_b128 v[76:79], v179 offset:28672
	v_mfma_f32_16x16x32_bf16 v[44:47], v[44:47], v[48:51], v[92:95]
	s_waitcnt lgkmcnt(0)
	v_mfma_f32_16x16x32_bf16 v[92:95], v[76:79], v[48:51], v[72:75]
	s_nop 2
	ds_read_b128 v[72:75], v179 offset:30720
	v_mfma_f32_16x16x32_bf16 v[36:39], v[36:39], v[48:51], v[96:99]
	v_mfma_f32_16x16x32_bf16 v[52:55], v[52:55], v[48:51], v[88:91]
	v_mfma_f32_16x16x32_bf16 v[56:59], v[56:59], v[48:51], v[84:87]
	v_mfma_f32_16x16x32_bf16 v[60:63], v[60:63], v[48:51], v[80:83]
	s_waitcnt lgkmcnt(0)
	v_mfma_f32_16x16x32_bf16 v[48:51], v[72:75], v[48:51], v[68:71]
	s_nop 2
	ds_read_b128 v[68:71], v179 offset:17408
	s_waitcnt lgkmcnt(0)
	v_mfma_f32_16x16x32_bf16 v[68:71], v[68:71], v[40:43], v[36:39]
	s_nop 2
	ds_read_b128 v[36:39], v179 offset:19456
	s_waitcnt lgkmcnt(0)
	v_mfma_f32_16x16x32_bf16 v[72:75], v[36:39], v[40:43], v[44:47]
	ds_read_b128 v[36:39], v179 offset:21504
	s_waitcnt lgkmcnt(0)
	v_mfma_f32_16x16x32_bf16 v[76:79], v[36:39], v[40:43], v[52:55]
	ds_read_b128 v[36:39], v179 offset:23552
	s_waitcnt lgkmcnt(0)
	v_mfma_f32_16x16x32_bf16 v[80:83], v[36:39], v[40:43], v[56:59]
	ds_read_b128 v[36:39], v179 offset:25600
	s_waitcnt lgkmcnt(0)
	v_mfma_f32_16x16x32_bf16 v[84:87], v[36:39], v[40:43], v[60:63]
	ds_read_b128 v[36:39], v179 offset:27648
	s_waitcnt lgkmcnt(0)
	v_mfma_f32_16x16x32_bf16 v[88:91], v[36:39], v[40:43], v[64:67]
	ds_read_b128 v[36:39], v179 offset:29696
	s_waitcnt lgkmcnt(0)
	v_mfma_f32_16x16x32_bf16 v[92:95], v[36:39], v[40:43], v[92:95]
	ds_read_b128 v[36:39], v179 offset:31744
	s_waitcnt lgkmcnt(0)
	v_mfma_f32_16x16x32_bf16 v[96:99], v[36:39], v[40:43], v[48:51]
	s_mov_b32 s24, 0xffff5b70
	s_mov_b32 s25, -1
	v_lshl_add_u64 v[40:41], v[186:187], 0, s[24:25]
	s_mov_b32 s24, 0xffff6000
	v_add_co_u32_e32 v48, vcc, s24, v186
	s_mov_b32 s24, 0xffff5bf0
	s_mov_b32 s25, -1
	s_mov_b32 m0, s11
	s_waitcnt vmcnt(12)
	s_barrier
	v_lshl_add_u64 v[36:37], v[192:193], 0, s[88:89]
	v_lshl_add_u64 v[50:51], v[186:187], 0, s[24:25]
	s_mov_b32 s24, 0xffff5f70
	global_load_lds_dwordx4 v[36:37], off
	v_lshl_add_u64 v[36:37], v[194:195], 0, s[88:89]
	s_mov_b32 m0, s9
	s_mov_b32 s25, -1
	global_load_lds_dwordx4 v[36:37], off
	v_lshl_add_u64 v[36:37], v[192:193], 0, s[90:91]
	s_mov_b32 m0, s8
	v_lshl_add_u64 v[56:57], v[186:187], 0, s[24:25]
	s_mov_b32 s24, 0xffff5ff0
	global_load_lds_dwordx4 v[36:37], off
	v_lshl_add_u64 v[36:37], v[194:195], 0, s[90:91]
	s_mov_b32 m0, s10
	s_mov_b32 s25, -1
	global_load_lds_dwordx4 v[36:37], off
	v_addc_co_u32_e32 v49, vcc, -1, v187, vcc
	v_lshl_add_u64 v[58:59], v[186:187], 0, s[24:25]
	s_mov_b64 exec, s[100:101]
	global_load_dwordx4 v[36:39], v[48:49], off offset:-1168
	s_nop 0
	global_load_dwordx4 v[40:43], v[40:41], off offset:16
	s_nop 0
	global_load_dwordx4 v[52:55], v[48:49], off offset:-1040
	global_load_dwordx4 v[44:47], v[48:49], off offset:-144
	global_load_dwordx4 v[64:67], v[50:51], off offset:16
	s_nop 0
	global_load_dwordx4 v[48:51], v[48:49], off offset:-16
	s_nop 0
	global_load_dwordx4 v[60:63], v[56:57], off offset:16
	s_nop 0
	global_load_dwordx4 v[56:59], v[58:59], off offset:16
	s_mov_b64 exec, -1
	v_cvt_pk_bf16_f32 v24, v24, v25
	v_cvt_pk_bf16_f32 v25, v26, v27
	v_cvt_pk_bf16_f32 v26, v12, v13
	v_cvt_pk_bf16_f32 v27, v14, v15
	v_cvt_pk_bf16_f32 v28, v28, v29
	v_cvt_pk_bf16_f32 v29, v30, v31
	v_cvt_pk_bf16_f32 v30, v32, v33
	v_cvt_pk_bf16_f32 v31, v34, v35
	v_cvt_pk_bf16_f32 v16, v16, v17
	v_cvt_pk_bf16_f32 v17, v18, v19
	v_cvt_pk_bf16_f32 v18, v20, v21
	v_cvt_pk_bf16_f32 v19, v22, v23
	v_cvt_pk_bf16_f32 v172, v8, v9
	v_cvt_pk_bf16_f32 v173, v10, v11
	v_cvt_pk_bf16_f32 v174, v4, v5
	v_cvt_pk_bf16_f32 v175, v6, v7
	ds_read_b128 v[4:7], v179 offset:32768
	ds_read_b128 v[8:11], v179 offset:34816
	ds_read_b128 v[12:15], v179 offset:36864
	s_waitcnt lgkmcnt(0)
	v_mfma_f32_16x16x32_bf16 v[20:23], v[8:11], v[24:27], v[104:107]
	ds_read_b128 v[8:11], v179 offset:38912
	v_mfma_f32_16x16x32_bf16 v[4:7], v[4:7], v[24:27], v[100:103]
	v_mfma_f32_16x16x32_bf16 v[32:35], v[12:15], v[24:27], v[108:111]
	ds_read_b128 v[12:15], v179 offset:40960
	s_waitcnt lgkmcnt(0)
	v_mfma_f32_16x16x32_bf16 v[100:103], v[8:11], v[24:27], v[112:115]
	ds_read_b128 v[8:11], v179 offset:43008
	v_mfma_f32_16x16x32_bf16 v[104:107], v[12:15], v[24:27], v[116:119]
	ds_read_b128 v[12:15], v179 offset:45056
	s_waitcnt lgkmcnt(0)
	v_mfma_f32_16x16x32_bf16 v[108:111], v[8:11], v[24:27], v[120:123]
	ds_read_b128 v[8:11], v179 offset:47104
	v_mfma_f32_16x16x32_bf16 v[112:115], v[12:15], v[24:27], v[124:127]
	s_waitcnt lgkmcnt(0)
	v_mfma_f32_16x16x32_bf16 v[116:119], v[8:11], v[24:27], v[128:131]
	ds_read_b128 v[8:11], v179 offset:33792
	s_waitcnt lgkmcnt(0)
	v_mfma_f32_16x16x32_bf16 v[8:11], v[8:11], v[28:31], v[4:7]
	s_nop 2
	ds_read_b128 v[4:7], v179 offset:35840
	s_waitcnt lgkmcnt(0)
	v_mfma_f32_16x16x32_bf16 v[12:15], v[4:7], v[28:31], v[20:23]
	ds_read_b128 v[4:7], v179 offset:37888
	s_waitcnt lgkmcnt(0)
	v_mfma_f32_16x16x32_bf16 v[20:23], v[4:7], v[28:31], v[32:35]
	ds_read_b128 v[4:7], v179 offset:39936
	s_waitcnt lgkmcnt(0)
	v_mfma_f32_16x16x32_bf16 v[24:27], v[4:7], v[28:31], v[100:103]
	ds_read_b128 v[4:7], v179 offset:41984
	s_waitcnt lgkmcnt(0)
	v_mfma_f32_16x16x32_bf16 v[32:35], v[4:7], v[28:31], v[104:107]
	ds_read_b128 v[4:7], v179 offset:44032
	s_waitcnt lgkmcnt(0)
	v_mfma_f32_16x16x32_bf16 v[100:103], v[4:7], v[28:31], v[108:111]
	ds_read_b128 v[4:7], v179 offset:46080
	s_waitcnt lgkmcnt(0)
	v_mfma_f32_16x16x32_bf16 v[104:107], v[4:7], v[28:31], v[112:115]
	ds_read_b128 v[4:7], v179 offset:48128
	s_waitcnt lgkmcnt(0)
	v_mfma_f32_16x16x32_bf16 v[116:119], v[4:7], v[28:31], v[116:119]
	ds_read_b128 v[4:7], v179 offset:49152
	ds_read_b128 v[28:31], v179 offset:51200
	s_waitcnt lgkmcnt(0)
	v_mfma_f32_16x16x32_bf16 v[4:7], v[4:7], v[16:19], v[68:71]
	s_nop 2
	ds_read_b128 v[68:71], v179 offset:53248
	v_mfma_f32_16x16x32_bf16 v[28:31], v[28:31], v[16:19], v[72:75]
	s_nop 2
	ds_read_b128 v[72:75], v179 offset:55296
	s_waitcnt lgkmcnt(0)
	v_mfma_f32_16x16x32_bf16 v[68:71], v[68:71], v[16:19], v[76:79]
	s_nop 2
	ds_read_b128 v[76:79], v179 offset:57344
	v_mfma_f32_16x16x32_bf16 v[72:75], v[72:75], v[16:19], v[80:83]
	s_waitcnt lgkmcnt(0)
	v_mfma_f32_16x16x32_bf16 v[80:83], v[76:79], v[16:19], v[84:87]
	ds_read_b128 v[76:79], v179 offset:59392
	s_waitcnt lgkmcnt(0)
	v_mfma_f32_16x16x32_bf16 v[108:111], v[76:79], v[16:19], v[88:91]
	ds_read_b128 v[76:79], v179 offset:61440
	s_waitcnt lgkmcnt(0)
	v_mfma_f32_16x16x32_bf16 v[92:95], v[76:79], v[16:19], v[92:95]
	ds_read_b128 v[76:79], v179 offset:63488
	s_waitcnt lgkmcnt(0)
	v_mfma_f32_16x16x32_bf16 v[16:19], v[76:79], v[16:19], v[96:99]
	ds_read_b128 v[76:79], v179 offset:50176
	s_waitcnt lgkmcnt(0)
	v_mfma_f32_16x16x32_bf16 v[76:79], v[76:79], v[172:175], v[4:7]
	s_nop 2
	ds_read_b128 v[4:7], v179 offset:52224
	s_waitcnt lgkmcnt(0)
	v_mfma_f32_16x16x32_bf16 v[84:87], v[4:7], v[172:175], v[28:31]
	ds_read_b128 v[4:7], v179 offset:54272
	s_waitcnt lgkmcnt(0)
	v_mfma_f32_16x16x32_bf16 v[88:91], v[4:7], v[172:175], v[68:71]
	ds_read_b128 v[4:7], v179 offset:56320
	s_waitcnt lgkmcnt(0)
	v_mfma_f32_16x16x32_bf16 v[112:115], v[4:7], v[172:175], v[72:75]
	ds_read_b128 v[4:7], v179 offset:58368
	s_waitcnt lgkmcnt(0)
	v_mfma_f32_16x16x32_bf16 v[128:131], v[4:7], v[172:175], v[80:83]
	ds_read_b128 v[4:7], v179 offset:60416
	s_waitcnt lgkmcnt(0)
	v_mfma_f32_16x16x32_bf16 v[164:167], v[4:7], v[172:175], v[108:111]
	ds_read_b128 v[4:7], v179 offset:62464
	s_waitcnt lgkmcnt(0)
	v_mfma_f32_16x16x32_bf16 v[168:171], v[4:7], v[172:175], v[92:95]
	ds_read_b128 v[4:7], v179 offset:64512
	s_waitcnt lgkmcnt(0)
	v_mfma_f32_16x16x32_bf16 v[172:175], v[4:7], v[172:175], v[16:19]
	s_mov_b32 s24, 0xffff6b70
	s_mov_b32 s25, -1
	s_nop 0
	v_lshl_add_u64 v[16:17], v[186:187], 0, s[24:25]
	s_mov_b32 s24, 0xffff7000
	v_add_co_u32_e32 v68, vcc, s24, v186
	s_mov_b32 s24, 0xffff6bf0
	s_mov_b32 s25, -1
	s_mov_b32 m0, s13
	s_waitcnt vmcnt(12)
	s_barrier
	v_lshl_add_u64 v[4:5], v[192:193], 0, s[92:93]
	v_lshl_add_u64 v[70:71], v[186:187], 0, s[24:25]
	s_mov_b32 s24, 0xffff6f70
	global_load_lds_dwordx4 v[4:5], off
	v_lshl_add_u64 v[4:5], v[194:195], 0, s[92:93]
	s_mov_b32 m0, s14
	s_mov_b32 s25, -1
	global_load_lds_dwordx4 v[4:5], off
	v_lshl_add_u64 v[4:5], v[192:193], 0, s[82:83]
	s_mov_b32 m0, s15
	v_lshl_add_u64 v[80:81], v[186:187], 0, s[24:25]
	s_mov_b32 s24, 0xffff6ff0
	global_load_lds_dwordx4 v[4:5], off
	v_lshl_add_u64 v[4:5], v[194:195], 0, s[82:83]
	s_mov_b32 m0, s16
	s_mov_b32 s25, -1
	global_load_lds_dwordx4 v[4:5], off
	v_addc_co_u32_e32 v69, vcc, -1, v187, vcc
	v_lshl_add_u64 v[82:83], v[186:187], 0, s[24:25]
	s_mov_b64 exec, s[100:101]
	global_load_dwordx4 v[4:7], v[68:69], off offset:-1168
	s_nop 0
	global_load_dwordx4 v[16:19], v[16:17], off offset:16
	s_nop 0
	global_load_dwordx4 v[72:75], v[68:69], off offset:-1040
	global_load_dwordx4 v[28:31], v[68:69], off offset:-144
	global_load_dwordx4 v[108:111], v[70:71], off offset:16
	s_nop 0
	global_load_dwordx4 v[68:71], v[68:69], off offset:-16
	s_nop 0
	global_load_dwordx4 v[96:99], v[80:81], off offset:16
	s_nop 0
	global_load_dwordx4 v[80:83], v[82:83], off offset:16
	s_mov_b64 exec, -1
	v_add_u32_e32 v208, s23, v181
	v_cvt_pk_bf16_f32 v92, v132, v133
	v_cvt_pk_bf16_f32 v93, v134, v135
	v_cvt_pk_bf16_f32 v94, v136, v137
	v_cvt_pk_bf16_f32 v95, v138, v139
	v_cvt_pk_bf16_f32 v132, v148, v149
	v_cvt_pk_bf16_f32 v133, v150, v151
	v_cvt_pk_bf16_f32 v134, v160, v161
	v_cvt_pk_bf16_f32 v135, v162, v163
	v_cvt_pk_bf16_f32 v136, v140, v141
	v_cvt_pk_bf16_f32 v137, v142, v143
	v_cvt_pk_bf16_f32 v138, v156, v157
	v_cvt_pk_bf16_f32 v139, v158, v159
	v_cvt_pk_bf16_f32 v160, v144, v145
	v_cvt_pk_bf16_f32 v161, v146, v147
	v_cvt_pk_bf16_f32 v162, v152, v153
	v_cvt_pk_bf16_f32 v163, v154, v155
	ds_read_b128 v[120:123], v208
	ds_read_b128 v[124:127], v208 offset:2048
	s_waitcnt lgkmcnt(0)
	v_mfma_f32_16x16x32_bf16 v[8:11], v[120:123], v[92:95], v[8:11]
	ds_read_b128 v[120:123], v208 offset:4096
	v_mfma_f32_16x16x32_bf16 v[124:127], v[124:127], v[92:95], v[12:15]
	s_nop 2
	ds_read_b128 v[12:15], v208 offset:6144
	s_waitcnt lgkmcnt(0)
	v_mfma_f32_16x16x32_bf16 v[20:23], v[120:123], v[92:95], v[20:23]
	ds_read_b128 v[120:123], v208 offset:8192
	v_mfma_f32_16x16x32_bf16 v[140:143], v[12:15], v[92:95], v[24:27]
	ds_read_b128 v[12:15], v208 offset:10240
	s_nop 1
	ds_read_b128 v[24:27], v208 offset:12288
	s_waitcnt lgkmcnt(0)
	v_mfma_f32_16x16x32_bf16 v[100:103], v[12:15], v[92:95], v[100:103]
	ds_read_b128 v[12:15], v208 offset:14336
	v_mfma_f32_16x16x32_bf16 v[32:35], v[120:123], v[92:95], v[32:35]
	v_mfma_f32_16x16x32_bf16 v[144:147], v[24:27], v[92:95], v[104:107]
	s_waitcnt lgkmcnt(0)
	v_mfma_f32_16x16x32_bf16 v[148:151], v[12:15], v[92:95], v[116:119]
	ds_read_b128 v[12:15], v208 offset:1024
	s_waitcnt lgkmcnt(0)
	v_mfma_f32_16x16x32_bf16 v[12:15], v[12:15], v[132:135], v[8:11]
	s_nop 2
	ds_read_b128 v[8:11], v208 offset:3072
	s_waitcnt lgkmcnt(0)
	v_mfma_f32_16x16x32_bf16 v[24:27], v[8:11], v[132:135], v[124:127]
	ds_read_b128 v[8:11], v208 offset:5120
	s_waitcnt lgkmcnt(0)
	v_mfma_f32_16x16x32_bf16 v[92:95], v[8:11], v[132:135], v[20:23]
	ds_read_b128 v[8:11], v208 offset:7168
	s_waitcnt lgkmcnt(0)
	v_mfma_f32_16x16x32_bf16 v[104:107], v[8:11], v[132:135], v[140:143]
	ds_read_b128 v[8:11], v208 offset:9216
	s_waitcnt lgkmcnt(0)
	v_mfma_f32_16x16x32_bf16 v[116:119], v[8:11], v[132:135], v[32:35]
	ds_read_b128 v[8:11], v208 offset:11264
	s_waitcnt lgkmcnt(0)
	v_mfma_f32_16x16x32_bf16 v[120:123], v[8:11], v[132:135], v[100:103]
	ds_read_b128 v[8:11], v208 offset:13312
	s_waitcnt lgkmcnt(0)
	v_mfma_f32_16x16x32_bf16 v[124:127], v[8:11], v[132:135], v[144:147]
	ds_read_b128 v[8:11], v208 offset:15360
	s_waitcnt lgkmcnt(0)
	v_mfma_f32_16x16x32_bf16 v[132:135], v[8:11], v[132:135], v[148:151]
	v_add_u32_e32 v207, s22, v181
	ds_read_b128 v[8:11], v207
	ds_read_b128 v[20:23], v207 offset:2048
	ds_read_b128 v[32:35], v207 offset:4096
	ds_read_b128 v[100:103], v207 offset:12288
	s_waitcnt lgkmcnt(0)
	v_mfma_f32_16x16x32_bf16 v[8:11], v[8:11], v[136:139], v[76:79]
	s_nop 2
	ds_read_b128 v[76:79], v207 offset:6144
	v_mfma_f32_16x16x32_bf16 v[20:23], v[20:23], v[136:139], v[84:87]
	v_mfma_f32_16x16x32_bf16 v[32:35], v[32:35], v[136:139], v[88:91]
	s_nop 1
	ds_read_b128 v[84:87], v207 offset:8192
	ds_read_b128 v[88:91], v207 offset:10240
	s_waitcnt lgkmcnt(0)
	v_mfma_f32_16x16x32_bf16 v[76:79], v[76:79], v[136:139], v[112:115]
	s_nop 2
	ds_read_b128 v[112:115], v207 offset:14336
	v_mfma_f32_16x16x32_bf16 v[84:87], v[84:87], v[136:139], v[128:131]
	v_mfma_f32_16x16x32_bf16 v[88:91], v[88:91], v[136:139], v[164:167]
	v_mfma_f32_16x16x32_bf16 v[100:103], v[100:103], v[136:139], v[168:171]
	s_waitcnt lgkmcnt(0)
	v_mfma_f32_16x16x32_bf16 v[112:115], v[112:115], v[136:139], v[172:175]
	ds_read_b128 v[128:131], v207 offset:1024
	s_waitcnt lgkmcnt(0)
	v_mfma_f32_16x16x32_bf16 v[128:131], v[128:131], v[160:163], v[8:11]
	s_nop 2
	ds_read_b128 v[8:11], v207 offset:3072
	s_waitcnt lgkmcnt(0)
	v_mfma_f32_16x16x32_bf16 v[136:139], v[8:11], v[160:163], v[20:23]
	ds_read_b128 v[8:11], v207 offset:5120
	s_waitcnt lgkmcnt(0)
	v_mfma_f32_16x16x32_bf16 v[140:143], v[8:11], v[160:163], v[32:35]
	ds_read_b128 v[8:11], v207 offset:7168
	s_waitcnt lgkmcnt(0)
	v_mfma_f32_16x16x32_bf16 v[144:147], v[8:11], v[160:163], v[76:79]
	ds_read_b128 v[8:11], v207 offset:9216
	s_waitcnt lgkmcnt(0)
	v_mfma_f32_16x16x32_bf16 v[148:151], v[8:11], v[160:163], v[84:87]
	ds_read_b128 v[8:11], v207 offset:11264
	s_waitcnt lgkmcnt(0)
	v_mfma_f32_16x16x32_bf16 v[152:155], v[8:11], v[160:163], v[88:91]
	ds_read_b128 v[8:11], v207 offset:13312
	s_waitcnt lgkmcnt(0)
	v_mfma_f32_16x16x32_bf16 v[156:159], v[8:11], v[160:163], v[100:103]
	ds_read_b128 v[8:11], v207 offset:15360
	s_waitcnt lgkmcnt(0)
	v_mfma_f32_16x16x32_bf16 v[160:163], v[8:11], v[160:163], v[112:115]
	s_mov_b32 s22, 0xffff7b70
	s_mov_b32 s23, -1
	v_lshl_add_u64 v[20:21], v[186:187], 0, s[22:23]
	s_movk_i32 s22, 0x8000
	v_add_co_u32_e32 v76, vcc, s22, v186
	s_mov_b32 s22, 0xffff7bf0
	s_mov_b32 s23, -1
	s_mov_b32 m0, s21
	s_waitcnt vmcnt(12)
	s_barrier
	v_lshl_add_u64 v[8:9], v[192:193], 0, s[72:73]
	v_lshl_add_u64 v[78:79], v[186:187], 0, s[22:23]
	s_mov_b32 s22, 0xffff7f70
	global_load_lds_dwordx4 v[8:9], off
	v_lshl_add_u64 v[8:9], v[194:195], 0, s[72:73]
	s_mov_b32 m0, s20
	s_mov_b32 s23, -1
	global_load_lds_dwordx4 v[8:9], off
	v_lshl_add_u64 v[8:9], v[192:193], 0, s[74:75]
	s_mov_b32 m0, s18
	v_lshl_add_u64 v[88:89], v[186:187], 0, s[22:23]
	s_mov_b32 s22, 0xffff7ff0
	global_load_lds_dwordx4 v[8:9], off
	v_lshl_add_u64 v[8:9], v[194:195], 0, s[74:75]
	s_mov_b32 m0, s19
	s_mov_b32 s23, -1
	global_load_lds_dwordx4 v[8:9], off
	v_addc_co_u32_e32 v77, vcc, -1, v187, vcc
	v_lshl_add_u64 v[90:91], v[186:187], 0, s[22:23]
	s_mov_b64 exec, s[100:101]
	global_load_dwordx4 v[8:11], v[76:77], off offset:-1168
	s_nop 0
	global_load_dwordx4 v[20:23], v[20:21], off offset:16
	s_nop 0
	global_load_dwordx4 v[84:87], v[76:77], off offset:-1040
	global_load_dwordx4 v[32:35], v[76:77], off offset:-144
	global_load_dwordx4 v[112:115], v[78:79], off offset:16
	s_nop 0
	global_load_dwordx4 v[76:79], v[76:77], off offset:-16
	s_nop 0
	global_load_dwordx4 v[100:103], v[88:89], off offset:16
	s_nop 0
	global_load_dwordx4 v[88:91], v[90:91], off offset:16
	s_mov_b64 exec, -1
	v_cvt_pk_bf16_f32 v36, v36, v37
	v_cvt_pk_bf16_f32 v37, v38, v39
	v_cvt_pk_bf16_f32 v38, v40, v41
	v_cvt_pk_bf16_f32 v39, v42, v43
	v_cvt_pk_bf16_f32 v164, v52, v53
	v_cvt_pk_bf16_f32 v165, v54, v55
	v_cvt_pk_bf16_f32 v166, v64, v65
	v_cvt_pk_bf16_f32 v167, v66, v67
	v_cvt_pk_bf16_f32 v168, v44, v45
	v_cvt_pk_bf16_f32 v169, v46, v47
	v_cvt_pk_bf16_f32 v170, v60, v61
	v_cvt_pk_bf16_f32 v171, v62, v63
	v_cvt_pk_bf16_f32 v48, v48, v49
	v_cvt_pk_bf16_f32 v49, v50, v51
	v_cvt_pk_bf16_f32 v50, v56, v57
	v_cvt_pk_bf16_f32 v51, v58, v59
	ds_read_b128 v[40:43], v179
	ds_read_b128 v[44:47], v179 offset:2048
	s_waitcnt lgkmcnt(0)
	v_mfma_f32_16x16x32_bf16 v[12:15], v[40:43], v[36:39], v[12:15]
	ds_read_b128 v[40:43], v179 offset:4096
	v_mfma_f32_16x16x32_bf16 v[24:27], v[44:47], v[36:39], v[24:27]
	ds_read_b128 v[44:47], v179 offset:6144
	s_waitcnt lgkmcnt(0)
	v_mfma_f32_16x16x32_bf16 v[52:55], v[40:43], v[36:39], v[92:95]
	ds_read_b128 v[40:43], v179 offset:8192
	v_mfma_f32_16x16x32_bf16 v[56:59], v[44:47], v[36:39], v[104:107]
	ds_read_b128 v[44:47], v179 offset:10240
	s_waitcnt lgkmcnt(0)
	v_mfma_f32_16x16x32_bf16 v[60:63], v[40:43], v[36:39], v[116:119]
	ds_read_b128 v[40:43], v179 offset:12288
	v_mfma_f32_16x16x32_bf16 v[92:95], v[44:47], v[36:39], v[120:123]
	ds_read_b128 v[44:47], v179 offset:14336
	s_waitcnt lgkmcnt(0)
	v_mfma_f32_16x16x32_bf16 v[104:107], v[40:43], v[36:39], v[124:127]
	v_mfma_f32_16x16x32_bf16 v[36:39], v[44:47], v[36:39], v[132:135]
	ds_read_b128 v[40:43], v179 offset:1024
	s_waitcnt lgkmcnt(0)
	v_mfma_f32_16x16x32_bf16 v[40:43], v[40:43], v[164:167], v[12:15]
	s_nop 2
	ds_read_b128 v[12:15], v179 offset:3072
	s_waitcnt lgkmcnt(0)
	v_mfma_f32_16x16x32_bf16 v[44:47], v[12:15], v[164:167], v[24:27]
	ds_read_b128 v[12:15], v179 offset:5120
	s_waitcnt lgkmcnt(0)
	v_mfma_f32_16x16x32_bf16 v[52:55], v[12:15], v[164:167], v[52:55]
	ds_read_b128 v[12:15], v179 offset:7168
	s_waitcnt lgkmcnt(0)
	v_mfma_f32_16x16x32_bf16 v[56:59], v[12:15], v[164:167], v[56:59]
	ds_read_b128 v[12:15], v179 offset:9216
	s_waitcnt lgkmcnt(0)
	v_mfma_f32_16x16x32_bf16 v[64:67], v[12:15], v[164:167], v[60:63]
	ds_read_b128 v[12:15], v179 offset:11264
	s_waitcnt lgkmcnt(0)
	v_mfma_f32_16x16x32_bf16 v[120:123], v[12:15], v[164:167], v[92:95]
	ds_read_b128 v[12:15], v179 offset:13312
	s_waitcnt lgkmcnt(0)
	v_mfma_f32_16x16x32_bf16 v[124:127], v[12:15], v[164:167], v[104:107]
	ds_read_b128 v[12:15], v179 offset:15360
	s_waitcnt lgkmcnt(0)
	v_mfma_f32_16x16x32_bf16 v[132:135], v[12:15], v[164:167], v[36:39]
	ds_read_b128 v[12:15], v179 offset:16384
	ds_read_b128 v[24:27], v179 offset:18432
	s_nop 0
	ds_read_b128 v[36:39], v179 offset:20480
	ds_read_b128 v[60:63], v179 offset:22528
	ds_read_b128 v[92:95], v179 offset:24576
	ds_read_b128 v[104:107], v179 offset:26624
	ds_read_b128 v[116:119], v179 offset:28672
	s_waitcnt lgkmcnt(0)
	v_mfma_f32_16x16x32_bf16 v[12:15], v[12:15], v[168:171], v[128:131]
	s_nop 2
	ds_read_b128 v[128:131], v179 offset:30720
	v_mfma_f32_16x16x32_bf16 v[24:27], v[24:27], v[168:171], v[136:139]
	v_mfma_f32_16x16x32_bf16 v[36:39], v[36:39], v[168:171], v[140:143]
	v_mfma_f32_16x16x32_bf16 v[60:63], v[60:63], v[168:171], v[144:147]
	v_mfma_f32_16x16x32_bf16 v[92:95], v[92:95], v[168:171], v[148:151]
	v_mfma_f32_16x16x32_bf16 v[104:107], v[104:107], v[168:171], v[152:155]
	v_mfma_f32_16x16x32_bf16 v[116:119], v[116:119], v[168:171], v[156:159]
	s_waitcnt lgkmcnt(0)
	v_mfma_f32_16x16x32_bf16 v[160:163], v[128:131], v[168:171], v[160:163]
	ds_read_b128 v[128:131], v179 offset:17408
	s_waitcnt lgkmcnt(0)
	v_mfma_f32_16x16x32_bf16 v[128:131], v[128:131], v[48:51], v[12:15]
	s_nop 2
	ds_read_b128 v[12:15], v179 offset:19456
	s_waitcnt lgkmcnt(0)
	v_mfma_f32_16x16x32_bf16 v[136:139], v[12:15], v[48:51], v[24:27]
	ds_read_b128 v[12:15], v179 offset:21504
	s_waitcnt lgkmcnt(0)
	v_mfma_f32_16x16x32_bf16 v[140:143], v[12:15], v[48:51], v[36:39]
	ds_read_b128 v[12:15], v179 offset:23552
	s_waitcnt lgkmcnt(0)
	v_mfma_f32_16x16x32_bf16 v[144:147], v[12:15], v[48:51], v[60:63]
	ds_read_b128 v[12:15], v179 offset:25600
	s_waitcnt lgkmcnt(0)
	v_mfma_f32_16x16x32_bf16 v[148:151], v[12:15], v[48:51], v[92:95]
	ds_read_b128 v[12:15], v179 offset:27648
	s_waitcnt lgkmcnt(0)
	v_mfma_f32_16x16x32_bf16 v[152:155], v[12:15], v[48:51], v[104:107]
	ds_read_b128 v[12:15], v179 offset:29696
	s_waitcnt lgkmcnt(0)
	v_mfma_f32_16x16x32_bf16 v[156:159], v[12:15], v[48:51], v[116:119]
	ds_read_b128 v[12:15], v179 offset:31744
	s_waitcnt lgkmcnt(0)
	v_mfma_f32_16x16x32_bf16 v[160:163], v[12:15], v[48:51], v[160:163]
	s_movk_i32 s22, 0x8b70
	s_mov_b32 s23, -1
	v_lshl_add_u64 v[24:25], v[186:187], 0, s[22:23]
	s_movk_i32 s22, 0x9000
	v_add_co_u32_e32 v48, vcc, s22, v186
	s_movk_i32 s22, 0x8bf0
	s_mov_b32 s23, -1
	s_mov_b32 m0, s11
	s_waitcnt vmcnt(12)
	s_barrier
	v_lshl_add_u64 v[12:13], v[192:193], 0, s[76:77]
	v_lshl_add_u64 v[50:51], v[186:187], 0, s[22:23]
	s_movk_i32 s22, 0x8f70
	global_load_lds_dwordx4 v[12:13], off
	v_lshl_add_u64 v[12:13], v[194:195], 0, s[76:77]
	s_mov_b32 m0, s9
	s_mov_b32 s23, -1
	global_load_lds_dwordx4 v[12:13], off
	v_lshl_add_u64 v[12:13], v[192:193], 0, s[60:61]
	s_mov_b32 m0, s8
	v_lshl_add_u64 v[92:93], v[186:187], 0, s[22:23]
	s_movk_i32 s22, 0x8ff0
	global_load_lds_dwordx4 v[12:13], off
	v_lshl_add_u64 v[12:13], v[194:195], 0, s[60:61]
	s_mov_b32 m0, s10
	s_mov_b32 s23, -1
	global_load_lds_dwordx4 v[12:13], off
	v_addc_co_u32_e32 v49, vcc, -1, v187, vcc
	v_lshl_add_u64 v[94:95], v[186:187], 0, s[22:23]
	s_mov_b64 exec, s[100:101]
	global_load_dwordx4 v[12:15], v[48:49], off offset:-1168
	s_nop 0
	global_load_dwordx4 v[24:27], v[24:25], off offset:16
	s_nop 0
	global_load_dwordx4 v[60:63], v[48:49], off offset:-1040
	global_load_dwordx4 v[36:39], v[48:49], off offset:-144
	global_load_dwordx4 v[116:119], v[50:51], off offset:16
	s_nop 0
	global_load_dwordx4 v[48:51], v[48:49], off offset:-16
	s_nop 0
	global_load_dwordx4 v[104:107], v[92:93], off offset:16
	s_nop 0
	global_load_dwordx4 v[92:95], v[94:95], off offset:16
	s_mov_b64 exec, -1
	v_cvt_pk_bf16_f32 v4, v4, v5
	v_cvt_pk_bf16_f32 v5, v6, v7
	v_cvt_pk_bf16_f32 v6, v16, v17
	v_cvt_pk_bf16_f32 v7, v18, v19
	v_cvt_pk_bf16_f32 v72, v72, v73
	v_cvt_pk_bf16_f32 v73, v74, v75
	v_cvt_pk_bf16_f32 v74, v108, v109
	v_cvt_pk_bf16_f32 v75, v110, v111
	v_cvt_pk_bf16_f32 v28, v28, v29
	v_cvt_pk_bf16_f32 v29, v30, v31
	v_cvt_pk_bf16_f32 v30, v96, v97
	v_cvt_pk_bf16_f32 v31, v98, v99
	v_cvt_pk_bf16_f32 v108, v68, v69
	v_cvt_pk_bf16_f32 v109, v70, v71
	v_cvt_pk_bf16_f32 v110, v80, v81
	v_cvt_pk_bf16_f32 v111, v82, v83
	ds_read_b128 v[16:19], v179 offset:32768
	ds_read_b128 v[68:71], v179 offset:34816
	s_waitcnt lgkmcnt(0)
	v_mfma_f32_16x16x32_bf16 v[16:19], v[16:19], v[4:7], v[40:43]
	s_nop 2
	ds_read_b128 v[40:43], v179 offset:36864
	v_mfma_f32_16x16x32_bf16 v[44:47], v[68:71], v[4:7], v[44:47]
	ds_read_b128 v[68:71], v179 offset:38912
	s_waitcnt lgkmcnt(0)
	v_mfma_f32_16x16x32_bf16 v[40:43], v[40:43], v[4:7], v[52:55]
	s_nop 2
	ds_read_b128 v[52:55], v179 offset:40960
	v_mfma_f32_16x16x32_bf16 v[68:71], v[68:71], v[4:7], v[56:59]
	s_nop 2
	ds_read_b128 v[56:59], v179 offset:43008
	s_waitcnt lgkmcnt(0)
	v_mfma_f32_16x16x32_bf16 v[52:55], v[52:55], v[4:7], v[64:67]
	s_nop 2
	ds_read_b128 v[64:67], v179 offset:45056
	v_mfma_f32_16x16x32_bf16 v[96:99], v[56:59], v[4:7], v[120:123]
	ds_read_b128 v[56:59], v179 offset:47104
	s_waitcnt lgkmcnt(0)
	v_mfma_f32_16x16x32_bf16 v[64:67], v[64:67], v[4:7], v[124:127]
	v_mfma_f32_16x16x32_bf16 v[4:7], v[56:59], v[4:7], v[132:135]
	ds_read_b128 v[56:59], v179 offset:33792
	s_waitcnt lgkmcnt(0)
	v_mfma_f32_16x16x32_bf16 v[16:19], v[56:59], v[72:75], v[16:19]
	ds_read_b128 v[56:59], v179 offset:35840
	s_waitcnt lgkmcnt(0)
	v_mfma_f32_16x16x32_bf16 v[44:47], v[56:59], v[72:75], v[44:47]
	ds_read_b128 v[56:59], v179 offset:37888
	s_waitcnt lgkmcnt(0)
	v_mfma_f32_16x16x32_bf16 v[56:59], v[56:59], v[72:75], v[40:43]
	s_nop 2
	ds_read_b128 v[40:43], v179 offset:39936
	s_waitcnt lgkmcnt(0)
	v_mfma_f32_16x16x32_bf16 v[68:71], v[40:43], v[72:75], v[68:71]
	ds_read_b128 v[40:43], v179 offset:41984
	s_waitcnt lgkmcnt(0)
	v_mfma_f32_16x16x32_bf16 v[80:83], v[40:43], v[72:75], v[52:55]
	ds_read_b128 v[40:43], v179 offset:44032
	s_waitcnt lgkmcnt(0)
	v_mfma_f32_16x16x32_bf16 v[96:99], v[40:43], v[72:75], v[96:99]
	ds_read_b128 v[40:43], v179 offset:46080
	s_waitcnt lgkmcnt(0)
	v_mfma_f32_16x16x32_bf16 v[124:127], v[40:43], v[72:75], v[64:67]
	ds_read_b128 v[40:43], v179 offset:48128
	s_waitcnt lgkmcnt(0)
	v_mfma_f32_16x16x32_bf16 v[132:135], v[40:43], v[72:75], v[4:7]
	s_nop 2
	ds_read_b128 v[4:7], v179 offset:49152
	ds_read_b128 v[40:43], v179 offset:51200
	ds_read_b128 v[52:55], v179 offset:53248
	ds_read_b128 v[64:67], v179 offset:55296
	ds_read_b128 v[72:75], v179 offset:57344
	ds_read_b128 v[120:123], v179 offset:59392
	s_waitcnt lgkmcnt(0)
	v_mfma_f32_16x16x32_bf16 v[4:7], v[4:7], v[28:31], v[128:131]
	s_nop 2
	ds_read_b128 v[128:131], v179 offset:61440
	v_mfma_f32_16x16x32_bf16 v[40:43], v[40:43], v[28:31], v[136:139]
	v_mfma_f32_16x16x32_bf16 v[52:55], v[52:55], v[28:31], v[140:143]
	s_waitcnt lgkmcnt(0)
	v_mfma_f32_16x16x32_bf16 v[156:159], v[128:131], v[28:31], v[156:159]
	ds_read_b128 v[128:131], v179 offset:63488
	v_mfma_f32_16x16x32_bf16 v[64:67], v[64:67], v[28:31], v[144:147]
	v_mfma_f32_16x16x32_bf16 v[72:75], v[72:75], v[28:31], v[148:151]
	v_mfma_f32_16x16x32_bf16 v[120:123], v[120:123], v[28:31], v[152:155]
	s_waitcnt lgkmcnt(0)
	v_mfma_f32_16x16x32_bf16 v[28:31], v[128:131], v[28:31], v[160:163]
	ds_read_b128 v[128:131], v179 offset:50176
	s_waitcnt lgkmcnt(0)
	v_mfma_f32_16x16x32_bf16 v[128:131], v[128:131], v[108:111], v[4:7]
	s_nop 2
	ds_read_b128 v[4:7], v179 offset:52224
	s_waitcnt lgkmcnt(0)
	v_mfma_f32_16x16x32_bf16 v[136:139], v[4:7], v[108:111], v[40:43]
	ds_read_b128 v[4:7], v179 offset:54272
	s_waitcnt lgkmcnt(0)
	v_mfma_f32_16x16x32_bf16 v[140:143], v[4:7], v[108:111], v[52:55]
	ds_read_b128 v[4:7], v179 offset:56320
	s_waitcnt lgkmcnt(0)
	v_mfma_f32_16x16x32_bf16 v[144:147], v[4:7], v[108:111], v[64:67]
	ds_read_b128 v[4:7], v179 offset:58368
	s_waitcnt lgkmcnt(0)
	v_mfma_f32_16x16x32_bf16 v[148:151], v[4:7], v[108:111], v[72:75]
	ds_read_b128 v[4:7], v179 offset:60416
	s_waitcnt lgkmcnt(0)
	v_mfma_f32_16x16x32_bf16 v[152:155], v[4:7], v[108:111], v[120:123]
	ds_read_b128 v[4:7], v179 offset:62464
	s_waitcnt lgkmcnt(0)
	v_mfma_f32_16x16x32_bf16 v[156:159], v[4:7], v[108:111], v[156:159]
	ds_read_b128 v[4:7], v179 offset:64512
	s_waitcnt lgkmcnt(0)
	v_mfma_f32_16x16x32_bf16 v[160:163], v[4:7], v[108:111], v[28:31]
	s_movk_i32 s22, 0x9b70
	s_mov_b32 s23, -1
	s_nop 0
	v_lshl_add_u64 v[28:29], v[186:187], 0, s[22:23]
	s_movk_i32 s22, 0xa000
	v_add_co_u32_e32 v52, vcc, s22, v186
	s_movk_i32 s22, 0x9bf0
	s_mov_b32 s23, -1
	s_mov_b32 m0, s13
	s_waitcnt vmcnt(12)
	s_barrier
	v_lshl_add_u64 v[4:5], v[192:193], 0, s[58:59]
	v_lshl_add_u64 v[54:55], v[186:187], 0, s[22:23]
	s_movk_i32 s22, 0x9f70
	global_load_lds_dwordx4 v[4:5], off
	v_lshl_add_u64 v[4:5], v[194:195], 0, s[58:59]
	s_mov_b32 m0, s14
	s_mov_b32 s23, -1
	global_load_lds_dwordx4 v[4:5], off
	v_lshl_add_u64 v[4:5], v[192:193], 0, s[54:55]
	s_mov_b32 m0, s15
	v_lshl_add_u64 v[72:73], v[186:187], 0, s[22:23]
	s_movk_i32 s22, 0x9ff0
	global_load_lds_dwordx4 v[4:5], off
	v_lshl_add_u64 v[4:5], v[194:195], 0, s[54:55]
	s_mov_b32 m0, s16
	s_mov_b32 s23, -1
	global_load_lds_dwordx4 v[4:5], off
	v_addc_co_u32_e32 v53, vcc, -1, v187, vcc
	v_lshl_add_u64 v[74:75], v[186:187], 0, s[22:23]
	s_mov_b64 exec, s[100:101]
	global_load_dwordx4 v[4:7], v[52:53], off offset:-1168
	s_nop 0
	global_load_dwordx4 v[28:31], v[28:29], off offset:16
	s_nop 0
	global_load_dwordx4 v[64:67], v[52:53], off offset:-1040
	global_load_dwordx4 v[40:43], v[52:53], off offset:-144
	global_load_dwordx4 v[120:123], v[54:55], off offset:16
	s_nop 0
	global_load_dwordx4 v[52:55], v[52:53], off offset:-16
	s_nop 0
	global_load_dwordx4 v[108:111], v[72:73], off offset:16
	s_nop 0
	global_load_dwordx4 v[72:75], v[74:75], off offset:16
	s_mov_b64 exec, -1
	v_cvt_pk_bf16_f32 v8, v8, v9
	v_cvt_pk_bf16_f32 v9, v10, v11
	v_cvt_pk_bf16_f32 v10, v20, v21
	v_cvt_pk_bf16_f32 v11, v22, v23
	v_cvt_pk_bf16_f32 v20, v84, v85
	v_cvt_pk_bf16_f32 v21, v86, v87
	v_cvt_pk_bf16_f32 v22, v112, v113
	v_cvt_pk_bf16_f32 v23, v114, v115
	v_cvt_pk_bf16_f32 v164, v32, v33
	v_cvt_pk_bf16_f32 v165, v34, v35
	v_cvt_pk_bf16_f32 v166, v100, v101
	v_cvt_pk_bf16_f32 v167, v102, v103
	v_cvt_pk_bf16_f32 v100, v76, v77
	v_cvt_pk_bf16_f32 v101, v78, v79
	v_cvt_pk_bf16_f32 v102, v88, v89
	v_cvt_pk_bf16_f32 v103, v90, v91
	ds_read_b128 v[32:35], v208
	ds_read_b128 v[76:79], v208 offset:2048
	s_waitcnt lgkmcnt(0)
	v_mfma_f32_16x16x32_bf16 v[16:19], v[32:35], v[8:11], v[16:19]
	ds_read_b128 v[32:35], v208 offset:4096
	v_mfma_f32_16x16x32_bf16 v[44:47], v[76:79], v[8:11], v[44:47]
	ds_read_b128 v[76:79], v208 offset:6144
	s_waitcnt lgkmcnt(0)
	v_mfma_f32_16x16x32_bf16 v[56:59], v[32:35], v[8:11], v[56:59]
	ds_read_b128 v[32:35], v208 offset:8192
	v_mfma_f32_16x16x32_bf16 v[68:71], v[76:79], v[8:11], v[68:71]
	ds_read_b128 v[76:79], v208 offset:10240
	s_waitcnt lgkmcnt(0)
	v_mfma_f32_16x16x32_bf16 v[80:83], v[32:35], v[8:11], v[80:83]
	ds_read_b128 v[32:35], v208 offset:12288
	v_mfma_f32_16x16x32_bf16 v[96:99], v[76:79], v[8:11], v[96:99]
	ds_read_b128 v[76:79], v208 offset:14336
	s_waitcnt lgkmcnt(0)
	v_mfma_f32_16x16x32_bf16 v[112:115], v[32:35], v[8:11], v[124:127]
	v_mfma_f32_16x16x32_bf16 v[124:127], v[76:79], v[8:11], v[132:135]
	ds_read_b128 v[8:11], v208 offset:1024
	s_waitcnt lgkmcnt(0)
	v_mfma_f32_16x16x32_bf16 v[8:11], v[8:11], v[20:23], v[16:19]
	s_nop 2
	ds_read_b128 v[16:19], v208 offset:3072
	s_waitcnt lgkmcnt(0)
	v_mfma_f32_16x16x32_bf16 v[32:35], v[16:19], v[20:23], v[44:47]
	ds_read_b128 v[16:19], v208 offset:5120
	s_waitcnt lgkmcnt(0)
	v_mfma_f32_16x16x32_bf16 v[76:79], v[16:19], v[20:23], v[56:59]
	ds_read_b128 v[16:19], v208 offset:7168
	s_waitcnt lgkmcnt(0)
	v_mfma_f32_16x16x32_bf16 v[84:87], v[16:19], v[20:23], v[68:71]
	ds_read_b128 v[16:19], v208 offset:9216
	s_waitcnt lgkmcnt(0)
	v_mfma_f32_16x16x32_bf16 v[88:91], v[16:19], v[20:23], v[80:83]
	ds_read_b128 v[16:19], v208 offset:11264
	s_waitcnt lgkmcnt(0)
	v_mfma_f32_16x16x32_bf16 v[96:99], v[16:19], v[20:23], v[96:99]
	ds_read_b128 v[16:19], v208 offset:13312
	s_waitcnt lgkmcnt(0)
	v_mfma_f32_16x16x32_bf16 v[112:115], v[16:19], v[20:23], v[112:115]
	ds_read_b128 v[16:19], v208 offset:15360
	s_waitcnt lgkmcnt(0)
	v_mfma_f32_16x16x32_bf16 v[132:135], v[16:19], v[20:23], v[124:127]
	ds_read_b128 v[16:19], v207
	ds_read_b128 v[20:23], v207 offset:2048
	ds_read_b128 v[44:47], v207 offset:4096
	ds_read_b128 v[56:59], v207 offset:6144
	ds_read_b128 v[68:71], v207 offset:8192
	ds_read_b128 v[80:83], v207 offset:10240
	ds_read_b128 v[124:127], v207 offset:12288
	s_waitcnt lgkmcnt(0)
	v_mfma_f32_16x16x32_bf16 v[16:19], v[16:19], v[164:167], v[128:131]
	s_nop 2
	ds_read_b128 v[128:131], v207 offset:14336
	v_mfma_f32_16x16x32_bf16 v[20:23], v[20:23], v[164:167], v[136:139]
	v_mfma_f32_16x16x32_bf16 v[44:47], v[44:47], v[164:167], v[140:143]
	v_mfma_f32_16x16x32_bf16 v[56:59], v[56:59], v[164:167], v[144:147]
	v_mfma_f32_16x16x32_bf16 v[68:71], v[68:71], v[164:167], v[148:151]
	v_mfma_f32_16x16x32_bf16 v[80:83], v[80:83], v[164:167], v[152:155]
	v_mfma_f32_16x16x32_bf16 v[124:127], v[124:127], v[164:167], v[156:159]
	s_waitcnt lgkmcnt(0)
	v_mfma_f32_16x16x32_bf16 v[160:163], v[128:131], v[164:167], v[160:163]
	ds_read_b128 v[128:131], v207 offset:1024
	s_waitcnt lgkmcnt(0)
	v_mfma_f32_16x16x32_bf16 v[128:131], v[128:131], v[100:103], v[16:19]
	s_nop 2
	ds_read_b128 v[16:19], v207 offset:3072
	s_waitcnt lgkmcnt(0)
	v_mfma_f32_16x16x32_bf16 v[136:139], v[16:19], v[100:103], v[20:23]
	ds_read_b128 v[16:19], v207 offset:5120
	s_waitcnt lgkmcnt(0)
	v_mfma_f32_16x16x32_bf16 v[140:143], v[16:19], v[100:103], v[44:47]
	ds_read_b128 v[16:19], v207 offset:7168
	s_waitcnt lgkmcnt(0)
	v_mfma_f32_16x16x32_bf16 v[144:147], v[16:19], v[100:103], v[56:59]
	ds_read_b128 v[16:19], v207 offset:9216
	s_waitcnt lgkmcnt(0)
	v_mfma_f32_16x16x32_bf16 v[148:151], v[16:19], v[100:103], v[68:71]
	ds_read_b128 v[16:19], v207 offset:11264
	s_waitcnt lgkmcnt(0)
	v_mfma_f32_16x16x32_bf16 v[152:155], v[16:19], v[100:103], v[80:83]
	ds_read_b128 v[16:19], v207 offset:13312
	s_waitcnt lgkmcnt(0)
	v_mfma_f32_16x16x32_bf16 v[156:159], v[16:19], v[100:103], v[124:127]
	ds_read_b128 v[16:19], v207 offset:15360
	s_waitcnt lgkmcnt(0)
	v_mfma_f32_16x16x32_bf16 v[160:163], v[16:19], v[100:103], v[160:163]
	s_movk_i32 s22, 0xab70
	s_mov_b32 s23, -1
	v_lshl_add_u64 v[20:21], v[186:187], 0, s[22:23]
	s_movk_i32 s22, 0xb000
	v_add_co_u32_e32 v56, vcc, s22, v186
	s_movk_i32 s22, 0xabf0
	s_mov_b32 s23, -1
	s_mov_b32 m0, s21
	s_waitcnt vmcnt(12)
	s_barrier
	v_lshl_add_u64 v[16:17], v[192:193], 0, s[42:43]
	v_lshl_add_u64 v[58:59], v[186:187], 0, s[22:23]
	s_movk_i32 s22, 0xaf70
	global_load_lds_dwordx4 v[16:17], off
	v_lshl_add_u64 v[16:17], v[194:195], 0, s[42:43]
	s_mov_b32 m0, s20
	s_mov_b32 s23, -1
	global_load_lds_dwordx4 v[16:17], off
	v_lshl_add_u64 v[16:17], v[192:193], 0, s[26:27]
	s_mov_b32 m0, s18
	v_lshl_add_u64 v[80:81], v[186:187], 0, s[22:23]
	s_movk_i32 s22, 0xaff0
	global_load_lds_dwordx4 v[16:17], off
	v_lshl_add_u64 v[16:17], v[194:195], 0, s[26:27]
	s_mov_b32 m0, s19
	s_mov_b32 s23, -1
	global_load_lds_dwordx4 v[16:17], off
	v_addc_co_u32_e32 v57, vcc, -1, v187, vcc
	v_lshl_add_u64 v[82:83], v[186:187], 0, s[22:23]
	s_mov_b64 exec, s[100:101]
	global_load_dwordx4 v[16:19], v[56:57], off offset:-1168
	s_nop 0
	global_load_dwordx4 v[20:23], v[20:21], off offset:16
	s_nop 0
	global_load_dwordx4 v[68:71], v[56:57], off offset:-1040
	global_load_dwordx4 v[44:47], v[56:57], off offset:-144
	global_load_dwordx4 v[124:127], v[58:59], off offset:16
	s_nop 0
	global_load_dwordx4 v[56:59], v[56:57], off offset:-16
	s_nop 0
	global_load_dwordx4 v[100:103], v[80:81], off offset:16
	s_nop 0
	global_load_dwordx4 v[80:83], v[82:83], off offset:16
	s_mov_b64 exec, -1
	v_cvt_pk_bf16_f32 v12, v12, v13
	v_cvt_pk_bf16_f32 v13, v14, v15
	v_cvt_pk_bf16_f32 v14, v24, v25
	v_cvt_pk_bf16_f32 v15, v26, v27
	v_cvt_pk_bf16_f32 v24, v60, v61
	v_cvt_pk_bf16_f32 v25, v62, v63
	v_cvt_pk_bf16_f32 v26, v116, v117
	v_cvt_pk_bf16_f32 v27, v118, v119
	v_cvt_pk_bf16_f32 v36, v36, v37
	v_cvt_pk_bf16_f32 v37, v38, v39
	v_cvt_pk_bf16_f32 v38, v104, v105
	v_cvt_pk_bf16_f32 v39, v106, v107
	v_cvt_pk_bf16_f32 v48, v48, v49
	v_cvt_pk_bf16_f32 v49, v50, v51
	v_cvt_pk_bf16_f32 v50, v92, v93
	v_cvt_pk_bf16_f32 v51, v94, v95
	ds_read_b128 v[60:63], v179
	ds_read_b128 v[92:95], v179 offset:2048
	s_waitcnt lgkmcnt(0)
	v_mfma_f32_16x16x32_bf16 v[8:11], v[60:63], v[12:15], v[8:11]
	ds_read_b128 v[60:63], v179 offset:4096
	v_mfma_f32_16x16x32_bf16 v[32:35], v[92:95], v[12:15], v[32:35]
	ds_read_b128 v[92:95], v179 offset:6144
	s_waitcnt lgkmcnt(0)
	v_mfma_f32_16x16x32_bf16 v[60:63], v[60:63], v[12:15], v[76:79]
	s_nop 2
	ds_read_b128 v[76:79], v179 offset:8192
	v_mfma_f32_16x16x32_bf16 v[84:87], v[92:95], v[12:15], v[84:87]
	ds_read_b128 v[92:95], v179 offset:10240
	s_waitcnt lgkmcnt(0)
	v_mfma_f32_16x16x32_bf16 v[88:91], v[76:79], v[12:15], v[88:91]
	ds_read_b128 v[76:79], v179 offset:12288
	v_mfma_f32_16x16x32_bf16 v[92:95], v[92:95], v[12:15], v[96:99]
	s_nop 2
	ds_read_b128 v[96:99], v179 offset:14336
	s_waitcnt lgkmcnt(0)
	v_mfma_f32_16x16x32_bf16 v[104:107], v[76:79], v[12:15], v[112:115]
	v_mfma_f32_16x16x32_bf16 v[12:15], v[96:99], v[12:15], v[132:135]
	ds_read_b128 v[76:79], v179 offset:1024
	s_waitcnt lgkmcnt(0)
	v_mfma_f32_16x16x32_bf16 v[8:11], v[76:79], v[24:27], v[8:11]
	ds_read_b128 v[76:79], v179 offset:3072
	s_waitcnt lgkmcnt(0)
	v_mfma_f32_16x16x32_bf16 v[32:35], v[76:79], v[24:27], v[32:35]
	ds_read_b128 v[76:79], v179 offset:5120
	s_waitcnt lgkmcnt(0)
	v_mfma_f32_16x16x32_bf16 v[76:79], v[76:79], v[24:27], v[60:63]
	s_nop 2
	ds_read_b128 v[60:63], v179 offset:7168
	s_waitcnt lgkmcnt(0)
	v_mfma_f32_16x16x32_bf16 v[84:87], v[60:63], v[24:27], v[84:87]
	ds_read_b128 v[60:63], v179 offset:9216
	s_waitcnt lgkmcnt(0)
	v_mfma_f32_16x16x32_bf16 v[88:91], v[60:63], v[24:27], v[88:91]
	ds_read_b128 v[60:63], v179 offset:11264
	s_waitcnt lgkmcnt(0)
	v_mfma_f32_16x16x32_bf16 v[92:95], v[60:63], v[24:27], v[92:95]
	ds_read_b128 v[60:63], v179 offset:13312
	s_waitcnt lgkmcnt(0)
	v_mfma_f32_16x16x32_bf16 v[104:107], v[60:63], v[24:27], v[104:107]
	ds_read_b128 v[60:63], v179 offset:15360
	s_waitcnt lgkmcnt(0)
	v_mfma_f32_16x16x32_bf16 v[116:119], v[60:63], v[24:27], v[12:15]
	s_nop 2
	ds_read_b128 v[12:15], v179 offset:16384
	ds_read_b128 v[24:27], v179 offset:18432
	ds_read_b128 v[132:135], v179 offset:28672
	ds_read_b128 v[60:63], v179 offset:20480
	ds_read_b128 v[96:99], v179 offset:22528
	ds_read_b128 v[112:115], v179 offset:24576
	s_waitcnt lgkmcnt(0)
	v_mfma_f32_16x16x32_bf16 v[12:15], v[12:15], v[36:39], v[128:131]
	s_nop 2
	ds_read_b128 v[128:131], v179 offset:26624
	v_mfma_f32_16x16x32_bf16 v[156:159], v[132:135], v[36:39], v[156:159]
	ds_read_b128 v[132:135], v179 offset:30720
	v_mfma_f32_16x16x32_bf16 v[24:27], v[24:27], v[36:39], v[136:139]
	v_mfma_f32_16x16x32_bf16 v[60:63], v[60:63], v[36:39], v[140:143]
	v_mfma_f32_16x16x32_bf16 v[96:99], v[96:99], v[36:39], v[144:147]
	v_mfma_f32_16x16x32_bf16 v[112:115], v[112:115], v[36:39], v[148:151]
	s_waitcnt lgkmcnt(0)
	v_mfma_f32_16x16x32_bf16 v[128:131], v[128:131], v[36:39], v[152:155]
	v_mfma_f32_16x16x32_bf16 v[36:39], v[132:135], v[36:39], v[160:163]
	ds_read_b128 v[132:135], v179 offset:17408
	s_waitcnt lgkmcnt(0)
	v_mfma_f32_16x16x32_bf16 v[132:135], v[132:135], v[48:51], v[12:15]
	s_nop 2
	ds_read_b128 v[12:15], v179 offset:19456
	s_waitcnt lgkmcnt(0)
	v_mfma_f32_16x16x32_bf16 v[136:139], v[12:15], v[48:51], v[24:27]
	ds_read_b128 v[12:15], v179 offset:21504
	s_waitcnt lgkmcnt(0)
	v_mfma_f32_16x16x32_bf16 v[140:143], v[12:15], v[48:51], v[60:63]
	ds_read_b128 v[12:15], v179 offset:23552
	s_waitcnt lgkmcnt(0)
	v_mfma_f32_16x16x32_bf16 v[144:147], v[12:15], v[48:51], v[96:99]
	ds_read_b128 v[12:15], v179 offset:25600
	s_waitcnt lgkmcnt(0)
	v_mfma_f32_16x16x32_bf16 v[148:151], v[12:15], v[48:51], v[112:115]
	ds_read_b128 v[12:15], v179 offset:27648
	s_waitcnt lgkmcnt(0)
	v_mfma_f32_16x16x32_bf16 v[152:155], v[12:15], v[48:51], v[128:131]
	ds_read_b128 v[12:15], v179 offset:29696
	s_waitcnt lgkmcnt(0)
	v_mfma_f32_16x16x32_bf16 v[156:159], v[12:15], v[48:51], v[156:159]
	ds_read_b128 v[12:15], v179 offset:31744
	s_waitcnt lgkmcnt(0)
	v_mfma_f32_16x16x32_bf16 v[160:163], v[12:15], v[48:51], v[36:39]
	s_movk_i32 s22, 0xbb70
	s_mov_b32 s23, -1
	v_lshl_add_u64 v[24:25], v[186:187], 0, s[22:23]
	s_movk_i32 s22, 0xc000
	v_add_co_u32_e32 v48, vcc, s22, v186
	s_movk_i32 s22, 0xbbf0
	s_mov_b32 s23, -1
	s_mov_b32 m0, s11
	s_waitcnt vmcnt(12)
	s_barrier
	v_lshl_add_u64 v[12:13], v[192:193], 0, s[28:29]
	v_lshl_add_u64 v[50:51], v[186:187], 0, s[22:23]
	s_movk_i32 s22, 0xbf70
	global_load_lds_dwordx4 v[12:13], off
	v_lshl_add_u64 v[12:13], v[194:195], 0, s[28:29]
	s_mov_b32 m0, s9
	s_mov_b32 s23, -1
	global_load_lds_dwordx4 v[12:13], off
	v_lshl_add_u64 v[12:13], v[192:193], 0, s[30:31]
	s_mov_b32 m0, s8
	v_lshl_add_u64 v[96:97], v[186:187], 0, s[22:23]
	s_movk_i32 s22, 0xbff0
	global_load_lds_dwordx4 v[12:13], off
	v_lshl_add_u64 v[12:13], v[194:195], 0, s[30:31]
	s_mov_b32 m0, s10
	s_mov_b32 s23, -1
	global_load_lds_dwordx4 v[12:13], off
	v_addc_co_u32_e32 v49, vcc, -1, v187, vcc
	v_lshl_add_u64 v[98:99], v[186:187], 0, s[22:23]
	s_mov_b64 exec, s[100:101]
	global_load_dwordx4 v[12:15], v[48:49], off offset:-1168
	s_nop 0
	global_load_dwordx4 v[24:27], v[24:25], off offset:16
	s_nop 0
	global_load_dwordx4 v[60:63], v[48:49], off offset:-1040
	global_load_dwordx4 v[36:39], v[48:49], off offset:-144
	global_load_dwordx4 v[128:131], v[50:51], off offset:16
	s_nop 0
	global_load_dwordx4 v[48:51], v[48:49], off offset:-16
	s_nop 0
	global_load_dwordx4 v[112:115], v[96:97], off offset:16
	s_nop 0
	global_load_dwordx4 v[96:99], v[98:99], off offset:16
	s_mov_b64 exec, -1
	v_cvt_pk_bf16_f32 v4, v4, v5
	v_cvt_pk_bf16_f32 v5, v6, v7
	v_cvt_pk_bf16_f32 v6, v28, v29
	v_cvt_pk_bf16_f32 v7, v30, v31
	v_cvt_pk_bf16_f32 v28, v64, v65
	v_cvt_pk_bf16_f32 v29, v66, v67
	v_cvt_pk_bf16_f32 v30, v120, v121
	v_cvt_pk_bf16_f32 v31, v122, v123
	v_cvt_pk_bf16_f32 v164, v40, v41
	v_cvt_pk_bf16_f32 v165, v42, v43
	v_cvt_pk_bf16_f32 v166, v108, v109
	v_cvt_pk_bf16_f32 v167, v110, v111
	v_cvt_pk_bf16_f32 v108, v52, v53
	v_cvt_pk_bf16_f32 v109, v54, v55
	v_cvt_pk_bf16_f32 v110, v72, v73
	v_cvt_pk_bf16_f32 v111, v74, v75
	ds_read_b128 v[40:43], v179 offset:32768
	ds_read_b128 v[52:55], v179 offset:34816
	s_waitcnt lgkmcnt(0)
	v_mfma_f32_16x16x32_bf16 v[8:11], v[40:43], v[4:7], v[8:11]
	ds_read_b128 v[40:43], v179 offset:36864
	v_mfma_f32_16x16x32_bf16 v[32:35], v[52:55], v[4:7], v[32:35]
	ds_read_b128 v[52:55], v179 offset:38912
	s_waitcnt lgkmcnt(0)
	v_mfma_f32_16x16x32_bf16 v[64:67], v[40:43], v[4:7], v[76:79]
	ds_read_b128 v[40:43], v179 offset:40960
	v_mfma_f32_16x16x32_bf16 v[72:75], v[52:55], v[4:7], v[84:87]
	ds_read_b128 v[52:55], v179 offset:43008
	s_waitcnt lgkmcnt(0)
	v_mfma_f32_16x16x32_bf16 v[76:79], v[40:43], v[4:7], v[88:91]
	ds_read_b128 v[40:43], v179 offset:45056
	v_mfma_f32_16x16x32_bf16 v[84:87], v[52:55], v[4:7], v[92:95]
	ds_read_b128 v[52:55], v179 offset:47104
	s_waitcnt lgkmcnt(0)
	v_mfma_f32_16x16x32_bf16 v[88:91], v[40:43], v[4:7], v[104:107]
	v_mfma_f32_16x16x32_bf16 v[4:7], v[52:55], v[4:7], v[116:119]
	ds_read_b128 v[40:43], v179 offset:33792
	s_waitcnt lgkmcnt(0)
	v_mfma_f32_16x16x32_bf16 v[40:43], v[40:43], v[28:31], v[8:11]
	s_nop 2
	ds_read_b128 v[8:11], v179 offset:35840
	s_waitcnt lgkmcnt(0)
	v_mfma_f32_16x16x32_bf16 v[52:55], v[8:11], v[28:31], v[32:35]
	ds_read_b128 v[8:11], v179 offset:37888
	s_waitcnt lgkmcnt(0)
	v_mfma_f32_16x16x32_bf16 v[64:67], v[8:11], v[28:31], v[64:67]
	ds_read_b128 v[8:11], v179 offset:39936
	s_waitcnt lgkmcnt(0)
	v_mfma_f32_16x16x32_bf16 v[72:75], v[8:11], v[28:31], v[72:75]
	ds_read_b128 v[8:11], v179 offset:41984
	s_waitcnt lgkmcnt(0)
	v_mfma_f32_16x16x32_bf16 v[92:95], v[8:11], v[28:31], v[76:79]
	ds_read_b128 v[8:11], v179 offset:44032
	s_waitcnt lgkmcnt(0)
	v_mfma_f32_16x16x32_bf16 v[104:107], v[8:11], v[28:31], v[84:87]
	ds_read_b128 v[8:11], v179 offset:46080
	s_waitcnt lgkmcnt(0)
	v_mfma_f32_16x16x32_bf16 v[116:119], v[8:11], v[28:31], v[88:91]
	ds_read_b128 v[8:11], v179 offset:48128
	s_waitcnt lgkmcnt(0)
	v_mfma_f32_16x16x32_bf16 v[120:123], v[8:11], v[28:31], v[4:7]
	s_nop 2
	ds_read_b128 v[4:7], v179 offset:49152
	ds_read_b128 v[8:11], v179 offset:51200
	ds_read_b128 v[28:31], v179 offset:53248
	ds_read_b128 v[32:35], v179 offset:55296
	ds_read_b128 v[76:79], v179 offset:57344
	ds_read_b128 v[84:87], v179 offset:59392
	ds_read_b128 v[88:91], v179 offset:61440
	s_waitcnt lgkmcnt(0)
	v_mfma_f32_16x16x32_bf16 v[4:7], v[4:7], v[164:167], v[132:135]
	s_nop 2
	ds_read_b128 v[132:135], v179 offset:63488
	v_mfma_f32_16x16x32_bf16 v[8:11], v[8:11], v[164:167], v[136:139]
	v_mfma_f32_16x16x32_bf16 v[28:31], v[28:31], v[164:167], v[140:143]
	v_mfma_f32_16x16x32_bf16 v[32:35], v[32:35], v[164:167], v[144:147]
	v_mfma_f32_16x16x32_bf16 v[76:79], v[76:79], v[164:167], v[148:151]
	v_mfma_f32_16x16x32_bf16 v[84:87], v[84:87], v[164:167], v[152:155]
	v_mfma_f32_16x16x32_bf16 v[88:91], v[88:91], v[164:167], v[156:159]
	s_waitcnt lgkmcnt(0)
	v_mfma_f32_16x16x32_bf16 v[160:163], v[132:135], v[164:167], v[160:163]
	ds_read_b128 v[132:135], v179 offset:50176
	s_waitcnt lgkmcnt(0)
	v_mfma_f32_16x16x32_bf16 v[132:135], v[132:135], v[108:111], v[4:7]
	s_nop 2
	ds_read_b128 v[4:7], v179 offset:52224
	s_waitcnt lgkmcnt(0)
	v_mfma_f32_16x16x32_bf16 v[136:139], v[4:7], v[108:111], v[8:11]
	ds_read_b128 v[4:7], v179 offset:54272
	s_waitcnt lgkmcnt(0)
	v_mfma_f32_16x16x32_bf16 v[140:143], v[4:7], v[108:111], v[28:31]
	ds_read_b128 v[4:7], v179 offset:56320
	s_waitcnt lgkmcnt(0)
	v_mfma_f32_16x16x32_bf16 v[144:147], v[4:7], v[108:111], v[32:35]
	ds_read_b128 v[4:7], v179 offset:58368
	s_waitcnt lgkmcnt(0)
	v_mfma_f32_16x16x32_bf16 v[148:151], v[4:7], v[108:111], v[76:79]
	ds_read_b128 v[4:7], v179 offset:60416
	s_waitcnt lgkmcnt(0)
	v_mfma_f32_16x16x32_bf16 v[152:155], v[4:7], v[108:111], v[84:87]
	ds_read_b128 v[4:7], v179 offset:62464
	s_waitcnt lgkmcnt(0)
	v_mfma_f32_16x16x32_bf16 v[156:159], v[4:7], v[108:111], v[88:91]
	ds_read_b128 v[4:7], v179 offset:64512
	s_waitcnt lgkmcnt(0)
	v_mfma_f32_16x16x32_bf16 v[160:163], v[4:7], v[108:111], v[160:163]
	s_movk_i32 s22, 0xcb70
	s_mov_b32 s23, -1
	v_lshl_add_u64 v[8:9], v[186:187], 0, s[22:23]
	s_movk_i32 s22, 0xd000
	v_add_co_u32_e32 v32, vcc, s22, v186
	s_movk_i32 s22, 0xcbf0
	s_mov_b32 s23, -1
	s_mov_b32 m0, s13
	s_waitcnt vmcnt(12)
	s_barrier
	v_lshl_add_u64 v[4:5], v[192:193], 0, s[34:35]
	v_lshl_add_u64 v[34:35], v[186:187], 0, s[22:23]
	s_movk_i32 s22, 0xcf70
	global_load_lds_dwordx4 v[4:5], off
	v_lshl_add_u64 v[4:5], v[194:195], 0, s[34:35]
	s_mov_b32 m0, s14
	s_mov_b32 s23, -1
	global_load_lds_dwordx4 v[4:5], off
	v_lshl_add_u64 v[4:5], v[192:193], 0, s[36:37]
	s_mov_b32 m0, s15
	v_lshl_add_u64 v[84:85], v[186:187], 0, s[22:23]
	s_movk_i32 s22, 0xcff0
	global_load_lds_dwordx4 v[4:5], off
	v_lshl_add_u64 v[4:5], v[194:195], 0, s[36:37]
	s_mov_b32 m0, s16
	s_mov_b32 s23, -1
	global_load_lds_dwordx4 v[4:5], off
	v_addc_co_u32_e32 v33, vcc, -1, v187, vcc
	v_lshl_add_u64 v[86:87], v[186:187], 0, s[22:23]
	s_mov_b64 exec, s[100:101]
	global_load_dwordx4 v[4:7], v[32:33], off offset:-1168
	s_nop 0
	global_load_dwordx4 v[8:11], v[8:9], off offset:16
	s_nop 0
	global_load_dwordx4 v[76:79], v[32:33], off offset:-1040
	global_load_dwordx4 v[28:31], v[32:33], off offset:-144
	global_load_dwordx4 v[108:111], v[34:35], off offset:16
	s_nop 0
	global_load_dwordx4 v[32:35], v[32:33], off offset:-16
	s_nop 0
	global_load_dwordx4 v[88:91], v[84:85], off offset:16
	s_nop 0
	global_load_dwordx4 v[84:87], v[86:87], off offset:16
	s_mov_b64 exec, -1
	v_cvt_pk_bf16_f32 v16, v16, v17
	v_cvt_pk_bf16_f32 v17, v18, v19
	v_cvt_pk_bf16_f32 v18, v20, v21
	v_cvt_pk_bf16_f32 v19, v22, v23
	v_cvt_pk_bf16_f32 v68, v68, v69
	v_cvt_pk_bf16_f32 v69, v70, v71
	v_cvt_pk_bf16_f32 v70, v124, v125
	v_cvt_pk_bf16_f32 v71, v126, v127
	v_cvt_pk_bf16_f32 v164, v44, v45
	v_cvt_pk_bf16_f32 v165, v46, v47
	v_cvt_pk_bf16_f32 v166, v100, v101
	v_cvt_pk_bf16_f32 v167, v102, v103
	v_cvt_pk_bf16_f32 v100, v56, v57
	v_cvt_pk_bf16_f32 v101, v58, v59
	v_cvt_pk_bf16_f32 v102, v80, v81
	v_cvt_pk_bf16_f32 v103, v82, v83
	ds_read_b128 v[20:23], v208
	ds_read_b128 v[44:47], v208 offset:2048
	s_waitcnt lgkmcnt(0)
	v_mfma_f32_16x16x32_bf16 v[20:23], v[20:23], v[16:19], v[40:43]
	s_nop 2
	ds_read_b128 v[40:43], v208 offset:4096
	ds_read_b128 v[56:59], v208 offset:8192
	ds_read_b128 v[80:83], v208 offset:14336
	v_mfma_f32_16x16x32_bf16 v[44:47], v[44:47], v[16:19], v[52:55]
	s_nop 2
	ds_read_b128 v[52:55], v208 offset:6144
	s_waitcnt lgkmcnt(0)
	v_mfma_f32_16x16x32_bf16 v[40:43], v[40:43], v[16:19], v[64:67]
	s_nop 2
	ds_read_b128 v[64:67], v208 offset:10240
	v_mfma_f32_16x16x32_bf16 v[52:55], v[52:55], v[16:19], v[72:75]
	s_nop 2
	ds_read_b128 v[72:75], v208 offset:12288
	v_mfma_f32_16x16x32_bf16 v[56:59], v[56:59], v[16:19], v[92:95]
	s_waitcnt lgkmcnt(0)
	v_mfma_f32_16x16x32_bf16 v[64:67], v[64:67], v[16:19], v[104:107]
	v_mfma_f32_16x16x32_bf16 v[72:75], v[72:75], v[16:19], v[116:119]
	v_mfma_f32_16x16x32_bf16 v[80:83], v[80:83], v[16:19], v[120:123]
	ds_read_b128 v[16:19], v208 offset:1024
	s_waitcnt lgkmcnt(0)
	v_mfma_f32_16x16x32_bf16 v[16:19], v[16:19], v[68:71], v[20:23]
	s_nop 2
	ds_read_b128 v[20:23], v208 offset:3072
	s_waitcnt lgkmcnt(0)
	v_mfma_f32_16x16x32_bf16 v[20:23], v[20:23], v[68:71], v[44:47]
	s_nop 2
	ds_read_b128 v[44:47], v208 offset:5120
	s_waitcnt lgkmcnt(0)
	v_mfma_f32_16x16x32_bf16 v[40:43], v[44:47], v[68:71], v[40:43]
	ds_read_b128 v[44:47], v208 offset:7168
	s_waitcnt lgkmcnt(0)
	v_mfma_f32_16x16x32_bf16 v[44:47], v[44:47], v[68:71], v[52:55]
	s_nop 2
	ds_read_b128 v[52:55], v208 offset:9216
	s_waitcnt lgkmcnt(0)
	v_mfma_f32_16x16x32_bf16 v[52:55], v[52:55], v[68:71], v[56:59]
	s_nop 2
	ds_read_b128 v[56:59], v208 offset:11264
	s_waitcnt lgkmcnt(0)
	v_mfma_f32_16x16x32_bf16 v[56:59], v[56:59], v[68:71], v[64:67]
	s_nop 2
	ds_read_b128 v[64:67], v208 offset:13312
	s_waitcnt lgkmcnt(0)
	v_mfma_f32_16x16x32_bf16 v[64:67], v[64:67], v[68:71], v[72:75]
	s_nop 2
	ds_read_b128 v[72:75], v208 offset:15360
	s_waitcnt lgkmcnt(0)
	v_mfma_f32_16x16x32_bf16 v[124:127], v[72:75], v[68:71], v[80:83]
	ds_read_b128 v[68:71], v207
	ds_read_b128 v[72:75], v207 offset:2048
	s_nop 0
	ds_read_b128 v[80:83], v207 offset:4096
	ds_read_b128 v[92:95], v207 offset:6144
	ds_read_b128 v[104:107], v207 offset:8192
	ds_read_b128 v[116:119], v207 offset:10240
	ds_read_b128 v[120:123], v207 offset:12288
	s_waitcnt lgkmcnt(0)
	v_mfma_f32_16x16x32_bf16 v[68:71], v[68:71], v[164:167], v[132:135]
	s_nop 2
	ds_read_b128 v[132:135], v207 offset:14336
	v_mfma_f32_16x16x32_bf16 v[72:75], v[72:75], v[164:167], v[136:139]
	v_mfma_f32_16x16x32_bf16 v[80:83], v[80:83], v[164:167], v[140:143]
	v_mfma_f32_16x16x32_bf16 v[92:95], v[92:95], v[164:167], v[144:147]
	v_mfma_f32_16x16x32_bf16 v[104:107], v[104:107], v[164:167], v[148:151]
	v_mfma_f32_16x16x32_bf16 v[116:119], v[116:119], v[164:167], v[152:155]
	v_mfma_f32_16x16x32_bf16 v[120:123], v[120:123], v[164:167], v[156:159]
	s_waitcnt lgkmcnt(0)
	v_mfma_f32_16x16x32_bf16 v[160:163], v[132:135], v[164:167], v[160:163]
	ds_read_b128 v[132:135], v207 offset:1024
	s_waitcnt lgkmcnt(0)
	v_mfma_f32_16x16x32_bf16 v[132:135], v[132:135], v[100:103], v[68:71]
	s_nop 2
	ds_read_b128 v[68:71], v207 offset:3072
	s_waitcnt lgkmcnt(0)
	v_mfma_f32_16x16x32_bf16 v[136:139], v[68:71], v[100:103], v[72:75]
	ds_read_b128 v[68:71], v207 offset:5120
	s_waitcnt lgkmcnt(0)
	v_mfma_f32_16x16x32_bf16 v[140:143], v[68:71], v[100:103], v[80:83]
	ds_read_b128 v[68:71], v207 offset:7168
	s_waitcnt lgkmcnt(0)
	v_mfma_f32_16x16x32_bf16 v[144:147], v[68:71], v[100:103], v[92:95]
	ds_read_b128 v[68:71], v207 offset:9216
	s_waitcnt lgkmcnt(0)
	v_mfma_f32_16x16x32_bf16 v[148:151], v[68:71], v[100:103], v[104:107]
	ds_read_b128 v[68:71], v207 offset:11264
	s_waitcnt lgkmcnt(0)
	v_mfma_f32_16x16x32_bf16 v[152:155], v[68:71], v[100:103], v[116:119]
	ds_read_b128 v[68:71], v207 offset:13312
	s_waitcnt lgkmcnt(0)
	v_mfma_f32_16x16x32_bf16 v[156:159], v[68:71], v[100:103], v[120:123]
	ds_read_b128 v[68:71], v207 offset:15360
	s_waitcnt lgkmcnt(0)
	v_mfma_f32_16x16x32_bf16 v[160:163], v[68:71], v[100:103], v[160:163]
	s_movk_i32 s22, 0xdb70
	s_mov_b32 s23, -1
	v_lshl_add_u64 v[72:73], v[186:187], 0, s[22:23]
	s_movk_i32 s22, 0xe000
	v_add_co_u32_e32 v92, vcc, s22, v186
	s_movk_i32 s22, 0xdbf0
	s_mov_b32 s23, -1
	s_mov_b32 m0, s21
	s_waitcnt vmcnt(12)
	s_barrier
	v_lshl_add_u64 v[68:69], v[192:193], 0, s[38:39]
	v_lshl_add_u64 v[94:95], v[186:187], 0, s[22:23]
	s_movk_i32 s22, 0xdf70
	global_load_lds_dwordx4 v[68:69], off
	v_lshl_add_u64 v[68:69], v[194:195], 0, s[38:39]
	s_mov_b32 m0, s20
	s_mov_b32 s23, -1
	global_load_lds_dwordx4 v[68:69], off
	v_lshl_add_u64 v[68:69], v[192:193], 0, s[40:41]
	s_mov_b32 m0, s18
	v_lshl_add_u64 v[104:105], v[186:187], 0, s[22:23]
	s_movk_i32 s22, 0xdff0
	global_load_lds_dwordx4 v[68:69], off
	v_lshl_add_u64 v[68:69], v[194:195], 0, s[40:41]
	s_mov_b32 m0, s19
	s_mov_b32 s23, -1
	global_load_lds_dwordx4 v[68:69], off
	v_addc_co_u32_e32 v93, vcc, -1, v187, vcc
	v_lshl_add_u64 v[106:107], v[186:187], 0, s[22:23]
	s_mov_b64 exec, s[100:101]
	global_load_dwordx4 v[68:71], v[92:93], off offset:-1168
	s_nop 0
	global_load_dwordx4 v[72:75], v[72:73], off offset:16
	s_nop 0
	global_load_dwordx4 v[100:103], v[92:93], off offset:-1040
	global_load_dwordx4 v[80:83], v[92:93], off offset:-144
	global_load_dwordx4 v[120:123], v[94:95], off offset:16
	s_nop 0
	global_load_dwordx4 v[92:95], v[92:93], off offset:-16
	s_nop 0
	global_load_dwordx4 v[116:119], v[104:105], off offset:16
	s_nop 0
	global_load_dwordx4 v[104:107], v[106:107], off offset:16
	s_mov_b64 exec, -1
	v_cvt_pk_bf16_f32 v12, v12, v13
	v_cvt_pk_bf16_f32 v13, v14, v15
	v_cvt_pk_bf16_f32 v14, v24, v25
	v_cvt_pk_bf16_f32 v15, v26, v27
	v_cvt_pk_bf16_f32 v60, v60, v61
	v_cvt_pk_bf16_f32 v61, v62, v63
	v_cvt_pk_bf16_f32 v62, v128, v129
	v_cvt_pk_bf16_f32 v63, v130, v131
	v_cvt_pk_bf16_f32 v36, v36, v37
	v_cvt_pk_bf16_f32 v37, v38, v39
	v_cvt_pk_bf16_f32 v38, v112, v113
	v_cvt_pk_bf16_f32 v39, v114, v115
	v_cvt_pk_bf16_f32 v48, v48, v49
	v_cvt_pk_bf16_f32 v49, v50, v51
	v_cvt_pk_bf16_f32 v50, v96, v97
	v_cvt_pk_bf16_f32 v51, v98, v99
	ds_read_b128 v[24:27], v179
	ds_read_b128 v[96:99], v179 offset:2048
	s_waitcnt lgkmcnt(0)
	v_mfma_f32_16x16x32_bf16 v[16:19], v[24:27], v[12:15], v[16:19]
	ds_read_b128 v[24:27], v179 offset:4096
	v_mfma_f32_16x16x32_bf16 v[20:23], v[96:99], v[12:15], v[20:23]
	ds_read_b128 v[96:99], v179 offset:6144
	s_waitcnt lgkmcnt(0)
	v_mfma_f32_16x16x32_bf16 v[24:27], v[24:27], v[12:15], v[40:43]
	s_nop 2
	ds_read_b128 v[40:43], v179 offset:8192
	v_mfma_f32_16x16x32_bf16 v[44:47], v[96:99], v[12:15], v[44:47]
	ds_read_b128 v[96:99], v179 offset:10240
	s_waitcnt lgkmcnt(0)
	v_mfma_f32_16x16x32_bf16 v[40:43], v[40:43], v[12:15], v[52:55]
	s_nop 2
	ds_read_b128 v[52:55], v179 offset:12288
	v_mfma_f32_16x16x32_bf16 v[56:59], v[96:99], v[12:15], v[56:59]
	ds_read_b128 v[96:99], v179 offset:14336
	s_waitcnt lgkmcnt(0)
	v_mfma_f32_16x16x32_bf16 v[52:55], v[52:55], v[12:15], v[64:67]
	v_mfma_f32_16x16x32_bf16 v[64:67], v[96:99], v[12:15], v[124:127]
	ds_read_b128 v[12:15], v179 offset:1024
	s_waitcnt lgkmcnt(0)
	v_mfma_f32_16x16x32_bf16 v[12:15], v[12:15], v[60:63], v[16:19]
	s_nop 2
	ds_read_b128 v[16:19], v179 offset:3072
	s_waitcnt lgkmcnt(0)
	v_mfma_f32_16x16x32_bf16 v[16:19], v[16:19], v[60:63], v[20:23]
	s_nop 2
	ds_read_b128 v[20:23], v179 offset:5120
	s_waitcnt lgkmcnt(0)
	v_mfma_f32_16x16x32_bf16 v[20:23], v[20:23], v[60:63], v[24:27]
	s_nop 2
	ds_read_b128 v[24:27], v179 offset:7168
	s_waitcnt lgkmcnt(0)
	v_mfma_f32_16x16x32_bf16 v[24:27], v[24:27], v[60:63], v[44:47]
	s_nop 2
	ds_read_b128 v[44:47], v179 offset:9216
	s_waitcnt lgkmcnt(0)
	v_mfma_f32_16x16x32_bf16 v[96:99], v[44:47], v[60:63], v[40:43]
	s_nop 2
	ds_read_b128 v[40:43], v179 offset:11264
	s_waitcnt lgkmcnt(0)
	v_mfma_f32_16x16x32_bf16 v[112:115], v[40:43], v[60:63], v[56:59]
	ds_read_b128 v[40:43], v179 offset:13312
	s_waitcnt lgkmcnt(0)
	v_mfma_f32_16x16x32_bf16 v[124:127], v[40:43], v[60:63], v[52:55]
	ds_read_b128 v[40:43], v179 offset:15360
	s_waitcnt lgkmcnt(0)
	v_mfma_f32_16x16x32_bf16 v[128:131], v[40:43], v[60:63], v[64:67]
	ds_read_b128 v[40:43], v179 offset:16384
	ds_read_b128 v[44:47], v179 offset:18432
	ds_read_b128 v[52:55], v179 offset:20480
	ds_read_b128 v[56:59], v179 offset:22528
	ds_read_b128 v[60:63], v179 offset:24576
	ds_read_b128 v[64:67], v179 offset:26624
	s_waitcnt lgkmcnt(0)
	v_mfma_f32_16x16x32_bf16 v[40:43], v[40:43], v[36:39], v[132:135]
	s_nop 2
	ds_read_b128 v[132:135], v179 offset:28672
	v_mfma_f32_16x16x32_bf16 v[44:47], v[44:47], v[36:39], v[136:139]
	v_mfma_f32_16x16x32_bf16 v[52:55], v[52:55], v[36:39], v[140:143]
	s_waitcnt lgkmcnt(0)
	v_mfma_f32_16x16x32_bf16 v[156:159], v[132:135], v[36:39], v[156:159]
	ds_read_b128 v[132:135], v179 offset:30720
	v_mfma_f32_16x16x32_bf16 v[56:59], v[56:59], v[36:39], v[144:147]
	v_mfma_f32_16x16x32_bf16 v[60:63], v[60:63], v[36:39], v[148:151]
	v_mfma_f32_16x16x32_bf16 v[64:67], v[64:67], v[36:39], v[152:155]
	s_waitcnt lgkmcnt(0)
	v_mfma_f32_16x16x32_bf16 v[36:39], v[132:135], v[36:39], v[160:163]
	ds_read_b128 v[132:135], v179 offset:17408
	s_waitcnt lgkmcnt(0)
	v_mfma_f32_16x16x32_bf16 v[132:135], v[132:135], v[48:51], v[40:43]
	s_nop 2
	ds_read_b128 v[40:43], v179 offset:19456
	s_waitcnt lgkmcnt(0)
	v_mfma_f32_16x16x32_bf16 v[136:139], v[40:43], v[48:51], v[44:47]
	ds_read_b128 v[40:43], v179 offset:21504
	s_waitcnt lgkmcnt(0)
	v_mfma_f32_16x16x32_bf16 v[140:143], v[40:43], v[48:51], v[52:55]
	ds_read_b128 v[40:43], v179 offset:23552
	s_waitcnt lgkmcnt(0)
	v_mfma_f32_16x16x32_bf16 v[144:147], v[40:43], v[48:51], v[56:59]
	ds_read_b128 v[40:43], v179 offset:25600
	s_waitcnt lgkmcnt(0)
	v_mfma_f32_16x16x32_bf16 v[148:151], v[40:43], v[48:51], v[60:63]
	ds_read_b128 v[40:43], v179 offset:27648
	s_waitcnt lgkmcnt(0)
	v_mfma_f32_16x16x32_bf16 v[152:155], v[40:43], v[48:51], v[64:67]
	ds_read_b128 v[40:43], v179 offset:29696
	s_waitcnt lgkmcnt(0)
	v_mfma_f32_16x16x32_bf16 v[156:159], v[40:43], v[48:51], v[156:159]
	ds_read_b128 v[40:43], v179 offset:31744
	s_waitcnt lgkmcnt(0)
	v_mfma_f32_16x16x32_bf16 v[160:163], v[40:43], v[48:51], v[36:39]
	s_mov_b32 m0, s11
	s_waitcnt vmcnt(12)
	s_barrier
	v_lshl_add_u64 v[36:37], v[192:193], 0, s[44:45]
	global_load_lds_dwordx4 v[36:37], off
	v_lshl_add_u64 v[36:37], v[194:195], 0, s[44:45]
	s_mov_b32 m0, s9
	s_movk_i32 s22, 0xeb70
	global_load_lds_dwordx4 v[36:37], off
	v_lshl_add_u64 v[36:37], v[192:193], 0, s[46:47]
	s_mov_b32 m0, s8
	s_mov_b32 s23, -1
	global_load_lds_dwordx4 v[36:37], off
	v_lshl_add_u64 v[36:37], v[194:195], 0, s[46:47]
	s_mov_b32 m0, s10
	s_nop 0
	global_load_lds_dwordx4 v[36:37], off
	v_lshl_add_u64 v[36:37], v[186:187], 0, s[22:23]
	s_movk_i32 s22, 0xf000
	v_add_co_u32_e32 v38, vcc, s22, v186
	s_movk_i32 s22, 0xebf0
	s_nop 0
	v_addc_co_u32_e32 v39, vcc, -1, v187, vcc
	s_mov_b32 s23, -1
	s_mov_b64 exec, s[100:101]
	global_load_dwordx4 v[60:63], v[38:39], off offset:-1168
	global_load_dwordx4 v[44:47], v[36:37], off offset:16
	v_lshl_add_u64 v[36:37], v[186:187], 0, s[22:23]
	s_movk_i32 s22, 0xef70
	s_mov_b32 s23, -1
	v_lshl_add_u64 v[52:53], v[186:187], 0, s[22:23]
	global_load_dwordx4 v[64:67], v[38:39], off offset:-1040
	global_load_dwordx4 v[48:51], v[38:39], off offset:-144
	global_load_dwordx4 v[56:59], v[36:37], off offset:16
	global_load_dwordx4 v[40:43], v[38:39], off offset:-16
	s_nop 0
	global_load_dwordx4 v[52:55], v[52:53], off offset:16
	s_nop 0
	global_load_dwordx4 v[36:39], v[186:187], off offset:-4096
	s_mov_b64 exec, -1
	v_cvt_pk_bf16_f32 v4, v4, v5
	v_cvt_pk_bf16_f32 v5, v6, v7
	v_cvt_pk_bf16_f32 v6, v8, v9
	v_cvt_pk_bf16_f32 v7, v10, v11
	v_cvt_pk_bf16_f32 v8, v76, v77
	v_cvt_pk_bf16_f32 v9, v78, v79
	v_cvt_pk_bf16_f32 v10, v108, v109
	v_cvt_pk_bf16_f32 v11, v110, v111
	v_cvt_pk_bf16_f32 v28, v28, v29
	v_cvt_pk_bf16_f32 v29, v30, v31
	v_cvt_pk_bf16_f32 v30, v88, v89
	v_cvt_pk_bf16_f32 v31, v90, v91
	v_cvt_pk_bf16_f32 v32, v32, v33
	v_cvt_pk_bf16_f32 v33, v34, v35
	v_cvt_pk_bf16_f32 v34, v84, v85
	v_cvt_pk_bf16_f32 v35, v86, v87
	ds_read_b128 v[76:79], v179 offset:32768
	ds_read_b128 v[84:87], v179 offset:34816
	s_waitcnt lgkmcnt(0)
	v_mfma_f32_16x16x32_bf16 v[12:15], v[76:79], v[4:7], v[12:15]
	ds_read_b128 v[76:79], v179 offset:36864
	v_mfma_f32_16x16x32_bf16 v[16:19], v[84:87], v[4:7], v[16:19]
	ds_read_b128 v[84:87], v179 offset:38912
	s_waitcnt lgkmcnt(0)
	v_mfma_f32_16x16x32_bf16 v[20:23], v[76:79], v[4:7], v[20:23]
	ds_read_b128 v[76:79], v179 offset:40960
	v_mfma_f32_16x16x32_bf16 v[24:27], v[84:87], v[4:7], v[24:27]
	ds_read_b128 v[84:87], v179 offset:43008
	s_waitcnt lgkmcnt(0)
	v_mfma_f32_16x16x32_bf16 v[108:111], v[76:79], v[4:7], v[96:99]
	ds_read_b128 v[76:79], v179 offset:45056
	v_mfma_f32_16x16x32_bf16 v[112:115], v[84:87], v[4:7], v[112:115]
	ds_read_b128 v[84:87], v179 offset:47104
	s_waitcnt lgkmcnt(0)
	v_mfma_f32_16x16x32_bf16 v[124:127], v[76:79], v[4:7], v[124:127]
	v_mfma_f32_16x16x32_bf16 v[4:7], v[84:87], v[4:7], v[128:131]
	ds_read_b128 v[76:79], v179 offset:33792
	s_waitcnt lgkmcnt(0)
	v_mfma_f32_16x16x32_bf16 v[76:79], v[76:79], v[8:11], v[12:15]
	s_nop 2
	ds_read_b128 v[12:15], v179 offset:35840
	s_waitcnt lgkmcnt(0)
	v_mfma_f32_16x16x32_bf16 v[84:87], v[12:15], v[8:11], v[16:19]
	ds_read_b128 v[12:15], v179 offset:37888
	s_waitcnt lgkmcnt(0)
	v_mfma_f32_16x16x32_bf16 v[88:91], v[12:15], v[8:11], v[20:23]
	ds_read_b128 v[12:15], v179 offset:39936
	s_waitcnt lgkmcnt(0)
	v_mfma_f32_16x16x32_bf16 v[96:99], v[12:15], v[8:11], v[24:27]
	ds_read_b128 v[12:15], v179 offset:41984
	s_waitcnt lgkmcnt(0)
	v_mfma_f32_16x16x32_bf16 v[108:111], v[12:15], v[8:11], v[108:111]
	ds_read_b128 v[12:15], v179 offset:44032
	s_waitcnt lgkmcnt(0)
	v_mfma_f32_16x16x32_bf16 v[112:115], v[12:15], v[8:11], v[112:115]
	ds_read_b128 v[12:15], v179 offset:46080
	s_waitcnt lgkmcnt(0)
	v_mfma_f32_16x16x32_bf16 v[124:127], v[12:15], v[8:11], v[124:127]
	ds_read_b128 v[12:15], v179 offset:48128
	s_waitcnt lgkmcnt(0)
	v_mfma_f32_16x16x32_bf16 v[128:131], v[12:15], v[8:11], v[4:7]
	s_nop 2
	ds_read_b128 v[4:7], v179 offset:49152
	ds_read_b128 v[8:11], v179 offset:51200
	ds_read_b128 v[12:15], v179 offset:53248
	ds_read_b128 v[16:19], v179 offset:55296
	ds_read_b128 v[20:23], v179 offset:57344
	ds_read_b128 v[24:27], v179 offset:59392
	s_waitcnt lgkmcnt(0)
	v_mfma_f32_16x16x32_bf16 v[4:7], v[4:7], v[28:31], v[132:135]
	s_nop 2
	ds_read_b128 v[132:135], v179 offset:61440
	v_mfma_f32_16x16x32_bf16 v[8:11], v[8:11], v[28:31], v[136:139]
	s_nop 2
	ds_read_b128 v[136:139], v179 offset:63488
	v_mfma_f32_16x16x32_bf16 v[12:15], v[12:15], v[28:31], v[140:143]
	v_mfma_f32_16x16x32_bf16 v[16:19], v[16:19], v[28:31], v[144:147]
	v_mfma_f32_16x16x32_bf16 v[20:23], v[20:23], v[28:31], v[148:151]
	v_mfma_f32_16x16x32_bf16 v[24:27], v[24:27], v[28:31], v[152:155]
	s_waitcnt lgkmcnt(0)
	v_mfma_f32_16x16x32_bf16 v[132:135], v[132:135], v[28:31], v[156:159]
	v_mfma_f32_16x16x32_bf16 v[28:31], v[136:139], v[28:31], v[160:163]
	ds_read_b128 v[136:139], v179 offset:50176
	s_waitcnt lgkmcnt(0)
	v_mfma_f32_16x16x32_bf16 v[136:139], v[136:139], v[32:35], v[4:7]
	s_nop 2
	ds_read_b128 v[4:7], v179 offset:52224
	s_waitcnt lgkmcnt(0)
	v_mfma_f32_16x16x32_bf16 v[140:143], v[4:7], v[32:35], v[8:11]
	ds_read_b128 v[4:7], v179 offset:54272
	s_waitcnt lgkmcnt(0)
	v_mfma_f32_16x16x32_bf16 v[144:147], v[4:7], v[32:35], v[12:15]
	ds_read_b128 v[4:7], v179 offset:56320
	s_waitcnt lgkmcnt(0)
	v_mfma_f32_16x16x32_bf16 v[148:151], v[4:7], v[32:35], v[16:19]
	ds_read_b128 v[4:7], v179 offset:58368
	s_waitcnt lgkmcnt(0)
	v_mfma_f32_16x16x32_bf16 v[152:155], v[4:7], v[32:35], v[20:23]
	ds_read_b128 v[4:7], v179 offset:60416
	s_waitcnt lgkmcnt(0)
	v_mfma_f32_16x16x32_bf16 v[156:159], v[4:7], v[32:35], v[24:27]
	ds_read_b128 v[4:7], v179 offset:62464
	s_waitcnt lgkmcnt(0)
	v_mfma_f32_16x16x32_bf16 v[132:135], v[4:7], v[32:35], v[132:135]
	ds_read_b128 v[4:7], v179 offset:64512
	s_waitcnt lgkmcnt(0)
	v_mfma_f32_16x16x32_bf16 v[160:163], v[4:7], v[32:35], v[28:31]
	s_mov_b32 m0, s13
	s_waitcnt vmcnt(12)
	s_barrier
	v_lshl_add_u64 v[4:5], v[192:193], 0, s[48:49]
	global_load_lds_dwordx4 v[4:5], off
	v_lshl_add_u64 v[4:5], v[194:195], 0, s[48:49]
	s_mov_b32 m0, s14
	s_nop 0
	global_load_lds_dwordx4 v[4:5], off
	v_lshl_add_u64 v[4:5], v[192:193], 0, s[50:51]
	s_mov_b32 m0, s15
	s_nop 0
	global_load_lds_dwordx4 v[4:5], off
	v_lshl_add_u64 v[4:5], v[194:195], 0, s[50:51]
	s_mov_b32 m0, s16
	s_nop 0
	global_load_lds_dwordx4 v[4:5], off
	s_mov_b64 exec, s[100:101]
	global_load_dwordx4 v[12:15], v[186:187], off offset:-1152
	global_load_dwordx4 v[24:27], v[186:187], off offset:-1168
	global_load_dwordx4 v[32:35], v[186:187], off offset:-1024
	global_load_dwordx4 v[28:31], v[186:187], off offset:-1040
	global_load_dwordx4 v[20:23], v[186:187], off offset:-128
	global_load_dwordx4 v[16:19], v[186:187], off offset:-144
	global_load_dwordx4 v[4:7], v[186:187], off
	global_load_dwordx4 v[8:11], v[186:187], off offset:-16
	s_mov_b64 exec, -1
	v_cvt_pk_bf16_f32 v68, v68, v69
	v_cvt_pk_bf16_f32 v69, v70, v71
	v_cvt_pk_bf16_f32 v70, v72, v73
	v_cvt_pk_bf16_f32 v71, v74, v75
	v_cvt_pk_bf16_f32 v72, v100, v101
	v_cvt_pk_bf16_f32 v73, v102, v103
	v_cvt_pk_bf16_f32 v74, v120, v121
	v_cvt_pk_bf16_f32 v75, v122, v123
	v_cvt_pk_bf16_f32 v80, v80, v81
	v_cvt_pk_bf16_f32 v81, v82, v83
	v_cvt_pk_bf16_f32 v82, v116, v117
	v_cvt_pk_bf16_f32 v83, v118, v119
	v_cvt_pk_bf16_f32 v164, v92, v93
	v_cvt_pk_bf16_f32 v165, v94, v95
	v_cvt_pk_bf16_f32 v166, v104, v105
	v_cvt_pk_bf16_f32 v167, v106, v107
	ds_read_b128 v[92:95], v208
	ds_read_b128 v[100:103], v208 offset:2048
	s_waitcnt lgkmcnt(0)
	v_mfma_f32_16x16x32_bf16 v[76:79], v[92:95], v[68:71], v[76:79]
	ds_read_b128 v[92:95], v208 offset:4096
	ds_read_b128 v[104:107], v208 offset:12288
	v_mfma_f32_16x16x32_bf16 v[84:87], v[100:103], v[68:71], v[84:87]
	ds_read_b128 v[100:103], v208 offset:6144
	s_waitcnt lgkmcnt(0)
	v_mfma_f32_16x16x32_bf16 v[88:91], v[92:95], v[68:71], v[88:91]
	ds_read_b128 v[92:95], v208 offset:8192
	v_mfma_f32_16x16x32_bf16 v[96:99], v[100:103], v[68:71], v[96:99]
	ds_read_b128 v[100:103], v208 offset:10240
	s_waitcnt lgkmcnt(0)
	v_mfma_f32_16x16x32_bf16 v[120:123], v[100:103], v[68:71], v[112:115]
	ds_read_b128 v[100:103], v208 offset:14336
	v_mfma_f32_16x16x32_bf16 v[92:95], v[92:95], v[68:71], v[108:111]
	v_mfma_f32_16x16x32_bf16 v[124:127], v[104:107], v[68:71], v[124:127]
	s_waitcnt lgkmcnt(0)
	v_mfma_f32_16x16x32_bf16 v[68:71], v[100:103], v[68:71], v[128:131]
	ds_read_b128 v[100:103], v208 offset:1024
	s_waitcnt lgkmcnt(0)
	v_mfma_f32_16x16x32_bf16 v[100:103], v[100:103], v[72:75], v[76:79]
	s_nop 2
	ds_read_b128 v[76:79], v208 offset:3072
	s_waitcnt lgkmcnt(0)
	v_mfma_f32_16x16x32_bf16 v[104:107], v[76:79], v[72:75], v[84:87]
	ds_read_b128 v[76:79], v208 offset:5120
	s_waitcnt lgkmcnt(0)
	v_mfma_f32_16x16x32_bf16 v[108:111], v[76:79], v[72:75], v[88:91]
	ds_read_b128 v[76:79], v208 offset:7168
	s_waitcnt lgkmcnt(0)
	v_mfma_f32_16x16x32_bf16 v[112:115], v[76:79], v[72:75], v[96:99]
	ds_read_b128 v[76:79], v208 offset:9216
	s_waitcnt lgkmcnt(0)
	v_mfma_f32_16x16x32_bf16 v[116:119], v[76:79], v[72:75], v[92:95]
	ds_read_b128 v[76:79], v208 offset:11264
	s_waitcnt lgkmcnt(0)
	v_mfma_f32_16x16x32_bf16 v[120:123], v[76:79], v[72:75], v[120:123]
	ds_read_b128 v[76:79], v208 offset:13312
	s_waitcnt lgkmcnt(0)
	v_mfma_f32_16x16x32_bf16 v[124:127], v[76:79], v[72:75], v[124:127]
	ds_read_b128 v[76:79], v208 offset:15360
	s_waitcnt lgkmcnt(0)
	v_mfma_f32_16x16x32_bf16 v[128:131], v[76:79], v[72:75], v[68:71]
	s_nop 2
	ds_read_b128 v[68:71], v207
	ds_read_b128 v[72:75], v207 offset:2048
	ds_read_b128 v[88:91], v207 offset:8192
	ds_read_b128 v[76:79], v207 offset:4096
	ds_read_b128 v[84:87], v207 offset:6144
	s_waitcnt lgkmcnt(0)
	v_mfma_f32_16x16x32_bf16 v[68:71], v[68:71], v[80:83], v[136:139]
	v_mfma_f32_16x16x32_bf16 v[136:139], v[88:91], v[80:83], v[152:155]
	ds_read_b128 v[88:91], v207 offset:10240
	v_mfma_f32_16x16x32_bf16 v[72:75], v[72:75], v[80:83], v[140:143]
	s_waitcnt lgkmcnt(0)
	v_mfma_f32_16x16x32_bf16 v[140:143], v[88:91], v[80:83], v[156:159]
	ds_read_b128 v[88:91], v207 offset:12288
	s_waitcnt lgkmcnt(0)
	v_mfma_f32_16x16x32_bf16 v[132:135], v[88:91], v[80:83], v[132:135]
	ds_read_b128 v[88:91], v207 offset:14336
	v_mfma_f32_16x16x32_bf16 v[76:79], v[76:79], v[80:83], v[144:147]
	v_mfma_f32_16x16x32_bf16 v[84:87], v[84:87], v[80:83], v[148:151]
	s_waitcnt lgkmcnt(0)
	v_mfma_f32_16x16x32_bf16 v[144:147], v[88:91], v[80:83], v[160:163]
	ds_read_b128 v[80:83], v207 offset:1024
	s_waitcnt lgkmcnt(0)
	v_mfma_f32_16x16x32_bf16 v[96:99], v[80:83], v[164:167], v[68:71]
	s_nop 2
	ds_read_b128 v[68:71], v207 offset:3072
	s_waitcnt lgkmcnt(0)
	v_mfma_f32_16x16x32_bf16 v[92:95], v[68:71], v[164:167], v[72:75]
	ds_read_b128 v[68:71], v207 offset:5120
	s_waitcnt lgkmcnt(0)
	v_mfma_f32_16x16x32_bf16 v[88:91], v[68:71], v[164:167], v[76:79]
	ds_read_b128 v[68:71], v207 offset:7168
	s_waitcnt lgkmcnt(0)
	v_mfma_f32_16x16x32_bf16 v[84:87], v[68:71], v[164:167], v[84:87]
	ds_read_b128 v[68:71], v207 offset:9216
	s_waitcnt lgkmcnt(0)
	v_mfma_f32_16x16x32_bf16 v[80:83], v[68:71], v[164:167], v[136:139]
	ds_read_b128 v[68:71], v207 offset:11264
	s_waitcnt lgkmcnt(0)
	v_mfma_f32_16x16x32_bf16 v[76:79], v[68:71], v[164:167], v[140:143]
	ds_read_b128 v[68:71], v207 offset:13312
	s_waitcnt lgkmcnt(0)
	v_mfma_f32_16x16x32_bf16 v[72:75], v[68:71], v[164:167], v[132:135]
	ds_read_b128 v[68:71], v207 offset:15360
	s_waitcnt lgkmcnt(0)
	v_mfma_f32_16x16x32_bf16 v[68:71], v[68:71], v[164:167], v[144:147]
	s_add_i32 s17, s17, 12
	s_add_u32 s0, s0, 0x600
	s_addc_u32 s1, s1, 0
	s_mov_b64 s[22:23], 0xc000
	s_cmp_gt_u32 s17, 47
	v_lshl_add_u64 v[186:187], v[186:187], 0, s[22:23]
	s_cbranch_scc0 .LBB0_564
	s_add_u32 s0, s6, 0x9301f00
	s_addc_u32 s1, s7, 0
	s_mov_b32 m0, s21
	s_waitcnt vmcnt(12)
	s_barrier
	v_lshl_add_u64 v[132:133], s[0:1], 0, v[2:3]
	global_load_lds_dwordx4 v[132:133], off
	v_lshl_add_u64 v[132:133], s[0:1], 0, v[184:185]
	s_add_u32 s0, s6, 0x9401f00
	s_mov_b32 m0, s20
	s_addc_u32 s1, s7, 0
	global_load_lds_dwordx4 v[132:133], off
	v_lshl_add_u64 v[132:133], s[0:1], 0, v[2:3]
	s_mov_b32 m0, s18
	s_nop 0
	global_load_lds_dwordx4 v[132:133], off
	v_lshl_add_u64 v[132:133], s[0:1], 0, v[184:185]
	s_mov_b32 m0, s19
	s_mov_b64 s[0:1], 0x3e000
	global_load_lds_dwordx4 v[132:133], off
	v_lshl_add_u64 v[132:133], v[182:183], 0, s[0:1]
	s_mov_b32 s0, 0x3e000
	v_add_co_u32_e32 v148, vcc, s0, v182
	s_mov_b32 s0, 0x3f000
	s_nop 0
	v_addc_co_u32_e32 v149, vcc, 0, v183, vcc
	v_add_co_u32_e32 v164, vcc, s0, v182
	s_mov_b64 s[0:1], 0x3e080
	v_lshl_add_u64 v[140:141], v[182:183], 0, s[0:1]
	s_mov_b64 s[0:1], 0x3e400
	v_lshl_add_u64 v[142:143], v[182:183], 0, s[0:1]
	s_mov_b64 s[0:1], 0x3e480
	v_lshl_add_u64 v[152:153], v[182:183], 0, s[0:1]
	v_addc_co_u32_e32 v165, vcc, 0, v183, vcc
	s_mov_b64 exec, s[100:101]
	global_load_dwordx4 v[136:139], v[132:133], off offset:16
	s_nop 0
	global_load_dwordx4 v[132:135], v[148:149], off offset:128
	global_load_dwordx4 v[144:147], v[140:141], off offset:16
	s_nop 0
	global_load_dwordx4 v[140:143], v[142:143], off offset:16
	s_nop 0
	global_load_dwordx4 v[156:159], v[148:149], off offset:1024
	s_nop 0
	global_load_dwordx4 v[148:151], v[148:149], off offset:1152
	s_nop 0
	global_load_dwordx4 v[160:163], v[164:165], off offset:-4096
	s_nop 0
	global_load_dwordx4 v[152:155], v[152:153], off offset:16
	s_mov_b64 exec, -1
	v_cvt_pk_bf16_f32 v60, v60, v61
	v_cvt_pk_bf16_f32 v61, v62, v63
	v_cvt_pk_bf16_f32 v62, v44, v45
	v_cvt_pk_bf16_f32 v63, v46, v47
	v_cvt_pk_bf16_f32 v44, v64, v65
	v_cvt_pk_bf16_f32 v45, v66, v67
	v_cvt_pk_bf16_f32 v46, v56, v57
	v_cvt_pk_bf16_f32 v47, v58, v59
	v_cvt_pk_bf16_f32 v48, v48, v49
	v_cvt_pk_bf16_f32 v49, v50, v51
	v_cvt_pk_bf16_f32 v50, v52, v53
	v_cvt_pk_bf16_f32 v51, v54, v55
	v_cvt_pk_bf16_f32 v40, v40, v41
	v_cvt_pk_bf16_f32 v41, v42, v43
	v_cvt_pk_bf16_f32 v42, v36, v37
	v_cvt_pk_bf16_f32 v43, v38, v39
	ds_read_b128 v[36:39], v179
	ds_read_b128 v[52:55], v179 offset:2048
	s_waitcnt lgkmcnt(0)
	v_mfma_f32_16x16x32_bf16 v[36:39], v[36:39], v[60:63], v[100:103]
	s_nop 2
	ds_read_b128 v[100:103], v179 offset:8192
	ds_read_b128 v[56:59], v179 offset:4096
	ds_read_b128 v[64:67], v179 offset:6144
	v_mfma_f32_16x16x32_bf16 v[52:55], v[52:55], v[60:63], v[104:107]
	s_nop 2
	ds_read_b128 v[104:107], v179 offset:10240
	s_waitcnt lgkmcnt(0)
	v_mfma_f32_16x16x32_bf16 v[116:119], v[100:103], v[60:63], v[116:119]
	ds_read_b128 v[100:103], v179 offset:12288
	v_mfma_f32_16x16x32_bf16 v[120:123], v[104:107], v[60:63], v[120:123]
	ds_read_b128 v[104:107], v179 offset:14336
	v_mfma_f32_16x16x32_bf16 v[56:59], v[56:59], v[60:63], v[108:111]
	v_mfma_f32_16x16x32_bf16 v[64:67], v[64:67], v[60:63], v[112:115]
	s_waitcnt lgkmcnt(0)
	v_mfma_f32_16x16x32_bf16 v[124:127], v[100:103], v[60:63], v[124:127]
	v_mfma_f32_16x16x32_bf16 v[60:63], v[104:107], v[60:63], v[128:131]
	ds_read_b128 v[100:103], v179 offset:1024
	s_waitcnt lgkmcnt(0)
	v_mfma_f32_16x16x32_bf16 v[100:103], v[100:103], v[44:47], v[36:39]
	s_nop 2
	ds_read_b128 v[36:39], v179 offset:3072
	s_waitcnt lgkmcnt(0)
	v_mfma_f32_16x16x32_bf16 v[104:107], v[36:39], v[44:47], v[52:55]
	ds_read_b128 v[36:39], v179 offset:5120
	s_waitcnt lgkmcnt(0)
	v_mfma_f32_16x16x32_bf16 v[108:111], v[36:39], v[44:47], v[56:59]
	ds_read_b128 v[36:39], v179 offset:7168
	s_waitcnt lgkmcnt(0)
	v_mfma_f32_16x16x32_bf16 v[112:115], v[36:39], v[44:47], v[64:67]
	ds_read_b128 v[36:39], v179 offset:9216
	s_waitcnt lgkmcnt(0)
	v_mfma_f32_16x16x32_bf16 v[116:119], v[36:39], v[44:47], v[116:119]
	ds_read_b128 v[36:39], v179 offset:11264
	s_waitcnt lgkmcnt(0)
	v_mfma_f32_16x16x32_bf16 v[120:123], v[36:39], v[44:47], v[120:123]
	ds_read_b128 v[36:39], v179 offset:13312
	s_waitcnt lgkmcnt(0)
	v_mfma_f32_16x16x32_bf16 v[124:127], v[36:39], v[44:47], v[124:127]
	ds_read_b128 v[36:39], v179 offset:15360
	s_waitcnt lgkmcnt(0)
	v_mfma_f32_16x16x32_bf16 v[128:131], v[36:39], v[44:47], v[60:63]
	s_nop 2
	ds_read_b128 v[60:63], v179 offset:24576
	ds_read_b128 v[64:67], v179 offset:26624
	ds_read_b128 v[36:39], v179 offset:16384
	ds_read_b128 v[44:47], v179 offset:18432
	ds_read_b128 v[52:55], v179 offset:20480
	ds_read_b128 v[56:59], v179 offset:22528
	s_waitcnt lgkmcnt(0)
	v_mfma_f32_16x16x32_bf16 v[64:67], v[64:67], v[48:51], v[76:79]
	s_nop 2
	ds_read_b128 v[76:79], v179 offset:28672
	v_mfma_f32_16x16x32_bf16 v[44:47], v[44:47], v[48:51], v[92:95]
	s_waitcnt lgkmcnt(0)
	v_mfma_f32_16x16x32_bf16 v[92:95], v[76:79], v[48:51], v[72:75]
	s_nop 2
	ds_read_b128 v[72:75], v179 offset:30720
	v_mfma_f32_16x16x32_bf16 v[36:39], v[36:39], v[48:51], v[96:99]
	v_mfma_f32_16x16x32_bf16 v[52:55], v[52:55], v[48:51], v[88:91]
	v_mfma_f32_16x16x32_bf16 v[56:59], v[56:59], v[48:51], v[84:87]
	v_mfma_f32_16x16x32_bf16 v[60:63], v[60:63], v[48:51], v[80:83]
	s_waitcnt lgkmcnt(0)
	v_mfma_f32_16x16x32_bf16 v[48:51], v[72:75], v[48:51], v[68:71]
	s_nop 2
	ds_read_b128 v[68:71], v179 offset:17408
	s_waitcnt lgkmcnt(0)
	v_mfma_f32_16x16x32_bf16 v[68:71], v[68:71], v[40:43], v[36:39]
	s_nop 2
	ds_read_b128 v[36:39], v179 offset:19456
	s_waitcnt lgkmcnt(0)
	v_mfma_f32_16x16x32_bf16 v[72:75], v[36:39], v[40:43], v[44:47]
	ds_read_b128 v[36:39], v179 offset:21504
	s_waitcnt lgkmcnt(0)
	v_mfma_f32_16x16x32_bf16 v[76:79], v[36:39], v[40:43], v[52:55]
	ds_read_b128 v[36:39], v179 offset:23552
	s_waitcnt lgkmcnt(0)
	v_mfma_f32_16x16x32_bf16 v[80:83], v[36:39], v[40:43], v[56:59]
	ds_read_b128 v[36:39], v179 offset:25600
	s_waitcnt lgkmcnt(0)
	v_mfma_f32_16x16x32_bf16 v[84:87], v[36:39], v[40:43], v[60:63]
	ds_read_b128 v[36:39], v179 offset:27648
	s_waitcnt lgkmcnt(0)
	v_mfma_f32_16x16x32_bf16 v[88:91], v[36:39], v[40:43], v[64:67]
	ds_read_b128 v[36:39], v179 offset:29696
	s_waitcnt lgkmcnt(0)
	v_mfma_f32_16x16x32_bf16 v[92:95], v[36:39], v[40:43], v[92:95]
	ds_read_b128 v[36:39], v179 offset:31744
	s_waitcnt lgkmcnt(0)
	v_mfma_f32_16x16x32_bf16 v[96:99], v[36:39], v[40:43], v[48:51]
	s_add_u32 s0, s6, 0x9301f80
	s_addc_u32 s1, s7, 0
	s_mov_b32 m0, s11
	s_waitcnt vmcnt(12)
	s_barrier
	v_lshl_add_u64 v[36:37], s[0:1], 0, v[2:3]
	global_load_lds_dwordx4 v[36:37], off
	v_lshl_add_u64 v[36:37], s[0:1], 0, v[184:185]
	s_add_u32 s0, s6, 0x9401f80
	s_mov_b32 m0, s9
	s_addc_u32 s1, s7, 0
	global_load_lds_dwordx4 v[36:37], off
	v_lshl_add_u64 v[36:37], s[0:1], 0, v[2:3]
	s_mov_b32 m0, s8
	s_nop 0
	global_load_lds_dwordx4 v[36:37], off
	v_lshl_add_u64 v[36:37], s[0:1], 0, v[184:185]
	s_mov_b64 s[0:1], 0x3f000
	v_lshl_add_u64 v[40:41], v[182:183], 0, s[0:1]
	s_mov_b64 s[0:1], 0x3f080
	v_lshl_add_u64 v[42:43], v[182:183], 0, s[0:1]
	s_mov_b64 s[0:1], 0x3f400
	s_mov_b32 m0, s10
	v_lshl_add_u64 v[56:57], v[182:183], 0, s[0:1]
	s_mov_b64 s[0:1], 0x3f480
	global_load_lds_dwordx4 v[36:37], off
	v_lshl_add_u64 v[58:59], v[182:183], 0, s[0:1]
	s_mov_b64 exec, s[100:101]
	global_load_dwordx4 v[44:47], v[164:165], off
	global_load_dwordx4 v[36:39], v[164:165], off offset:128
	global_load_dwordx4 v[48:51], v[40:41], off offset:16
	s_nop 0
	global_load_dwordx4 v[40:43], v[42:43], off offset:16
	s_nop 0
	global_load_dwordx4 v[60:63], v[164:165], off offset:1024
	global_load_dwordx4 v[52:55], v[164:165], off offset:1152
	global_load_dwordx4 v[64:67], v[56:57], off offset:16
	s_nop 0
	global_load_dwordx4 v[56:59], v[58:59], off offset:16
	s_mov_b64 exec, -1
	v_cvt_pk_bf16_f32 v24, v24, v25
	v_cvt_pk_bf16_f32 v25, v26, v27
	v_cvt_pk_bf16_f32 v26, v12, v13
	v_cvt_pk_bf16_f32 v27, v14, v15
	v_cvt_pk_bf16_f32 v12, v28, v29
	v_cvt_pk_bf16_f32 v13, v30, v31
	v_cvt_pk_bf16_f32 v14, v32, v33
	v_cvt_pk_bf16_f32 v15, v34, v35
	v_cvt_pk_bf16_f32 v16, v16, v17
	v_cvt_pk_bf16_f32 v17, v18, v19
	v_cvt_pk_bf16_f32 v18, v20, v21
	v_cvt_pk_bf16_f32 v19, v22, v23
	v_cvt_pk_bf16_f32 v8, v8, v9
	v_cvt_pk_bf16_f32 v9, v10, v11
	v_cvt_pk_bf16_f32 v10, v4, v5
	v_cvt_pk_bf16_f32 v11, v6, v7
	ds_read_b128 v[4:7], v179 offset:32768
	ds_read_b128 v[20:23], v179 offset:34816
	ds_read_b128 v[28:31], v179 offset:36864
	ds_read_b128 v[32:35], v179 offset:38912
	s_waitcnt lgkmcnt(0)
	v_mfma_f32_16x16x32_bf16 v[4:7], v[4:7], v[24:27], v[100:103]
	s_nop 2
	ds_read_b128 v[100:103], v179 offset:40960
	v_mfma_f32_16x16x32_bf16 v[20:23], v[20:23], v[24:27], v[104:107]
	v_mfma_f32_16x16x32_bf16 v[28:31], v[28:31], v[24:27], v[108:111]
	s_nop 1
	ds_read_b128 v[104:107], v179 offset:43008
	v_mfma_f32_16x16x32_bf16 v[32:35], v[32:35], v[24:27], v[112:115]
	ds_read_b128 v[108:111], v179 offset:45056
	s_nop 1
	ds_read_b128 v[112:115], v179 offset:47104
	s_waitcnt lgkmcnt(0)
	v_mfma_f32_16x16x32_bf16 v[100:103], v[100:103], v[24:27], v[116:119]
	v_mfma_f32_16x16x32_bf16 v[104:107], v[104:107], v[24:27], v[120:123]
	v_mfma_f32_16x16x32_bf16 v[108:111], v[108:111], v[24:27], v[124:127]
	v_mfma_f32_16x16x32_bf16 v[24:27], v[112:115], v[24:27], v[128:131]
	ds_read_b128 v[112:115], v179 offset:33792
	s_waitcnt lgkmcnt(0)
	v_mfma_f32_16x16x32_bf16 v[4:7], v[112:115], v[12:15], v[4:7]
	ds_read_b128 v[112:115], v179 offset:35840
	s_waitcnt lgkmcnt(0)
	v_mfma_f32_16x16x32_bf16 v[20:23], v[112:115], v[12:15], v[20:23]
	ds_read_b128 v[112:115], v179 offset:37888
	s_waitcnt lgkmcnt(0)
	v_mfma_f32_16x16x32_bf16 v[28:31], v[112:115], v[12:15], v[28:31]
	ds_read_b128 v[112:115], v179 offset:39936
	s_waitcnt lgkmcnt(0)
	v_mfma_f32_16x16x32_bf16 v[32:35], v[112:115], v[12:15], v[32:35]
	ds_read_b128 v[112:115], v179 offset:41984
	s_waitcnt lgkmcnt(0)
	v_mfma_f32_16x16x32_bf16 v[100:103], v[112:115], v[12:15], v[100:103]
	ds_read_b128 v[112:115], v179 offset:44032
	s_waitcnt lgkmcnt(0)
	v_mfma_f32_16x16x32_bf16 v[104:107], v[112:115], v[12:15], v[104:107]
	ds_read_b128 v[112:115], v179 offset:46080
	s_waitcnt lgkmcnt(0)
	v_mfma_f32_16x16x32_bf16 v[108:111], v[112:115], v[12:15], v[108:111]
	ds_read_b128 v[112:115], v179 offset:48128
	s_waitcnt lgkmcnt(0)
	v_mfma_f32_16x16x32_bf16 v[12:15], v[112:115], v[12:15], v[24:27]
	s_nop 2
	ds_read_b128 v[24:27], v179 offset:49152
	s_waitcnt lgkmcnt(0)
	v_mfma_f32_16x16x32_bf16 v[24:27], v[24:27], v[16:19], v[68:71]
	s_nop 2
	ds_read_b128 v[68:71], v179 offset:51200
	s_waitcnt lgkmcnt(0)
	v_mfma_f32_16x16x32_bf16 v[68:71], v[68:71], v[16:19], v[72:75]
	s_nop 2
	ds_read_b128 v[72:75], v179 offset:53248
	s_waitcnt lgkmcnt(0)
	v_mfma_f32_16x16x32_bf16 v[72:75], v[72:75], v[16:19], v[76:79]
	s_nop 2
	ds_read_b128 v[76:79], v179 offset:55296
	s_waitcnt lgkmcnt(0)
	v_mfma_f32_16x16x32_bf16 v[76:79], v[76:79], v[16:19], v[80:83]
	s_nop 2
	ds_read_b128 v[80:83], v179 offset:57344
	s_waitcnt lgkmcnt(0)
	v_mfma_f32_16x16x32_bf16 v[80:83], v[80:83], v[16:19], v[84:87]
	s_nop 2
	ds_read_b128 v[84:87], v179 offset:59392
	s_waitcnt lgkmcnt(0)
	v_mfma_f32_16x16x32_bf16 v[84:87], v[84:87], v[16:19], v[88:91]
	s_nop 2
	ds_read_b128 v[88:91], v179 offset:61440
	s_waitcnt lgkmcnt(0)
	v_mfma_f32_16x16x32_bf16 v[88:91], v[88:91], v[16:19], v[92:95]
	s_nop 2
	ds_read_b128 v[92:95], v179 offset:63488
	s_waitcnt lgkmcnt(0)
	v_mfma_f32_16x16x32_bf16 v[16:19], v[92:95], v[16:19], v[96:99]
	ds_read_b128 v[92:95], v179 offset:50176
	s_waitcnt lgkmcnt(0)
	v_mfma_f32_16x16x32_bf16 v[24:27], v[92:95], v[8:11], v[24:27]
	ds_read_b128 v[92:95], v179 offset:52224
	s_waitcnt lgkmcnt(0)
	v_mfma_f32_16x16x32_bf16 v[68:71], v[92:95], v[8:11], v[68:71]
	ds_read_b128 v[92:95], v179 offset:54272
	s_waitcnt lgkmcnt(0)
	v_mfma_f32_16x16x32_bf16 v[72:75], v[92:95], v[8:11], v[72:75]
	ds_read_b128 v[92:95], v179 offset:56320
	s_waitcnt lgkmcnt(0)
	v_mfma_f32_16x16x32_bf16 v[76:79], v[92:95], v[8:11], v[76:79]
	ds_read_b128 v[92:95], v179 offset:58368
	s_waitcnt lgkmcnt(0)
	v_mfma_f32_16x16x32_bf16 v[80:83], v[92:95], v[8:11], v[80:83]
	ds_read_b128 v[92:95], v179 offset:60416
	s_waitcnt lgkmcnt(0)
	v_mfma_f32_16x16x32_bf16 v[84:87], v[92:95], v[8:11], v[84:87]
	ds_read_b128 v[92:95], v179 offset:62464
	s_waitcnt lgkmcnt(0)
	v_mfma_f32_16x16x32_bf16 v[88:91], v[92:95], v[8:11], v[88:91]
	ds_read_b128 v[92:95], v179 offset:64512
	s_waitcnt lgkmcnt(0)
	v_mfma_f32_16x16x32_bf16 v[8:11], v[92:95], v[8:11], v[16:19]
	s_waitcnt vmcnt(12)
	s_barrier
	v_cvt_pk_bf16_f32 v16, v160, v161
	v_cvt_pk_bf16_f32 v17, v162, v163
	v_cvt_pk_bf16_f32 v18, v136, v137
	v_cvt_pk_bf16_f32 v19, v138, v139
	v_cvt_pk_bf16_f32 v92, v132, v133
	v_cvt_pk_bf16_f32 v93, v134, v135
	v_cvt_pk_bf16_f32 v94, v144, v145
	v_cvt_pk_bf16_f32 v95, v146, v147
	v_cvt_pk_bf16_f32 v96, v156, v157
	v_cvt_pk_bf16_f32 v97, v158, v159
	v_cvt_pk_bf16_f32 v98, v140, v141
	v_cvt_pk_bf16_f32 v99, v142, v143
	v_cvt_pk_bf16_f32 v112, v148, v149
	v_cvt_pk_bf16_f32 v113, v150, v151
	v_cvt_pk_bf16_f32 v114, v152, v153
	v_cvt_pk_bf16_f32 v115, v154, v155
	ds_read_b128 v[116:119], v208
	ds_read_b128 v[120:123], v208 offset:2048
	s_waitcnt lgkmcnt(0)
	v_mfma_f32_16x16x32_bf16 v[4:7], v[116:119], v[16:19], v[4:7]
	ds_read_b128 v[116:119], v208 offset:4096
	v_mfma_f32_16x16x32_bf16 v[20:23], v[120:123], v[16:19], v[20:23]
	ds_read_b128 v[120:123], v208 offset:6144
	s_waitcnt lgkmcnt(0)
	v_mfma_f32_16x16x32_bf16 v[28:31], v[116:119], v[16:19], v[28:31]
	ds_read_b128 v[116:119], v208 offset:8192
	v_mfma_f32_16x16x32_bf16 v[32:35], v[120:123], v[16:19], v[32:35]
	ds_read_b128 v[120:123], v208 offset:10240
	s_waitcnt lgkmcnt(0)
	v_mfma_f32_16x16x32_bf16 v[100:103], v[116:119], v[16:19], v[100:103]
	ds_read_b128 v[116:119], v208 offset:12288
	v_mfma_f32_16x16x32_bf16 v[104:107], v[120:123], v[16:19], v[104:107]
	ds_read_b128 v[120:123], v208 offset:14336
	s_waitcnt lgkmcnt(0)
	v_mfma_f32_16x16x32_bf16 v[108:111], v[116:119], v[16:19], v[108:111]
	v_mfma_f32_16x16x32_bf16 v[12:15], v[120:123], v[16:19], v[12:15]
	ds_read_b128 v[16:19], v208 offset:1024
	s_waitcnt lgkmcnt(0)
	v_mfma_f32_16x16x32_bf16 v[4:7], v[16:19], v[92:95], v[4:7]
	ds_read_b128 v[16:19], v208 offset:3072
	s_waitcnt lgkmcnt(0)
	v_mfma_f32_16x16x32_bf16 v[16:19], v[16:19], v[92:95], v[20:23]
	s_nop 2
	ds_read_b128 v[20:23], v208 offset:5120
	s_waitcnt lgkmcnt(0)
	v_mfma_f32_16x16x32_bf16 v[20:23], v[20:23], v[92:95], v[28:31]
	s_nop 2
	ds_read_b128 v[28:31], v208 offset:7168
	s_waitcnt lgkmcnt(0)
	v_mfma_f32_16x16x32_bf16 v[28:31], v[28:31], v[92:95], v[32:35]
	s_nop 2
	ds_read_b128 v[32:35], v208 offset:9216
	s_waitcnt lgkmcnt(0)
	v_mfma_f32_16x16x32_bf16 v[32:35], v[32:35], v[92:95], v[100:103]
	s_nop 2
	ds_read_b128 v[100:103], v208 offset:11264
	s_waitcnt lgkmcnt(0)
	v_mfma_f32_16x16x32_bf16 v[100:103], v[100:103], v[92:95], v[104:107]
	s_nop 2
	ds_read_b128 v[104:107], v208 offset:13312
	s_waitcnt lgkmcnt(0)
	v_mfma_f32_16x16x32_bf16 v[104:107], v[104:107], v[92:95], v[108:111]
	s_nop 2
	ds_read_b128 v[108:111], v208 offset:15360
	s_waitcnt lgkmcnt(0)
	v_mfma_f32_16x16x32_bf16 v[12:15], v[108:111], v[92:95], v[12:15]
	ds_read_b128 v[92:95], v207
	s_waitcnt lgkmcnt(0)
	v_mfma_f32_16x16x32_bf16 v[24:27], v[92:95], v[96:99], v[24:27]
	ds_read_b128 v[92:95], v207 offset:2048
	s_waitcnt lgkmcnt(0)
	v_mfma_f32_16x16x32_bf16 v[68:71], v[92:95], v[96:99], v[68:71]
	ds_read_b128 v[92:95], v207 offset:4096
	s_waitcnt lgkmcnt(0)
	v_mfma_f32_16x16x32_bf16 v[72:75], v[92:95], v[96:99], v[72:75]
	ds_read_b128 v[92:95], v207 offset:6144
	s_waitcnt lgkmcnt(0)
	v_mfma_f32_16x16x32_bf16 v[76:79], v[92:95], v[96:99], v[76:79]
	ds_read_b128 v[92:95], v207 offset:8192
	s_waitcnt lgkmcnt(0)
	v_mfma_f32_16x16x32_bf16 v[80:83], v[92:95], v[96:99], v[80:83]
	ds_read_b128 v[92:95], v207 offset:10240
	s_waitcnt lgkmcnt(0)
	v_mfma_f32_16x16x32_bf16 v[84:87], v[92:95], v[96:99], v[84:87]
	ds_read_b128 v[92:95], v207 offset:12288
	s_waitcnt lgkmcnt(0)
	v_mfma_f32_16x16x32_bf16 v[88:91], v[92:95], v[96:99], v[88:91]
	ds_read_b128 v[92:95], v207 offset:14336
	s_waitcnt lgkmcnt(0)
	v_mfma_f32_16x16x32_bf16 v[8:11], v[92:95], v[96:99], v[8:11]
	ds_read_b128 v[92:95], v207 offset:1024
	s_waitcnt lgkmcnt(0)
	v_mfma_f32_16x16x32_bf16 v[24:27], v[92:95], v[112:115], v[24:27]
	ds_read_b128 v[92:95], v207 offset:3072
	s_waitcnt lgkmcnt(0)
	v_mfma_f32_16x16x32_bf16 v[68:71], v[92:95], v[112:115], v[68:71]
	ds_read_b128 v[92:95], v207 offset:5120
	s_waitcnt lgkmcnt(0)
	v_mfma_f32_16x16x32_bf16 v[72:75], v[92:95], v[112:115], v[72:75]
	ds_read_b128 v[92:95], v207 offset:7168
	s_waitcnt lgkmcnt(0)
	v_mfma_f32_16x16x32_bf16 v[76:79], v[92:95], v[112:115], v[76:79]
	ds_read_b128 v[92:95], v207 offset:9216
	s_waitcnt lgkmcnt(0)
	v_mfma_f32_16x16x32_bf16 v[80:83], v[92:95], v[112:115], v[80:83]
	ds_read_b128 v[92:95], v207 offset:11264
	s_waitcnt lgkmcnt(0)
	v_mfma_f32_16x16x32_bf16 v[84:87], v[92:95], v[112:115], v[84:87]
	ds_read_b128 v[92:95], v207 offset:13312
	s_waitcnt lgkmcnt(0)
	v_mfma_f32_16x16x32_bf16 v[88:91], v[92:95], v[112:115], v[88:91]
	ds_read_b128 v[92:95], v207 offset:15360
	s_waitcnt lgkmcnt(0)
	v_mfma_f32_16x16x32_bf16 v[8:11], v[92:95], v[112:115], v[8:11]
	s_waitcnt vmcnt(0)
	s_barrier
	v_cvt_pk_bf16_f32 v44, v44, v45
	v_cvt_pk_bf16_f32 v45, v46, v47
	v_cvt_pk_bf16_f32 v46, v48, v49
	v_cvt_pk_bf16_f32 v47, v50, v51
	v_cvt_pk_bf16_f32 v36, v36, v37
	v_cvt_pk_bf16_f32 v37, v38, v39
	v_cvt_pk_bf16_f32 v38, v40, v41
	v_cvt_pk_bf16_f32 v39, v42, v43
	v_cvt_pk_bf16_f32 v40, v60, v61
	v_cvt_pk_bf16_f32 v41, v62, v63
	v_cvt_pk_bf16_f32 v42, v64, v65
	v_cvt_pk_bf16_f32 v43, v66, v67
	v_cvt_pk_bf16_f32 v48, v52, v53
	v_cvt_pk_bf16_f32 v49, v54, v55
	v_cvt_pk_bf16_f32 v50, v56, v57
	v_cvt_pk_bf16_f32 v51, v58, v59
	ds_read_b128 v[52:55], v179
	ds_read_b128 v[56:59], v179 offset:2048
	s_waitcnt lgkmcnt(1)
	v_mfma_f32_16x16x32_bf16 v[4:7], v[52:55], v[44:47], v[4:7]
	ds_read_b128 v[52:55], v179 offset:4096
	ds_read_b128 v[60:63], v179 offset:14336
	s_waitcnt lgkmcnt(2)
	v_mfma_f32_16x16x32_bf16 v[16:19], v[56:59], v[44:47], v[16:19]
	ds_read_b128 v[56:59], v179 offset:6144
	s_waitcnt lgkmcnt(2)
	v_mfma_f32_16x16x32_bf16 v[20:23], v[52:55], v[44:47], v[20:23]
	ds_read_b128 v[52:55], v179 offset:8192
	s_waitcnt lgkmcnt(1)
	v_mfma_f32_16x16x32_bf16 v[28:31], v[56:59], v[44:47], v[28:31]
	ds_read_b128 v[56:59], v179 offset:10240
	s_waitcnt lgkmcnt(1)
	v_mfma_f32_16x16x32_bf16 v[32:35], v[52:55], v[44:47], v[32:35]
	ds_read_b128 v[52:55], v179 offset:12288
	s_waitcnt lgkmcnt(1)
	v_mfma_f32_16x16x32_bf16 v[56:59], v[56:59], v[44:47], v[100:103]
	s_waitcnt lgkmcnt(0)
	v_mfma_f32_16x16x32_bf16 v[52:55], v[52:55], v[44:47], v[104:107]
	v_mfma_f32_16x16x32_bf16 v[12:15], v[60:63], v[44:47], v[12:15]
	ds_read_b128 v[44:47], v179 offset:1024
	s_waitcnt lgkmcnt(0)
	v_mfma_f32_16x16x32_bf16 v[92:95], v[44:47], v[36:39], v[4:7]
	s_nop 2
	ds_read_b128 v[4:7], v179 offset:3072
	s_waitcnt lgkmcnt(0)
	v_mfma_f32_16x16x32_bf16 v[96:99], v[4:7], v[36:39], v[16:19]
	ds_read_b128 v[4:7], v179 offset:5120
	s_waitcnt lgkmcnt(0)
	v_mfma_f32_16x16x32_bf16 v[100:103], v[4:7], v[36:39], v[20:23]
	ds_read_b128 v[4:7], v179 offset:7168
	s_waitcnt lgkmcnt(0)
	v_mfma_f32_16x16x32_bf16 v[104:107], v[4:7], v[36:39], v[28:31]
	ds_read_b128 v[4:7], v179 offset:9216
	s_waitcnt lgkmcnt(0)
	v_mfma_f32_16x16x32_bf16 v[108:111], v[4:7], v[36:39], v[32:35]
	ds_read_b128 v[4:7], v179 offset:11264
	s_waitcnt lgkmcnt(0)
	v_mfma_f32_16x16x32_bf16 v[112:115], v[4:7], v[36:39], v[56:59]
	ds_read_b128 v[4:7], v179 offset:13312
	s_waitcnt lgkmcnt(0)
	v_mfma_f32_16x16x32_bf16 v[116:119], v[4:7], v[36:39], v[52:55]
	ds_read_b128 v[4:7], v179 offset:15360
	s_waitcnt lgkmcnt(0)
	v_mfma_f32_16x16x32_bf16 v[120:123], v[4:7], v[36:39], v[12:15]
	ds_read_b128 v[16:19], v179 offset:20480
	ds_read_b128 v[4:7], v179 offset:16384
	s_nop 0
	ds_read_b128 v[12:15], v179 offset:18432
	s_waitcnt lgkmcnt(2)
	v_mfma_f32_16x16x32_bf16 v[20:23], v[16:19], v[40:43], v[72:75]
	ds_read_b128 v[16:19], v179 offset:22528
	s_waitcnt lgkmcnt(2)
	v_mfma_f32_16x16x32_bf16 v[4:7], v[4:7], v[40:43], v[24:27]
	s_waitcnt lgkmcnt(1)
	v_mfma_f32_16x16x32_bf16 v[12:15], v[12:15], v[40:43], v[68:71]
	s_waitcnt lgkmcnt(0)
	v_mfma_f32_16x16x32_bf16 v[24:27], v[16:19], v[40:43], v[76:79]
	ds_read_b128 v[16:19], v179 offset:24576
	s_waitcnt lgkmcnt(0)
	v_mfma_f32_16x16x32_bf16 v[28:31], v[16:19], v[40:43], v[80:83]
	ds_read_b128 v[16:19], v179 offset:26624
	s_waitcnt lgkmcnt(0)
	v_mfma_f32_16x16x32_bf16 v[32:35], v[16:19], v[40:43], v[84:87]
	ds_read_b128 v[16:19], v179 offset:28672
	s_waitcnt lgkmcnt(0)
	v_mfma_f32_16x16x32_bf16 v[36:39], v[16:19], v[40:43], v[88:91]
	ds_read_b128 v[16:19], v179 offset:30720
	s_waitcnt lgkmcnt(0)
	v_mfma_f32_16x16x32_bf16 v[40:43], v[16:19], v[40:43], v[8:11]
	s_nop 2
	ds_read_b128 v[8:11], v179 offset:17408
	s_waitcnt lgkmcnt(0)
	v_mfma_f32_16x16x32_bf16 v[8:11], v[8:11], v[48:51], v[4:7]
	s_nop 2
	ds_read_b128 v[4:7], v179 offset:19456
	s_waitcnt lgkmcnt(0)
	v_mfma_f32_16x16x32_bf16 v[16:19], v[4:7], v[48:51], v[12:15]
	ds_read_b128 v[4:7], v179 offset:21504
	s_nop 1
	ds_read_b128 v[12:15], v179 offset:31744
	s_waitcnt lgkmcnt(1)
	v_mfma_f32_16x16x32_bf16 v[20:23], v[4:7], v[48:51], v[20:23]
	ds_read_b128 v[4:7], v179 offset:23552
	s_waitcnt lgkmcnt(1)
	v_mfma_f32_16x16x32_bf16 v[12:15], v[12:15], v[48:51], v[40:43]
	s_waitcnt lgkmcnt(0)
	v_mfma_f32_16x16x32_bf16 v[24:27], v[4:7], v[48:51], v[24:27]
	ds_read_b128 v[4:7], v179 offset:25600
	s_waitcnt lgkmcnt(0)
	v_mfma_f32_16x16x32_bf16 v[28:31], v[4:7], v[48:51], v[28:31]
	ds_read_b128 v[4:7], v179 offset:27648
	s_waitcnt lgkmcnt(0)
	v_mfma_f32_16x16x32_bf16 v[32:35], v[4:7], v[48:51], v[32:35]
	ds_read_b128 v[4:7], v179 offset:29696
	s_waitcnt lgkmcnt(0)
	v_mfma_f32_16x16x32_bf16 v[4:7], v[4:7], v[48:51], v[36:39]
	v_lshlrev_b32_e32 v152, 4, v205
	v_mov_b32_e32 v153, v3
	s_nop 0
	v_lshl_add_u64 v[36:37], s[6:7], 0, v[152:153]
	s_mov_b32 s0, 0xa00000
	v_add_co_u32_e32 v36, vcc, s0, v36
	v_lshlrev_b32_e32 v162, 2, v205
	s_nop 0
	v_addc_co_u32_e32 v37, vcc, 0, v37, vcc
	global_load_dwordx4 v[68:71], v[36:37], off
	global_load_dwordx4 v[72:75], v[36:37], off offset:64
	global_load_dwordx4 v[76:79], v[36:37], off offset:128
	global_load_dwordx4 v[80:83], v[36:37], off offset:192
	global_load_dwordx4 v[84:87], v[36:37], off offset:256
	global_load_dwordx4 v[124:127], v[36:37], off offset:320
	global_load_dwordx4 v[128:131], v[36:37], off offset:384
	global_load_dwordx4 v[132:135], v[36:37], off offset:448
	global_load_dwordx4 v[64:67], v[36:37], off offset:512
	global_load_dwordx4 v[60:63], v[36:37], off offset:576
	global_load_dwordx4 v[56:59], v[36:37], off offset:640
	global_load_dwordx4 v[52:55], v[36:37], off offset:704
	global_load_dwordx4 v[48:51], v[36:37], off offset:768
	global_load_dwordx4 v[44:47], v[36:37], off offset:832
	global_load_dwordx4 v[40:43], v[36:37], off offset:896
	s_nop 0
	global_load_dwordx4 v[36:39], v[36:37], off offset:960
	s_waitcnt vmcnt(15)
	v_pk_add_f32 v[94:95], v[94:95], v[70:71]
	v_pk_add_f32 v[92:93], v[92:93], v[68:69]
	s_waitcnt vmcnt(14)
	v_pk_add_f32 v[98:99], v[98:99], v[74:75]
	v_pk_add_f32 v[96:97], v[96:97], v[72:73]
	s_waitcnt vmcnt(13)
	v_pk_add_f32 v[102:103], v[102:103], v[78:79]
	v_pk_add_f32 v[100:101], v[100:101], v[76:77]
	s_waitcnt vmcnt(12)
	v_pk_add_f32 v[82:83], v[106:107], v[82:83]
	v_pk_add_f32 v[80:81], v[104:105], v[80:81]
	s_waitcnt vmcnt(11)
	v_pk_add_f32 v[88:89], v[110:111], v[86:87]
	v_pk_add_f32 v[90:91], v[108:109], v[84:85]
	s_waitcnt vmcnt(10)
	v_pk_add_f32 v[84:85], v[114:115], v[126:127]
	v_pk_add_f32 v[86:87], v[112:113], v[124:125]
	s_waitcnt vmcnt(9)
	v_pk_add_f32 v[72:73], v[118:119], v[130:131]
	v_pk_add_f32 v[74:75], v[116:117], v[128:129]
	s_waitcnt vmcnt(8)
	v_pk_add_f32 v[68:69], v[122:123], v[134:135]
	v_pk_add_f32 v[70:71], v[120:121], v[132:133]
	v_mul_f32_e32 v2, 0x3d372713, v92
	v_mul_f32_e32 v76, 0x3d372713, v93
	v_mul_f32_e32 v2, v92, v2
	v_mul_f32_e32 v76, v93, v76
	v_mul_f32_e32 v77, 0x3d372713, v94
	v_fma_f32 v2, v92, v2, v92
	v_fma_f32 v76, v93, v76, v93
	v_mul_f32_e32 v77, v94, v77
	v_mul_f32_e32 v2, 0x3f4c422a, v2
	v_mul_f32_e32 v76, 0x3f4c422a, v76
	v_fma_f32 v77, v94, v77, v94
	v_mul_f32_e32 v2, 0xc038aa3b, v2
	v_mul_f32_e32 v76, 0xc038aa3b, v76
	v_mul_f32_e32 v77, 0x3f4c422a, v77
	v_exp_f32_e32 v2, v2
	v_exp_f32_e32 v76, v76
	v_mul_f32_e32 v77, 0xc038aa3b, v77
	v_exp_f32_e32 v77, v77
	v_add_f32_e32 v2, 1.0, v2
	v_add_f32_e32 v76, 1.0, v76
	v_rcp_f32_e32 v2, v2
	v_rcp_f32_e32 v76, v76
	v_add_f32_e32 v77, 1.0, v77
	v_rcp_f32_e32 v77, v77
	v_mul_f32_e32 v78, 0x3d372713, v95
	v_mul_f32_e32 v2, v92, v2
	v_mul_f32_e32 v76, v93, v76
	v_mul_f32_e32 v79, 0x3d372713, v96
	v_mul_f32_e32 v92, 0x3d372713, v97
	v_mul_f32_e32 v93, 0x3d372713, v98
	v_mul_f32_e32 v78, v95, v78
	v_mul_f32_e32 v77, v94, v77
	v_mul_f32_e32 v79, v96, v79
	v_mul_f32_e32 v92, v97, v92
	v_mul_f32_e32 v93, v98, v93
	v_mul_f32_e32 v94, 0x3d372713, v99
	v_fma_f32 v78, v95, v78, v95
	v_fma_f32 v79, v96, v79, v96
	v_fma_f32 v92, v97, v92, v97
	v_fma_f32 v93, v98, v93, v98
	v_mul_f32_e32 v94, v99, v94
	v_mul_f32_e32 v78, 0x3f4c422a, v78
	v_mul_f32_e32 v79, 0x3f4c422a, v79
	v_mul_f32_e32 v92, 0x3f4c422a, v92
	v_mul_f32_e32 v93, 0x3f4c422a, v93
	v_fma_f32 v94, v99, v94, v99
	v_mul_f32_e32 v78, 0xc038aa3b, v78
	v_mul_f32_e32 v79, 0xc038aa3b, v79
	v_mul_f32_e32 v92, 0xc038aa3b, v92
	v_mul_f32_e32 v93, 0xc038aa3b, v93
	v_mul_f32_e32 v94, 0x3f4c422a, v94
	v_exp_f32_e32 v78, v78
	v_exp_f32_e32 v79, v79
	v_exp_f32_e32 v92, v92
	v_exp_f32_e32 v93, v93
	v_mul_f32_e32 v94, 0xc038aa3b, v94
	v_exp_f32_e32 v94, v94
	v_add_f32_e32 v78, 1.0, v78
	v_add_f32_e32 v79, 1.0, v79
	v_add_f32_e32 v92, 1.0, v92
	v_add_f32_e32 v93, 1.0, v93
	v_rcp_f32_e32 v78, v78
	v_rcp_f32_e32 v79, v79
	v_rcp_f32_e32 v92, v92
	v_rcp_f32_e32 v93, v93
	v_add_f32_e32 v94, 1.0, v94
	v_rcp_f32_e32 v94, v94
	v_mul_f32_e32 v78, v95, v78
	v_mul_f32_e32 v79, v96, v79
	v_mul_f32_e32 v92, v97, v92
	v_mul_f32_e32 v93, v98, v93
	v_mul_f32_e32 v94, v99, v94
	v_cvt_pk_bf16_f32 v76, v2, v76
	v_mul_f32_e32 v2, 0x3d372713, v100
	v_cvt_pk_bf16_f32 v77, v77, v78
	v_cvt_pk_bf16_f32 v78, v79, v92
	v_cvt_pk_bf16_f32 v79, v93, v94
	v_mul_f32_e32 v92, 0x3d372713, v101
	v_mul_f32_e32 v93, 0x3d372713, v102
	v_mul_f32_e32 v2, v100, v2
	v_mul_f32_e32 v92, v101, v92
	v_mul_f32_e32 v93, v102, v93
	v_mul_f32_e32 v94, 0x3d372713, v103
	v_mul_f32_e32 v95, 0x3d372713, v80
	v_mul_f32_e32 v96, 0x3d372713, v81
	v_fma_f32 v2, v100, v2, v100
	v_fma_f32 v92, v101, v92, v101
	v_fma_f32 v93, v102, v93, v102
	v_mul_f32_e32 v94, v103, v94
	v_mul_f32_e32 v95, v80, v95
	v_mul_f32_e32 v96, v81, v96
	v_mul_f32_e32 v2, 0x3f4c422a, v2
	v_mul_f32_e32 v92, 0x3f4c422a, v92
	v_mul_f32_e32 v93, 0x3f4c422a, v93
	v_fma_f32 v94, v103, v94, v103
	v_fma_f32 v95, v80, v95, v80
	v_fma_f32 v96, v81, v96, v81
	v_mul_f32_e32 v2, 0xc038aa3b, v2
	v_mul_f32_e32 v92, 0xc038aa3b, v92
	v_mul_f32_e32 v93, 0xc038aa3b, v93
	v_mul_f32_e32 v94, 0x3f4c422a, v94
	v_mul_f32_e32 v95, 0x3f4c422a, v95
	v_mul_f32_e32 v96, 0x3f4c422a, v96
	v_exp_f32_e32 v2, v2
	v_exp_f32_e32 v92, v92
	v_exp_f32_e32 v93, v93
	v_mul_f32_e32 v94, 0xc038aa3b, v94
	v_mul_f32_e32 v95, 0xc038aa3b, v95
	v_mul_f32_e32 v96, 0xc038aa3b, v96
	v_exp_f32_e32 v94, v94
	v_exp_f32_e32 v95, v95
	v_exp_f32_e32 v96, v96
	v_add_f32_e32 v2, 1.0, v2
	v_add_f32_e32 v92, 1.0, v92
	v_add_f32_e32 v93, 1.0, v93
	v_rcp_f32_e32 v2, v2
	v_rcp_f32_e32 v92, v92
	v_rcp_f32_e32 v93, v93
	v_add_f32_e32 v94, 1.0, v94
	v_add_f32_e32 v95, 1.0, v95
	v_add_f32_e32 v96, 1.0, v96
	v_rcp_f32_e32 v94, v94
	v_rcp_f32_e32 v95, v95
	v_rcp_f32_e32 v96, v96
	v_mul_f32_e32 v2, v100, v2
	v_mul_f32_e32 v92, v101, v92
	v_mul_f32_e32 v93, v102, v93
	v_mul_f32_e32 v94, v103, v94
	v_mul_f32_e32 v95, v80, v95
	v_mul_f32_e32 v96, v81, v96
	v_cvt_pk_bf16_f32 v80, v2, v92
	v_mul_f32_e32 v2, 0x3d372713, v90
	v_cvt_pk_bf16_f32 v81, v93, v94
	v_mul_f32_e32 v92, 0x3d372713, v91
	v_mul_f32_e32 v93, 0x3d372713, v88
	v_mul_f32_e32 v2, v90, v2
	v_mul_f32_e32 v92, v91, v92
	v_mul_f32_e32 v93, v88, v93
	v_fma_f32 v2, v90, v2, v90
	v_fma_f32 v92, v91, v92, v91
	v_fma_f32 v93, v88, v93, v88
	v_mul_f32_e32 v2, 0x3f4c422a, v2
	v_mul_f32_e32 v92, 0x3f4c422a, v92
	v_mul_f32_e32 v93, 0x3f4c422a, v93
	v_mul_f32_e32 v2, 0xc038aa3b, v2
	v_mul_f32_e32 v92, 0xc038aa3b, v92
	v_mul_f32_e32 v93, 0xc038aa3b, v93
	v_exp_f32_e32 v2, v2
	v_exp_f32_e32 v92, v92
	v_exp_f32_e32 v93, v93
	v_mul_f32_e32 v94, 0x3d372713, v89
	v_add_f32_e32 v2, 1.0, v2
	v_add_f32_e32 v92, 1.0, v92
	v_add_f32_e32 v93, 1.0, v93
	v_rcp_f32_e32 v2, v2
	v_rcp_f32_e32 v92, v92
	v_rcp_f32_e32 v93, v93
	v_mul_f32_e32 v94, v89, v94
	v_fma_f32 v94, v89, v94, v89
	v_mul_f32_e32 v94, 0x3f4c422a, v94
	v_mul_f32_e32 v94, 0xc038aa3b, v94
	v_exp_f32_e32 v94, v94
	v_mul_f32_e32 v2, v90, v2
	v_mul_f32_e32 v90, v91, v92
	v_mul_f32_e32 v88, v88, v93
	v_mul_f32_e32 v92, 0x3d372713, v86
	v_mul_f32_e32 v93, 0x3d372713, v87
	v_mul_f32_e32 v92, v86, v92
	v_mul_f32_e32 v93, v87, v93
	v_fma_f32 v92, v86, v92, v86
	v_fma_f32 v93, v87, v93, v87
	v_mul_f32_e32 v92, 0x3f4c422a, v92
	v_mul_f32_e32 v93, 0x3f4c422a, v93
	v_add_f32_e32 v91, 1.0, v94
	v_mul_f32_e32 v92, 0xc038aa3b, v92
	v_mul_f32_e32 v93, 0xc038aa3b, v93
	v_rcp_f32_e32 v91, v91
	v_exp_f32_e32 v92, v92
	v_exp_f32_e32 v93, v93
	v_mul_f32_e32 v98, 0x3d372713, v83
	v_mul_f32_e32 v97, 0x3d372713, v82
	v_mul_f32_e32 v98, v83, v98
	v_mul_f32_e32 v89, v89, v91
	v_add_f32_e32 v91, 1.0, v92
	v_add_f32_e32 v92, 1.0, v93
	v_mul_f32_e32 v93, 0x3d372713, v84
	v_mul_f32_e32 v94, 0x3d372713, v85
	v_mul_f32_e32 v97, v82, v97
	v_fma_f32 v98, v83, v98, v83
	v_mul_f32_e32 v93, v84, v93
	v_mul_f32_e32 v94, v85, v94
	v_fma_f32 v97, v82, v97, v82
	v_mul_f32_e32 v98, 0x3f4c422a, v98
	v_fma_f32 v93, v84, v93, v84
	v_fma_f32 v94, v85, v94, v85
	v_mul_f32_e32 v97, 0x3f4c422a, v97
	v_mul_f32_e32 v98, 0xc038aa3b, v98
	v_mul_f32_e32 v93, 0x3f4c422a, v93
	v_mul_f32_e32 v94, 0x3f4c422a, v94
	v_mul_f32_e32 v97, 0xc038aa3b, v97
	v_exp_f32_e32 v98, v98
	v_mul_f32_e32 v93, 0xc038aa3b, v93
	v_mul_f32_e32 v94, 0xc038aa3b, v94
	v_exp_f32_e32 v97, v97
	v_exp_f32_e32 v93, v93
	v_exp_f32_e32 v94, v94
	v_add_f32_e32 v98, 1.0, v98
	v_add_f32_e32 v97, 1.0, v97
	v_rcp_f32_e32 v98, v98
	v_add_f32_e32 v93, 1.0, v93
	v_add_f32_e32 v94, 1.0, v94
	v_rcp_f32_e32 v97, v97
	v_rcp_f32_e32 v91, v91
	v_rcp_f32_e32 v92, v92
	v_rcp_f32_e32 v93, v93
	v_rcp_f32_e32 v94, v94
	v_mul_f32_e32 v83, v83, v98
	v_mul_f32_e32 v97, v82, v97
	v_cvt_pk_bf16_f32 v82, v95, v96
	v_cvt_pk_bf16_f32 v83, v97, v83
	v_mul_f32_e32 v86, v86, v91
	v_mul_f32_e32 v87, v87, v92
	v_mul_f32_e32 v91, v84, v93
	v_mul_f32_e32 v92, v85, v94
	v_cvt_pk_bf16_f32 v84, v2, v90
	v_mul_f32_e32 v2, 0x3d372713, v74
	v_cvt_pk_bf16_f32 v85, v88, v89
	v_mul_f32_e32 v88, 0x3d372713, v75
	v_mul_f32_e32 v89, 0x3d372713, v72
	v_mul_f32_e32 v2, v74, v2
	v_mul_f32_e32 v88, v75, v88
	v_mul_f32_e32 v89, v72, v89
	v_fma_f32 v2, v74, v2, v74
	v_fma_f32 v88, v75, v88, v75
	v_fma_f32 v89, v72, v89, v72
	v_mul_f32_e32 v2, 0x3f4c422a, v2
	v_mul_f32_e32 v88, 0x3f4c422a, v88
	v_mul_f32_e32 v89, 0x3f4c422a, v89
	v_mul_f32_e32 v2, 0xc038aa3b, v2
	v_mul_f32_e32 v88, 0xc038aa3b, v88
	v_mul_f32_e32 v89, 0xc038aa3b, v89
	v_exp_f32_e32 v2, v2
	v_exp_f32_e32 v88, v88
	v_exp_f32_e32 v89, v89
	v_mul_f32_e32 v90, 0x3d372713, v73
	v_add_f32_e32 v2, 1.0, v2
	v_add_f32_e32 v88, 1.0, v88
	v_add_f32_e32 v89, 1.0, v89
	v_rcp_f32_e32 v2, v2
	v_rcp_f32_e32 v88, v88
	v_rcp_f32_e32 v89, v89
	v_mul_f32_e32 v90, v73, v90
	v_fma_f32 v90, v73, v90, v73
	v_mul_f32_e32 v90, 0x3f4c422a, v90
	v_mul_f32_e32 v90, 0xc038aa3b, v90
	v_exp_f32_e32 v90, v90
	v_mul_f32_e32 v2, v74, v2
	v_mul_f32_e32 v74, v75, v88
	v_mul_f32_e32 v72, v72, v89
	v_mul_f32_e32 v88, 0x3d372713, v70
	v_mul_f32_e32 v89, 0x3d372713, v71
	v_mul_f32_e32 v88, v70, v88
	v_mul_f32_e32 v89, v71, v89
	v_fma_f32 v88, v70, v88, v70
	v_fma_f32 v89, v71, v89, v71
	v_mul_f32_e32 v88, 0x3f4c422a, v88
	v_mul_f32_e32 v89, 0x3f4c422a, v89
	v_add_f32_e32 v75, 1.0, v90
	v_mul_f32_e32 v88, 0xc038aa3b, v88
	v_mul_f32_e32 v89, 0xc038aa3b, v89
	v_rcp_f32_e32 v75, v75
	v_exp_f32_e32 v88, v88
	v_exp_f32_e32 v89, v89
	v_mul_f32_e32 v90, 0x3d372713, v69
	v_mul_f32_e32 v73, v73, v75
	v_add_f32_e32 v75, 1.0, v88
	v_add_f32_e32 v88, 1.0, v89
	v_mul_f32_e32 v89, 0x3d372713, v68
	v_mul_f32_e32 v89, v68, v89
	v_mul_f32_e32 v90, v69, v90
	v_fma_f32 v89, v68, v89, v68
	v_fma_f32 v90, v69, v90, v69
	v_mul_f32_e32 v89, 0x3f4c422a, v89
	v_mul_f32_e32 v90, 0x3f4c422a, v90
	v_mul_f32_e32 v89, 0xc038aa3b, v89
	v_mul_f32_e32 v90, 0xc038aa3b, v90
	v_exp_f32_e32 v89, v89
	v_exp_f32_e32 v90, v90
	v_rcp_f32_e32 v75, v75
	v_rcp_f32_e32 v88, v88
	v_add_f32_e32 v89, 1.0, v89
	v_add_f32_e32 v90, 1.0, v90
	v_rcp_f32_e32 v89, v89
	v_rcp_f32_e32 v90, v90
	v_readlane_b32 s8, v254, 0
	v_readlane_b32 s9, v254, 1
	s_mov_b64 s[0:1], s[8:9]
	v_cvt_pk_bf16_f32 v86, v86, v87
	v_cvt_pk_bf16_f32 v87, v91, v92
	v_mul_f32_e32 v70, v70, v75
	v_mul_f32_e32 v71, v71, v88
	v_mul_f32_e32 v68, v68, v89
	v_mul_f32_e32 v69, v69, v90
	v_cvt_pk_bf16_f32 v88, v2, v74
	v_cvt_pk_bf16_f32 v89, v72, v73
	v_cvt_pk_bf16_f32 v90, v70, v71
	v_cvt_pk_bf16_f32 v91, v68, v69
	s_load_dwordx2 s[0:1], s[0:1], 0xa8
	v_mov_b32_e32 v179, v3
	v_lshlrev_b32_e32 v2, 10, v205
	v_or_b32_e32 v96, 0x1000, v2
	v_mov_b32_e32 v97, v3
	s_waitcnt lgkmcnt(0)
	v_lshl_add_u64 v[158:159], s[0:1], 0, v[178:179]
	v_or_b32_e32 v98, 0x1100, v2
	v_mov_b32_e32 v99, v3
	v_or_b32_e32 v100, 0x1200, v2
	v_mov_b32_e32 v101, v3
	v_or_b32_e32 v102, 0x1300, v2
	v_mov_b32_e32 v103, v3
	v_or_b32_e32 v104, 0x2000, v2
	v_mov_b32_e32 v105, v3
	v_or_b32_e32 v106, 0x2100, v2
	v_mov_b32_e32 v107, v3
	v_or_b32_e32 v110, 0x2300, v2
	v_mov_b32_e32 v111, v3
	v_or_b32_e32 v112, 0x3000, v2
	v_mov_b32_e32 v113, v3
	v_or_b32_e32 v114, 0x3100, v2
	v_mov_b32_e32 v115, v3
	v_or_b32_e32 v116, 0x3200, v2
	v_mov_b32_e32 v117, v3
	v_or_b32_e32 v118, 0x3300, v2
	v_mov_b32_e32 v119, v3
	v_or_b32_e32 v120, 0x4000, v2
	v_mov_b32_e32 v121, v3
	v_or_b32_e32 v122, 0x4100, v2
	v_mov_b32_e32 v123, v3
	v_or_b32_e32 v124, 0x4200, v2
	v_mov_b32_e32 v125, v3
	v_or_b32_e32 v126, 0x4300, v2
	v_mov_b32_e32 v127, v3
	v_lshl_add_u64 v[156:157], v[158:159], 0, v[2:3]
	v_lshl_add_u64 v[68:69], v[158:159], 0, v[96:97]
	v_lshl_add_u64 v[70:71], v[158:159], 0, v[98:99]
	v_lshl_add_u64 v[72:73], v[158:159], 0, v[100:101]
	v_lshl_add_u64 v[74:75], v[158:159], 0, v[102:103]
	v_lshl_add_u64 v[92:93], v[158:159], 0, v[104:105]
	v_lshl_add_u64 v[94:95], v[158:159], 0, v[106:107]
	v_or_b32_e32 v108, 0x2200, v2
	v_mov_b32_e32 v109, v3
	v_lshl_add_u64 v[160:161], v[158:159], 0, v[110:111]
	v_lshl_add_u64 v[164:165], v[158:159], 0, v[112:113]
	v_lshl_add_u64 v[166:167], v[158:159], 0, v[114:115]
	v_lshl_add_u64 v[168:169], v[158:159], 0, v[116:117]
	v_lshl_add_u64 v[170:171], v[158:159], 0, v[118:119]
	v_lshl_add_u64 v[172:173], v[158:159], 0, v[120:121]
	v_lshl_add_u64 v[174:175], v[158:159], 0, v[122:123]
	v_lshl_add_u64 v[182:183], v[158:159], 0, v[124:125]
	v_lshl_add_u64 v[184:185], v[158:159], 0, v[126:127]
	v_or_b32_e32 v128, 0x5000, v2
	v_mov_b32_e32 v129, v3
	v_or_b32_e32 v130, 0x5100, v2
	v_mov_b32_e32 v131, v3
	v_or_b32_e32 v132, 0x5200, v2
	v_mov_b32_e32 v133, v3
	v_or_b32_e32 v134, 0x5300, v2
	v_mov_b32_e32 v135, v3
	v_or_b32_e32 v136, 0x6000, v2
	v_mov_b32_e32 v137, v3
	v_or_b32_e32 v138, 0x6100, v2
	v_mov_b32_e32 v139, v3
	v_or_b32_e32 v140, 0x6200, v2
	v_mov_b32_e32 v141, v3
	v_or_b32_e32 v142, 0x6300, v2
	v_mov_b32_e32 v143, v3
	v_or_b32_e32 v144, 0x7000, v2
	v_mov_b32_e32 v145, v3
	v_or_b32_e32 v146, 0x7100, v2
	v_mov_b32_e32 v147, v3
	v_or_b32_e32 v148, 0x7200, v2
	v_mov_b32_e32 v149, v3
	v_or_b32_e32 v150, 0x7300, v2
	v_mov_b32_e32 v151, v3
	v_lshl_add_u64 v[154:155], v[158:159], 0, v[108:109]
	v_lshl_add_u64 v[186:187], v[158:159], 0, v[128:129]
	v_lshl_add_u64 v[188:189], v[158:159], 0, v[130:131]
	v_lshl_add_u64 v[190:191], v[158:159], 0, v[132:133]
	v_lshl_add_u64 v[192:193], v[158:159], 0, v[134:135]
	v_lshl_add_u64 v[194:195], v[158:159], 0, v[136:137]
	v_lshl_add_u64 v[196:197], v[158:159], 0, v[138:139]
	v_lshl_add_u64 v[198:199], v[158:159], 0, v[140:141]
	v_lshl_add_u64 v[202:203], v[158:159], 0, v[142:143]
	v_lshl_add_u64 v[208:209], v[158:159], 0, v[144:145]
	v_lshl_add_u64 v[210:211], v[158:159], 0, v[146:147]
	v_lshl_add_u64 v[212:213], v[158:159], 0, v[148:149]
	v_lshl_add_u64 v[214:215], v[158:159], 0, v[150:151]
	global_load_dword v153, v[156:157], off offset:256
	global_load_dword v163, v[156:157], off offset:768
	s_nop 0
	global_load_dword v70, v[70:71], off
	s_nop 0
	global_load_dword v71, v[74:75], off
	s_nop 0
	global_load_dword v72, v[72:73], off
	s_nop 0
	global_load_dword v73, v[68:69], off
	s_nop 0
	global_load_dword v69, v[156:157], off offset:512
	global_load_dword v68, v[156:157], off
	global_load_dword v74, v[94:95], off
	global_load_dword v75, v[160:161], off
	s_nop 0
	global_load_dword v94, v[166:167], off
	global_load_dword v95, v[170:171], off
	global_load_dword v160, v[168:169], off
	global_load_dword v161, v[164:165], off
	s_nop 0
	global_load_dword v164, v[154:155], off
	s_nop 0
	global_load_dword v92, v[92:93], off
	s_nop 0
	global_load_dword v93, v[174:175], off
	global_load_dword v165, v[184:185], off
	global_load_dword v166, v[188:189], off
	global_load_dword v167, v[192:193], off
	global_load_dword v168, v[190:191], off
	global_load_dword v169, v[186:187], off
	global_load_dword v170, v[182:183], off
	global_load_dword v171, v[172:173], off
	s_nop 0
	global_load_dword v172, v[196:197], off
	global_load_dword v173, v[202:203], off
	global_load_dword v174, v[210:211], off
	global_load_dword v175, v[214:215], off
	global_load_dword v182, v[212:213], off
	global_load_dword v183, v[208:209], off
	global_load_dword v184, v[198:199], off
	global_load_dword v185, v[194:195], off
	v_ashrrev_i32_e32 v181, 31, v180
	v_lshlrev_b64 v[154:155], 10, v[180:181]
	s_waitcnt vmcnt(24)
	v_cvt_pk_bf16_f32 v68, v68, v153
	v_cvt_pk_bf16_f32 v69, v69, v163
	v_cvt_pk_bf16_f32 v70, v73, v70
	v_cvt_pk_bf16_f32 v71, v72, v71
	s_waitcnt vmcnt(16)
	v_cvt_pk_bf16_f32 v72, v92, v74
	v_cvt_pk_bf16_f32 v73, v164, v75
	v_cvt_pk_bf16_f32 v74, v161, v94
	v_cvt_pk_bf16_f32 v75, v160, v95
	v_mfma_f32_16x16x32_bf16 v[68:71], v[68:71], v[76:79], 0
	v_mfma_f32_16x16x32_bf16 v[68:71], v[72:75], v[80:83], v[68:71]
	s_waitcnt vmcnt(8)
	v_cvt_pk_bf16_f32 v72, v171, v93
	v_cvt_pk_bf16_f32 v73, v170, v165
	v_cvt_pk_bf16_f32 v74, v169, v166
	v_cvt_pk_bf16_f32 v75, v168, v167
	s_nop 0
	v_mfma_f32_16x16x32_bf16 v[68:71], v[72:75], v[84:87], v[68:71]
	s_waitcnt vmcnt(0)
	v_cvt_pk_bf16_f32 v72, v185, v172
	v_cvt_pk_bf16_f32 v73, v184, v173
	v_cvt_pk_bf16_f32 v74, v183, v174
	v_cvt_pk_bf16_f32 v75, v182, v175
	s_nop 0
	v_mfma_f32_16x16x32_bf16 v[92:95], v[72:75], v[88:91], v[68:71]
	s_nop 4
	v_lshl_add_u64 v[68:69], v[158:159], 0, 64
	v_lshl_add_u64 v[70:71], v[68:69], 0, v[96:97]
	v_lshl_add_u64 v[72:73], v[68:69], 0, v[98:99]
	v_lshl_add_u64 v[74:75], v[68:69], 0, v[100:101]
	v_lshl_add_u64 v[160:161], v[68:69], 0, v[102:103]
	v_lshl_add_u64 v[164:165], v[68:69], 0, v[104:105]
	v_lshl_add_u64 v[166:167], v[68:69], 0, v[106:107]
	v_lshl_add_u64 v[168:169], v[68:69], 0, v[108:109]
	v_lshl_add_u64 v[170:171], v[68:69], 0, v[110:111]
	v_lshl_add_u64 v[172:173], v[68:69], 0, v[112:113]
	v_lshl_add_u64 v[174:175], v[68:69], 0, v[114:115]
	v_lshl_add_u64 v[180:181], v[68:69], 0, v[116:117]
	v_lshl_add_u64 v[182:183], v[68:69], 0, v[118:119]
	v_lshl_add_u64 v[184:185], v[68:69], 0, v[120:121]
	v_lshl_add_u64 v[186:187], v[68:69], 0, v[122:123]
	v_lshl_add_u64 v[188:189], v[68:69], 0, v[124:125]
	v_lshl_add_u64 v[190:191], v[68:69], 0, v[126:127]
	v_lshl_add_u64 v[192:193], v[68:69], 0, v[128:129]
	v_lshl_add_u64 v[194:195], v[68:69], 0, v[130:131]
	v_lshl_add_u64 v[196:197], v[68:69], 0, v[132:133]
	v_lshl_add_u64 v[198:199], v[68:69], 0, v[134:135]
	v_lshl_add_u64 v[202:203], v[68:69], 0, v[136:137]
	v_lshl_add_u64 v[208:209], v[68:69], 0, v[138:139]
	v_lshl_add_u64 v[210:211], v[68:69], 0, v[140:141]
	v_lshl_add_u64 v[212:213], v[68:69], 0, v[142:143]
	v_lshl_add_u64 v[214:215], v[68:69], 0, v[144:145]
	v_lshl_add_u64 v[216:217], v[68:69], 0, v[146:147]
	v_lshl_add_u64 v[218:219], v[68:69], 0, v[148:149]
	v_lshl_add_u64 v[68:69], v[68:69], 0, v[150:151]
	global_load_dword v153, v[156:157], off offset:320
	global_load_dword v163, v[156:157], off offset:832
	s_nop 0
	global_load_dword v72, v[72:73], off
	s_nop 0
	global_load_dword v73, v[160:161], off
	s_nop 0
	global_load_dword v74, v[74:75], off
	s_nop 0
	global_load_dword v70, v[70:71], off
	s_nop 0
	global_load_dword v71, v[156:157], off offset:576
	global_load_dword v75, v[156:157], off offset:64
	global_load_dword v160, v[166:167], off
	global_load_dword v161, v[170:171], off
	s_nop 0
	global_load_dword v166, v[174:175], off
	global_load_dword v167, v[182:183], off
	global_load_dword v170, v[180:181], off
	global_load_dword v171, v[172:173], off
	s_nop 0
	global_load_dword v168, v[168:169], off
	s_nop 0
	global_load_dword v164, v[164:165], off
	s_nop 0
	global_load_dword v165, v[186:187], off
	global_load_dword v169, v[190:191], off
	global_load_dword v172, v[194:195], off
	global_load_dword v173, v[198:199], off
	global_load_dword v174, v[196:197], off
	global_load_dword v175, v[192:193], off
	global_load_dword v180, v[188:189], off
	global_load_dword v181, v[184:185], off
	global_load_dword v182, v[208:209], off
	global_load_dword v183, v[212:213], off
	s_nop 0
	global_load_dword v184, v[216:217], off
	global_load_dword v185, v[68:69], off
	global_load_dword v186, v[218:219], off
	global_load_dword v187, v[214:215], off
	global_load_dword v188, v[210:211], off
	global_load_dword v189, v[202:203], off
	s_waitcnt vmcnt(24)
	v_cvt_pk_bf16_f32 v68, v75, v153
	v_cvt_pk_bf16_f32 v69, v71, v163
	v_cvt_pk_bf16_f32 v70, v70, v72
	v_cvt_pk_bf16_f32 v71, v74, v73
	s_waitcnt vmcnt(16)
	v_cvt_pk_bf16_f32 v72, v164, v160
	v_cvt_pk_bf16_f32 v73, v168, v161
	v_cvt_pk_bf16_f32 v74, v171, v166
	v_cvt_pk_bf16_f32 v75, v170, v167
	v_mfma_f32_16x16x32_bf16 v[68:71], v[68:71], v[76:79], 0
	v_mfma_f32_16x16x32_bf16 v[68:71], v[72:75], v[80:83], v[68:71]
	s_waitcnt vmcnt(8)
	v_cvt_pk_bf16_f32 v72, v181, v165
	v_cvt_pk_bf16_f32 v73, v180, v169
	v_cvt_pk_bf16_f32 v74, v175, v172
	v_cvt_pk_bf16_f32 v75, v174, v173
	s_nop 0
	v_mfma_f32_16x16x32_bf16 v[68:71], v[72:75], v[84:87], v[68:71]
	s_waitcnt vmcnt(0)
	v_cvt_pk_bf16_f32 v72, v189, v182
	v_cvt_pk_bf16_f32 v73, v188, v183
	v_cvt_pk_bf16_f32 v74, v187, v184
	v_cvt_pk_bf16_f32 v75, v186, v185
	s_nop 0
	v_mfma_f32_16x16x32_bf16 v[68:71], v[72:75], v[88:91], v[68:71]
	s_mov_b64 s[0:1], 0x80
	v_lshl_add_u64 v[72:73], v[158:159], 0, s[0:1]
	v_lshl_add_u64 v[74:75], v[72:73], 0, v[96:97]
	v_lshl_add_u64 v[160:161], v[72:73], 0, v[98:99]
	v_lshl_add_u64 v[164:165], v[72:73], 0, v[100:101]
	v_lshl_add_u64 v[166:167], v[72:73], 0, v[102:103]
	v_lshl_add_u64 v[168:169], v[72:73], 0, v[104:105]
	v_lshl_add_u64 v[170:171], v[72:73], 0, v[106:107]
	v_lshl_add_u64 v[172:173], v[72:73], 0, v[108:109]
	v_lshl_add_u64 v[174:175], v[72:73], 0, v[110:111]
	v_lshl_add_u64 v[180:181], v[72:73], 0, v[112:113]
	v_lshl_add_u64 v[182:183], v[72:73], 0, v[114:115]
	v_lshl_add_u64 v[184:185], v[72:73], 0, v[116:117]
	v_lshl_add_u64 v[186:187], v[72:73], 0, v[118:119]
	v_lshl_add_u64 v[188:189], v[72:73], 0, v[120:121]
	v_lshl_add_u64 v[190:191], v[72:73], 0, v[122:123]
	v_lshl_add_u64 v[192:193], v[72:73], 0, v[124:125]
	v_lshl_add_u64 v[194:195], v[72:73], 0, v[126:127]
	v_lshl_add_u64 v[196:197], v[72:73], 0, v[128:129]
	v_lshl_add_u64 v[198:199], v[72:73], 0, v[130:131]
	v_lshl_add_u64 v[202:203], v[72:73], 0, v[132:133]
	v_lshl_add_u64 v[208:209], v[72:73], 0, v[134:135]
	v_lshl_add_u64 v[210:211], v[72:73], 0, v[136:137]
	v_lshl_add_u64 v[212:213], v[72:73], 0, v[138:139]
	v_lshl_add_u64 v[214:215], v[72:73], 0, v[140:141]
	v_lshl_add_u64 v[216:217], v[72:73], 0, v[142:143]
	v_lshl_add_u64 v[218:219], v[72:73], 0, v[144:145]
	v_lshl_add_u64 v[220:221], v[72:73], 0, v[146:147]
	v_lshl_add_u64 v[222:223], v[72:73], 0, v[148:149]
	v_lshl_add_u64 v[72:73], v[72:73], 0, v[150:151]
	global_load_dword v153, v[156:157], off offset:384
	global_load_dword v163, v[156:157], off offset:896
	s_nop 0
	global_load_dword v160, v[160:161], off
	s_nop 0
	global_load_dword v161, v[166:167], off
	s_nop 0
	global_load_dword v164, v[164:165], off
	s_nop 0
	global_load_dword v74, v[74:75], off
	s_nop 0
	global_load_dword v75, v[156:157], off offset:640
	global_load_dword v165, v[156:157], off offset:128
	global_load_dword v166, v[170:171], off
	global_load_dword v167, v[174:175], off
	s_nop 0
	global_load_dword v170, v[182:183], off
	global_load_dword v171, v[186:187], off
	global_load_dword v174, v[184:185], off
	global_load_dword v175, v[180:181], off
	s_nop 0
	global_load_dword v172, v[172:173], off
	s_nop 0
	global_load_dword v168, v[168:169], off
	s_nop 0
	global_load_dword v169, v[190:191], off
	global_load_dword v173, v[194:195], off
	global_load_dword v180, v[198:199], off
	global_load_dword v181, v[208:209], off
	global_load_dword v182, v[202:203], off
	global_load_dword v183, v[196:197], off
	global_load_dword v184, v[192:193], off
	global_load_dword v185, v[188:189], off
	global_load_dword v186, v[212:213], off
	global_load_dword v187, v[216:217], off
	s_nop 0
	global_load_dword v188, v[220:221], off
	global_load_dword v189, v[72:73], off
	global_load_dword v190, v[222:223], off
	global_load_dword v191, v[218:219], off
	global_load_dword v192, v[214:215], off
	global_load_dword v193, v[210:211], off
	s_waitcnt vmcnt(24)
	v_cvt_pk_bf16_f32 v72, v165, v153
	v_cvt_pk_bf16_f32 v73, v75, v163
	v_cvt_pk_bf16_f32 v74, v74, v160
	v_cvt_pk_bf16_f32 v75, v164, v161
	s_waitcnt vmcnt(16)
	v_cvt_pk_bf16_f32 v164, v168, v166
	v_cvt_pk_bf16_f32 v165, v172, v167
	v_cvt_pk_bf16_f32 v166, v175, v170
	v_cvt_pk_bf16_f32 v167, v174, v171
	v_mfma_f32_16x16x32_bf16 v[72:75], v[72:75], v[76:79], 0
	v_mfma_f32_16x16x32_bf16 v[72:75], v[164:167], v[80:83], v[72:75]
	s_waitcnt vmcnt(8)
	v_cvt_pk_bf16_f32 v164, v185, v169
	v_cvt_pk_bf16_f32 v165, v184, v173
	v_cvt_pk_bf16_f32 v166, v183, v180
	v_cvt_pk_bf16_f32 v167, v182, v181
	s_nop 0
	v_mfma_f32_16x16x32_bf16 v[72:75], v[164:167], v[84:87], v[72:75]
	s_waitcnt vmcnt(0)
	v_cvt_pk_bf16_f32 v164, v193, v186
	v_cvt_pk_bf16_f32 v165, v192, v187
	v_cvt_pk_bf16_f32 v166, v191, v188
	v_cvt_pk_bf16_f32 v167, v190, v189
	s_nop 0
	v_mfma_f32_16x16x32_bf16 v[72:75], v[164:167], v[88:91], v[72:75]
	s_mov_b64 s[0:1], 0xc0
	v_lshl_add_u64 v[158:159], v[158:159], 0, s[0:1]
	v_lshl_add_u64 v[160:161], v[158:159], 0, v[96:97]
	v_lshl_add_u64 v[164:165], v[158:159], 0, v[98:99]
	v_lshl_add_u64 v[166:167], v[158:159], 0, v[100:101]
	v_lshl_add_u64 v[168:169], v[158:159], 0, v[102:103]
	v_lshl_add_u64 v[170:171], v[158:159], 0, v[104:105]
	v_lshl_add_u64 v[172:173], v[158:159], 0, v[106:107]
	v_lshl_add_u64 v[174:175], v[158:159], 0, v[108:109]
	v_lshl_add_u64 v[180:181], v[158:159], 0, v[110:111]
	v_lshl_add_u64 v[182:183], v[158:159], 0, v[112:113]
	v_lshl_add_u64 v[184:185], v[158:159], 0, v[114:115]
	v_lshl_add_u64 v[186:187], v[158:159], 0, v[116:117]
	v_lshl_add_u64 v[188:189], v[158:159], 0, v[118:119]
	v_lshl_add_u64 v[190:191], v[158:159], 0, v[120:121]
	v_lshl_add_u64 v[192:193], v[158:159], 0, v[122:123]
	v_lshl_add_u64 v[194:195], v[158:159], 0, v[124:125]
	v_lshl_add_u64 v[196:197], v[158:159], 0, v[126:127]
	v_lshl_add_u64 v[198:199], v[158:159], 0, v[128:129]
	v_lshl_add_u64 v[202:203], v[158:159], 0, v[130:131]
	v_lshl_add_u64 v[208:209], v[158:159], 0, v[132:133]
	v_lshl_add_u64 v[210:211], v[158:159], 0, v[134:135]
	v_lshl_add_u64 v[212:213], v[158:159], 0, v[136:137]
	v_lshl_add_u64 v[214:215], v[158:159], 0, v[138:139]
	v_lshl_add_u64 v[216:217], v[158:159], 0, v[140:141]
	v_lshl_add_u64 v[218:219], v[158:159], 0, v[142:143]
	v_lshl_add_u64 v[220:221], v[158:159], 0, v[144:145]
	v_lshl_add_u64 v[222:223], v[158:159], 0, v[146:147]
	v_lshl_add_u64 v[224:225], v[158:159], 0, v[148:149]
	v_lshl_add_u64 v[158:159], v[158:159], 0, v[150:151]
	global_load_dword v153, v[156:157], off offset:448
	global_load_dword v163, v[156:157], off offset:960
	s_nop 0
	global_load_dword v164, v[164:165], off
	s_nop 0
	global_load_dword v165, v[168:169], off
	s_nop 0
	global_load_dword v166, v[166:167], off
	s_nop 0
	global_load_dword v160, v[160:161], off
	s_nop 0
	global_load_dword v161, v[156:157], off offset:704
	s_nop 0
	global_load_dword v156, v[156:157], off offset:192
	s_nop 0
	global_load_dword v167, v[172:173], off
	global_load_dword v168, v[180:181], off
	global_load_dword v169, v[184:185], off
	s_nop 0
	global_load_dword v172, v[188:189], off
	global_load_dword v173, v[186:187], off
	global_load_dword v180, v[182:183], off
	s_nop 0
	global_load_dword v174, v[174:175], off
	s_nop 0
	global_load_dword v170, v[170:171], off
	s_nop 0
	global_load_dword v171, v[192:193], off
	global_load_dword v175, v[196:197], off
	global_load_dword v181, v[202:203], off
	global_load_dword v182, v[210:211], off
	global_load_dword v183, v[208:209], off
	global_load_dword v184, v[198:199], off
	global_load_dword v185, v[194:195], off
	global_load_dword v186, v[190:191], off
	global_load_dword v187, v[214:215], off
	global_load_dword v188, v[218:219], off
	global_load_dword v189, v[222:223], off
	s_nop 0
	global_load_dword v190, v[158:159], off
	global_load_dword v191, v[224:225], off
	global_load_dword v192, v[220:221], off
	global_load_dword v193, v[216:217], off
	global_load_dword v194, v[212:213], off
	s_waitcnt vmcnt(24)
	v_cvt_pk_bf16_f32 v156, v156, v153
	v_cvt_pk_bf16_f32 v157, v161, v163
	v_cvt_pk_bf16_f32 v158, v160, v164
	v_cvt_pk_bf16_f32 v159, v166, v165
	s_nop 0
	v_mfma_f32_16x16x32_bf16 v[76:79], v[156:159], v[76:79], 0
	s_waitcnt vmcnt(16)
	v_cvt_pk_bf16_f32 v156, v170, v167
	v_cvt_pk_bf16_f32 v157, v174, v168
	v_cvt_pk_bf16_f32 v158, v180, v169
	v_cvt_pk_bf16_f32 v159, v173, v172
	s_nop 0
	v_mfma_f32_16x16x32_bf16 v[76:79], v[156:159], v[80:83], v[76:79]
	s_waitcnt vmcnt(8)
	v_cvt_pk_bf16_f32 v80, v186, v171
	v_cvt_pk_bf16_f32 v81, v185, v175
	v_cvt_pk_bf16_f32 v82, v184, v181
	v_cvt_pk_bf16_f32 v83, v183, v182
	s_nop 0
	v_mfma_f32_16x16x32_bf16 v[76:79], v[80:83], v[84:87], v[76:79]
	s_waitcnt vmcnt(0)
	v_cvt_pk_bf16_f32 v80, v194, v187
	v_cvt_pk_bf16_f32 v81, v193, v188
	v_cvt_pk_bf16_f32 v82, v192, v189
	v_cvt_pk_bf16_f32 v83, v191, v190
	s_nop 0
	v_mfma_f32_16x16x32_bf16 v[76:79], v[80:83], v[88:91], v[76:79]
	v_mul_f32_e64 v80, v94, v94
	v_mul_f32_e64 v81, v95, v95
	v_pk_mul_f32 v[82:83], v[92:93], v[92:93]
	s_mov_b32 s0, 0x800000
	v_pk_mov_b32 v[84:85], v[82:83], v[80:81] op_sel:[1,0]
	v_mov_b32_e32 v83, v81
	v_pk_add_f32 v[80:81], v[84:85], v[82:83]
	v_pk_mul_f32 v[82:83], v[70:71], v[70:71]
	v_pk_mul_f32 v[84:85], v[68:69], v[68:69]
	v_pk_add_f32 v[80:81], v[80:81], v[80:81] op_sel:[0,1] op_sel_hi:[1,0]
	v_pk_mov_b32 v[86:87], v[84:85], v[82:83] op_sel:[1,0]
	v_mov_b32_e32 v85, v83
	v_pk_add_f32 v[82:83], v[86:87], v[84:85]
	v_mul_f32_e32 v84, v76, v76
	v_mul_f32_e32 v85, v77, v77
	v_pk_add_f32 v[82:83], v[82:83], v[82:83] op_sel:[0,1] op_sel_hi:[1,0]
	v_mov_b32_e32 v81, v84
	v_mov_b32_e32 v83, v85
	v_pk_add_f32 v[80:81], v[80:81], v[82:83]
	v_mul_f32_e32 v82, v73, v73
	v_mul_f32_e32 v84, v75, v75
	v_mul_f32_e32 v86, v78, v78
	v_mul_f32_e32 v87, v79, v79
	v_pk_fma_f32 v[82:83], v[72:73], v[72:73], v[82:83] op_sel_hi:[1,1,0]
	v_pk_fma_f32 v[84:85], v[74:75], v[74:75], v[84:85] op_sel_hi:[1,1,0]
	v_mov_b32_e32 v83, v86
	v_mov_b32_e32 v85, v87
	v_pk_add_f32 v[82:83], v[82:83], v[84:85]
	s_nop 0
	v_pk_add_f32 v[80:81], v[80:81], v[82:83]
	v_and_b32_e32 v82, 64, v229
	v_add_f32_e32 v80, v80, v81
	v_xor_b32_e32 v81, 16, v229
	v_add_u32_e32 v82, 64, v82
	v_cmp_lt_i32_e32 vcc, v81, v82
	s_nop 1
	v_cndmask_b32_e32 v81, v229, v81, vcc
	v_lshlrev_b32_e32 v81, 2, v81
	ds_bpermute_b32 v81, v81, v80
	s_waitcnt lgkmcnt(0)
	v_add_f32_e32 v80, v80, v81
	v_xor_b32_e32 v81, 32, v229
	v_cmp_lt_i32_e32 vcc, v81, v82
	s_nop 1
	v_cndmask_b32_e32 v81, v229, v81, vcc
	v_lshlrev_b32_e32 v153, 2, v81
	ds_bpermute_b32 v81, v153, v80
	s_waitcnt lgkmcnt(0)
	v_add_f32_e32 v80, v80, v81
	v_fmamk_f32 v80, v80, 0x3c800000, v226
	v_cmp_gt_f32_e32 vcc, s0, v80
	v_mul_f32_e32 v81, 0x4b800000, v80
	s_mov_b64 s[0:1], s[8:9]
	v_cndmask_b32_e32 v80, v80, v81, vcc
	v_rsq_f32_e32 v80, v80
	s_load_dwordx2 s[0:1], s[0:1], 0x90
	v_mul_f32_e32 v81, 0x45800000, v80
	v_cndmask_b32_e32 v156, v80, v81, vcc
	s_waitcnt lgkmcnt(0)
	global_load_dwordx4 v[80:83], v152, s[0:1]
	s_mov_b64 s[0:1], s[8:9]
	s_load_dwordx2 s[0:1], s[0:1], 0x90
	v_pk_mul_f32 v[84:85], v[92:93], v[156:157] op_sel_hi:[1,0]
	v_pk_mul_f32 v[86:87], v[94:95], v[156:157] op_sel_hi:[1,0]
	v_lshl_add_u64 v[94:95], s[6:7], 0, v[154:155]
	v_lshlrev_b32_e32 v92, 2, v162
	s_waitcnt vmcnt(0)
	v_pk_mul_f32 v[90:91], v[82:83], v[86:87]
	v_pk_mul_f32 v[88:89], v[80:81], v[84:85]
	s_waitcnt lgkmcnt(0)
	global_load_dwordx4 v[80:83], v152, s[0:1] offset:64
	s_mov_b64 s[0:1], s[8:9]
	s_load_dwordx2 s[0:1], s[0:1], 0x90
	ds_bpermute_b32 v160, v153, v88
	ds_bpermute_b32 v161, v153, v89
	ds_bpermute_b32 v158, v153, v90
	ds_bpermute_b32 v159, v153, v91
	s_waitcnt lgkmcnt(0)
	global_load_dwordx4 v[84:87], v152, s[0:1] offset:128
	v_lshlrev_b32_e32 v152, 2, v176
	s_and_saveexec_b64 s[0:1], s[4:5]
	s_cbranch_execz .LBB0_567
	v_lshlrev_b32_e32 v154, 12, v1
	v_mov_b32_e32 v155, v3
	v_and_b32_e32 v93, 8, v206
	v_lshl_add_u64 v[154:155], s[6:7], 0, v[154:155]
	v_lshlrev_b32_e32 v164, 2, v93
	v_mov_b32_e32 v165, v3
	v_lshl_add_u64 v[154:155], v[154:155], 0, v[164:165]
	s_mov_b64 s[10:11], 0x900fc0
	v_lshl_add_u64 v[168:169], v[154:155], 0, s[10:11]
	v_add_co_u32_e32 v154, vcc, 0x900000, v154
	v_mov_b32_e32 v157, v156
	s_nop 0
	v_addc_co_u32_e32 v155, vcc, 0, v155, vcc
	global_load_dwordx4 v[164:167], v[154:155], off offset:4032
	s_nop 0
	global_load_dwordx4 v[168:171], v[168:169], off offset:16
	s_load_dwordx2 s[8:9], s[8:9], 0x90
	v_cmp_gt_u32_e32 vcc, 2, v205
	v_pk_mul_f32 v[72:73], v[72:73], v[156:157]
	v_pk_mul_f32 v[68:69], v[68:69], v[156:157]
	s_waitcnt vmcnt(2)
	v_pk_mul_f32 v[72:73], v[84:85], v[72:73]
	v_pk_mul_f32 v[68:69], v[80:81], v[68:69]
	v_lshlrev_b32_e32 v80, 9, v177
	v_lshlrev_b32_e32 v81, 7, v204
	v_or3_b32 v80, v80, v81, v1
	v_ashrrev_i32_e32 v81, 31, v80
	v_lshlrev_b64 v[80:81], 7, v[80:81]
	v_lshl_add_u64 v[80:81], s[6:7], 0, v[80:81]
	s_waitcnt vmcnt(1)
	v_mov_b32_e32 v154, v165
	v_mov_b32_e32 v155, v167
	v_pk_mul_f32 v[154:155], v[154:155], v[160:161]
	s_waitcnt vmcnt(0)
	v_mov_b32_e32 v160, v169
	v_mov_b32_e32 v161, v171
	v_pk_mul_f32 v[158:159], v[160:161], v[158:159]
	v_xor_b32_e32 v93, 0x80000000, v154
	v_xor_b32_e32 v153, 0x80000000, v155
	v_xor_b32_e32 v160, 0x80000000, v158
	v_xor_b32_e32 v161, 0x80000000, v159
	v_cndmask_b32_e32 v155, v155, v153, vcc
	v_cndmask_b32_e32 v154, v154, v93, vcc
	v_mov_b32_e32 v165, v166
	v_cndmask_b32_e32 v159, v159, v161, vcc
	v_cndmask_b32_e32 v158, v158, v160, vcc
	v_pk_fma_f32 v[88:89], v[88:89], v[164:165], v[154:155]
	v_mov_b32_e32 v169, v170
	v_mov_b32_e32 v154, v156
	v_mov_b32_e32 v155, v156
	v_pk_fma_f32 v[90:91], v[90:91], v[168:169], v[158:159]
	v_pk_mul_f32 v[158:159], v[78:79], v[154:155]
	v_pk_mul_f32 v[160:161], v[76:77], v[156:157]
	s_waitcnt lgkmcnt(0)
	global_load_dwordx4 v[76:79], v92, s[8:9] offset:192
	v_pk_mul_f32 v[70:71], v[70:71], v[154:155]
	v_mov_b32_e32 v153, v3
	v_mov_b32_e32 v93, v3
	v_pk_mul_f32 v[70:71], v[82:83], v[70:71]
	v_lshl_add_u64 v[82:83], v[94:95], 0, v[152:153]
	v_lshl_add_u64 v[82:83], v[82:83], 0, v[92:93]
	s_mov_b64 s[8:9], 0x2a900000
	v_lshl_add_u64 v[84:85], v[82:83], 0, s[8:9]
	s_mov_b32 s8, 0x2a900000
	v_add_co_u32_e32 v82, vcc, s8, v82
	v_pk_mul_f32 v[74:75], v[74:75], v[154:155]
	s_nop 0
	v_addc_co_u32_e32 v83, vcc, 0, v83, vcc
	v_pk_mul_f32 v[74:75], v[86:87], v[74:75]
	s_mov_b64 s[8:9], 0x2b500000
	v_bfe_u32 v86, v91, 16, 1
	v_add3_u32 v86, v91, v86, s96
	s_waitcnt vmcnt(0)
	v_pk_mul_f32 v[78:79], v[158:159], v[78:79]
	v_pk_mul_f32 v[76:77], v[160:161], v[76:77]
	global_store_dwordx4 v[82:83], v[88:91], off
	global_store_dwordx4 v[84:85], v[68:71], off offset:64
	global_store_dwordx4 v[84:85], v[72:75], off offset:128
	global_store_dwordx4 v[84:85], v[76:79], off offset:192
	v_bfe_u32 v84, v88, 16, 1
	v_add3_u32 v84, v88, v84, s96
	v_bfe_u32 v85, v89, 16, 1
	v_lshlrev_b32_e32 v82, 1, v162
	v_mov_b32_e32 v83, v3
	v_lshrrev_b32_e32 v84, 16, v84
	v_add3_u32 v85, v89, v85, s96
	v_lshl_add_u64 v[82:83], v[80:81], 0, v[82:83]
	v_and_or_b32 v84, v85, s97, v84
	v_bfe_u32 v85, v90, 16, 1
	v_lshl_add_u64 v[80:81], v[82:83], 0, s[8:9]
	v_add3_u32 v85, v90, v85, s96
	s_mov_b32 s8, 0x2b500000
	v_lshrrev_b32_e32 v85, 16, v85
	v_add_co_u32_e32 v82, vcc, s8, v82
	v_and_or_b32 v85, v86, s97, v85
	s_nop 0
	v_addc_co_u32_e32 v83, vcc, 0, v83, vcc
	global_store_dwordx2 v[82:83], v[84:85], off
	v_bfe_u32 v82, v68, 16, 1
	v_add3_u32 v68, v68, v82, s96
	v_bfe_u32 v82, v69, 16, 1
	v_lshrrev_b32_e32 v68, 16, v68
	v_add3_u32 v69, v69, v82, s96
	v_and_or_b32 v68, v69, s97, v68
	v_bfe_u32 v69, v70, 16, 1
	v_add3_u32 v69, v70, v69, s96
	v_bfe_u32 v70, v71, 16, 1
	v_lshrrev_b32_e32 v69, 16, v69
	v_add3_u32 v70, v71, v70, s96
	v_and_or_b32 v69, v70, s97, v69
	global_store_dwordx2 v[80:81], v[68:69], off offset:32
	v_bfe_u32 v68, v72, 16, 1
	v_add3_u32 v68, v72, v68, s96
	v_bfe_u32 v69, v73, 16, 1
	v_lshrrev_b32_e32 v68, 16, v68
	v_add3_u32 v69, v73, v69, s96
	v_and_or_b32 v68, v69, s97, v68
	v_bfe_u32 v69, v74, 16, 1
	v_add3_u32 v69, v74, v69, s96
	v_bfe_u32 v70, v75, 16, 1
	v_lshrrev_b32_e32 v69, 16, v69
	v_add3_u32 v70, v75, v70, s96
	v_and_or_b32 v69, v70, s97, v69
	global_store_dwordx2 v[80:81], v[68:69], off offset:64
	v_bfe_u32 v68, v76, 16, 1
	v_add3_u32 v68, v76, v68, s96
	v_bfe_u32 v69, v77, 16, 1
	v_lshrrev_b32_e32 v68, 16, v68
	v_add3_u32 v69, v77, v69, s96
	v_and_or_b32 v68, v69, s97, v68
	v_bfe_u32 v69, v78, 16, 1
	v_add3_u32 v69, v78, v69, s96
	v_bfe_u32 v70, v79, 16, 1
	v_lshrrev_b32_e32 v69, 16, v69
	v_add3_u32 v70, v79, v70, s96
	v_and_or_b32 v69, v70, s97, v69
	global_store_dwordx2 v[80:81], v[68:69], off offset:96
